# rec scan: cross-row exchange of (P,H) with v_permlane32/16_swap all-gather instead of 8 ds_bpermute round trips per step
# speedup vs baseline: 1.0065x; 1.0054x over previous
.Lrec2_loopA_d0:
	ds_read_b128 v[198:201], v130 offset:0
	ds_read_b128 v[214:217], v130 offset:576
	ds_read_b128 v[202:205], v131 offset:0
	ds_read_b128 v[218:221], v131 offset:576
	ds_read_b128 v[206:209], v130 offset:144
	ds_read_b128 v[222:225], v130 offset:720
	ds_read_b128 v[210:213], v131 offset:144
	s_waitcnt lgkmcnt(14)
	ds_read_b128 v[226:229], v131 offset:720
	s_waitcnt lgkmcnt(6)
	v_mfma_f32_16x16x32_bf16 v[100:103], v[198:201], v[20:23], v[12:15]
	v_mfma_f32_16x16x32_bf16 v[104:107], v[198:201], v[52:55], v[16:19]
	v_mfma_f32_16x16x32_bf16 v[108:111], v[198:201], v[84:87], v[242:245]
	v_mfma_f32_16x16x32_bf16 v[112:115], v[214:217], v[20:23], v[12:15]
	v_mfma_f32_16x16x32_bf16 v[138:141], v[214:217], v[52:55], v[16:19]
	v_mfma_f32_16x16x32_bf16 v[142:145], v[214:217], v[84:87], v[242:245]
	s_waitcnt lgkmcnt(4)
	v_mfma_f32_16x16x32_bf16 v[100:103], v[202:205], v[24:27], v[100:103]
	v_mfma_f32_16x16x32_bf16 v[104:107], v[202:205], v[56:59], v[104:107]
	v_mfma_f32_16x16x32_bf16 v[112:115], v[218:221], v[24:27], v[112:115]
	v_mfma_f32_16x16x32_bf16 v[138:141], v[218:221], v[56:59], v[138:141]
	ds_read_b128 v[198:201], v130 offset:288
	ds_read_b128 v[214:217], v130 offset:864
	ds_read_b128 v[202:205], v131 offset:288
	ds_read_b128 v[218:221], v131 offset:864
	s_waitcnt lgkmcnt(6)
	v_mfma_f32_16x16x32_bf16 v[100:103], v[206:209], v[28:31], v[100:103]
	v_mfma_f32_16x16x32_bf16 v[104:107], v[206:209], v[60:63], v[104:107]
	v_mfma_f32_16x16x32_bf16 v[108:111], v[206:209], v[88:91], v[108:111]
	v_mfma_f32_16x16x32_bf16 v[112:115], v[222:225], v[28:31], v[112:115]
	v_mfma_f32_16x16x32_bf16 v[138:141], v[222:225], v[60:63], v[138:141]
	v_mfma_f32_16x16x32_bf16 v[142:145], v[222:225], v[88:91], v[142:145]
	s_waitcnt lgkmcnt(4)
	v_mfma_f32_16x16x32_bf16 v[100:103], v[210:213], v[32:35], v[100:103]
	v_mfma_f32_16x16x32_bf16 v[104:107], v[210:213], v[64:67], v[104:107]
	v_mfma_f32_16x16x32_bf16 v[112:115], v[226:229], v[32:35], v[112:115]
	v_mfma_f32_16x16x32_bf16 v[138:141], v[226:229], v[64:67], v[138:141]
	ds_read_b128 v[206:209], v130 offset:432
	ds_read_b128 v[222:225], v130 offset:1008
	ds_read_b128 v[210:213], v131 offset:432
	ds_read_b128 v[226:229], v131 offset:1008
	s_waitcnt lgkmcnt(6)
	v_mfma_f32_16x16x32_bf16 v[100:103], v[198:201], v[36:39], v[100:103]
	v_mfma_f32_16x16x32_bf16 v[104:107], v[198:201], v[68:71], v[104:107]
	v_mfma_f32_16x16x32_bf16 v[108:111], v[198:201], v[92:95], v[108:111]
	v_mfma_f32_16x16x32_bf16 v[112:115], v[214:217], v[36:39], v[112:115]
	v_mfma_f32_16x16x32_bf16 v[138:141], v[214:217], v[68:71], v[138:141]
	v_mfma_f32_16x16x32_bf16 v[142:145], v[214:217], v[92:95], v[142:145]
	s_waitcnt lgkmcnt(4)
	v_mfma_f32_16x16x32_bf16 v[100:103], v[202:205], v[40:43], v[100:103]
	v_mfma_f32_16x16x32_bf16 v[104:107], v[202:205], v[72:75], v[104:107]
	v_mfma_f32_16x16x32_bf16 v[112:115], v[218:221], v[40:43], v[112:115]
	v_mfma_f32_16x16x32_bf16 v[138:141], v[218:221], v[72:75], v[138:141]
	s_waitcnt lgkmcnt(2)
	v_mfma_f32_16x16x32_bf16 v[100:103], v[206:209], v[44:47], v[100:103]
	v_mfma_f32_16x16x32_bf16 v[104:107], v[206:209], v[76:79], v[104:107]
	v_mfma_f32_16x16x32_bf16 v[108:111], v[206:209], v[96:99], v[108:111]
	v_mfma_f32_16x16x32_bf16 v[112:115], v[222:225], v[44:47], v[112:115]
	v_mfma_f32_16x16x32_bf16 v[138:141], v[222:225], v[76:79], v[138:141]
	v_mfma_f32_16x16x32_bf16 v[142:145], v[222:225], v[96:99], v[142:145]
	s_waitcnt lgkmcnt(0)
	v_mfma_f32_16x16x32_bf16 v[100:103], v[210:213], v[48:51], v[100:103]
	v_mfma_f32_16x16x32_bf16 v[104:107], v[210:213], v[80:83], v[104:107]
	v_mfma_f32_16x16x32_bf16 v[112:115], v[226:229], v[48:51], v[112:115]
	v_mfma_f32_16x16x32_bf16 v[138:141], v[226:229], v[80:83], v[138:141]
	s_waitcnt lgkmcnt(0)
	s_barrier
	s_waitcnt vmcnt(3)
	ds_write_b128 v134, v[146:149]
	ds_write_b128 v134, v[150:153] offset:4608
	ds_write_b128 v135, v[160:163]
	s_add_i32 s52, s4, 3
	s_min_u32 s52, s52, 31
	s_lshl_b32 s52, s52, 13
	s_add_u32 s26, s50, s52
	s_addc_u32 s27, s51, 0
	global_load_dwordx4 v[146:149], v154, s[26:27]
	global_load_dwordx4 v[150:153], v155, s[26:27]
	global_load_dwordx4 v[160:163], v159, s[26:27]
	v_exp_f32_e32 v198, v100
	v_exp_f32_e32 v199, v101
	v_exp_f32_e32 v200, v102
	v_exp_f32_e32 v201, v103
	v_exp_f32_e32 v202, v112
	v_exp_f32_e32 v203, v113
	v_exp_f32_e32 v204, v114
	v_exp_f32_e32 v205, v115
	v_exp_f32_e32 v214, v104
	v_add_f32_e32 v198, 1.0, v198
	v_exp_f32_e32 v215, v105
	v_add_f32_e32 v199, 1.0, v199
	v_exp_f32_e32 v216, v106
	v_add_f32_e32 v200, 1.0, v200
	v_exp_f32_e32 v217, v107
	v_add_f32_e32 v201, 1.0, v201
	v_exp_f32_e32 v218, v138
	v_add_f32_e32 v202, 1.0, v202
	v_exp_f32_e32 v219, v139
	v_add_f32_e32 v203, 1.0, v203
	v_exp_f32_e32 v220, v140
	v_add_f32_e32 v204, 1.0, v204
	v_exp_f32_e32 v221, v141
	v_add_f32_e32 v205, 1.0, v205
	v_rcp_f32_e32 v198, v198
	v_add_f32_e32 v214, 1.0, v214
	v_rcp_f32_e32 v199, v199
	v_add_f32_e32 v215, 1.0, v215
	v_rcp_f32_e32 v200, v200
	v_add_f32_e32 v216, 1.0, v216
	v_rcp_f32_e32 v201, v201
	v_add_f32_e32 v217, 1.0, v217
	v_rcp_f32_e32 v202, v202
	v_add_f32_e32 v218, 1.0, v218
	v_rcp_f32_e32 v203, v203
	v_add_f32_e32 v219, 1.0, v219
	v_rcp_f32_e32 v204, v204
	v_add_f32_e32 v220, 1.0, v220
	v_rcp_f32_e32 v205, v205
	v_add_f32_e32 v221, 1.0, v221
	v_mul_f32_e32 v198, v179, v198
	v_mul_f32_e32 v199, v179, v199
	v_mul_f32_e32 v200, v179, v200
	v_mul_f32_e32 v201, v179, v201
	v_mul_f32_e32 v202, v179, v202
	v_mul_f32_e32 v203, v179, v203
	v_mul_f32_e32 v204, v179, v204
	v_mul_f32_e32 v205, v179, v205
	v_exp_f32_e32 v120, v198
	v_exp_f32_e32 v121, v199
	v_exp_f32_e32 v122, v200
	v_exp_f32_e32 v123, v201
	v_exp_f32_e32 v124, v202
	v_exp_f32_e32 v125, v203
	v_exp_f32_e32 v126, v204
	v_exp_f32_e32 v127, v205
	v_fma_f32 v206, -v120, v120, 1.0
	v_fma_f32 v207, -v121, v121, 1.0
	v_fma_f32 v208, -v122, v122, 1.0
	v_fma_f32 v209, -v123, v123, 1.0
	v_fma_f32 v210, -v124, v124, 1.0
	v_fma_f32 v211, -v125, v125, 1.0
	v_fma_f32 v212, -v126, v126, 1.0
	v_fma_f32 v213, -v127, v127, 1.0
	v_max_f32_e32 v206, 0xda24260, v206
	v_max_f32_e32 v207, 0xda24260, v207
	v_max_f32_e32 v208, 0xda24260, v208
	v_max_f32_e32 v209, 0xda24260, v209
	v_max_f32_e32 v210, 0xda24260, v210
	v_max_f32_e32 v211, 0xda24260, v211
	v_max_f32_e32 v212, 0xda24260, v212
	v_max_f32_e32 v213, 0xda24260, v213
	v_mul_f32_e32 v198, v214, v206
	v_mul_f32_e32 v199, v215, v207
	v_mul_f32_e32 v200, v216, v208
	v_mul_f32_e32 v201, v217, v209
	v_mul_f32_e32 v202, v218, v210
	v_mul_f32_e32 v203, v219, v211
	v_mul_f32_e32 v204, v220, v212
	v_mul_f32_e32 v205, v221, v213
	v_mul_f32_e32 v214, v214, v198
	v_mul_f32_e32 v215, v215, v199
	v_mul_f32_e32 v216, v216, v200
	v_mul_f32_e32 v217, v217, v201
	v_mul_f32_e32 v218, v218, v202
	v_mul_f32_e32 v219, v219, v203
	v_mul_f32_e32 v220, v220, v204
	v_mul_f32_e32 v221, v221, v205
	v_rsq_f32_e32 v214, v214
	v_mul_f32_e32 v222, v108, v206
	v_rsq_f32_e32 v215, v215
	v_mul_f32_e32 v223, v109, v207
	v_rsq_f32_e32 v216, v216
	v_mul_f32_e32 v224, v110, v208
	v_rsq_f32_e32 v217, v217
	v_mul_f32_e32 v225, v111, v209
	v_rsq_f32_e32 v218, v218
	v_mul_f32_e32 v226, v142, v210
	v_rsq_f32_e32 v219, v219
	v_mul_f32_e32 v227, v143, v211
	v_rsq_f32_e32 v220, v220
	v_mul_f32_e32 v228, v144, v212
	v_rsq_f32_e32 v221, v221
	v_mul_f32_e32 v229, v145, v213
	v_mul_f32_e32 v170, v222, v214
	v_mul_f32_e32 v171, v223, v215
	v_mul_f32_e32 v172, v224, v216
	v_mul_f32_e32 v173, v225, v217
	v_mul_f32_e32 v174, v226, v218
	v_mul_f32_e32 v175, v227, v219
	v_mul_f32_e32 v176, v228, v220
	v_mul_f32_e32 v177, v229, v221
	v_mov_b32_e32 v198, v170
	v_mov_b32_e32 v199, v120
	v_fma_f32 v198, v121, v198, v171
	v_mul_f32_e32 v199, v199, v121
	v_fma_f32 v198, v122, v198, v172
	v_mul_f32_e32 v199, v199, v122
	v_fma_f32 v198, v123, v198, v173
	v_mul_f32_e32 v199, v199, v123
	v_fma_f32 v198, v124, v198, v174
	v_mul_f32_e32 v199, v199, v124
	v_fma_f32 v198, v125, v198, v175
	v_mul_f32_e32 v199, v199, v125
	v_fma_f32 v198, v126, v198, v176
	v_mul_f32_e32 v199, v199, v126
	v_fma_f32 v198, v127, v198, v177
	v_mul_f32_e32 v199, v199, v127
	v_mov_b32_e32 v164, v199
	v_mov_b32_e32 v166, v199
	v_mov_b32_e32 v246, v198
	v_mov_b32_e32 v248, v198
	s_nop 1
	v_permlane32_swap_b32 v164, v166
	v_permlane32_swap_b32 v246, v248
	s_nop 1
	v_mov_b32_e32 v165, v164
	v_mov_b32_e32 v167, v166
	v_mov_b32_e32 v247, v246
	v_mov_b32_e32 v249, v248
	s_nop 1
	v_permlane16_swap_b32 v164, v165
	v_permlane16_swap_b32 v166, v167
	v_permlane16_swap_b32 v246, v247
	v_permlane16_swap_b32 v248, v249
	s_nop 1
	v_mov_b32_e32 v251, v246
	v_mov_b32_e32 v250, v164
	v_fma_f32 v251, v251, v165, v247
	v_mul_f32_e32 v250, v250, v165
	v_fma_f32 v251, v251, v166, v248
	v_mul_f32_e32 v250, v250, v166
	v_fma_f32 v251, v251, v167, v249
	v_mul_f32_e32 v250, v250, v167
	s_mov_b64 exec, s[10:11]
	ds_write_b64 v182, v[250:251] offset:0
	s_mov_b64 exec, -1
	s_waitcnt lgkmcnt(0)
	s_barrier
	ds_read2_b64 v[4:7], v183 offset0:0 offset1:16
	s_add_i32 s52, s4, 0
	s_lshl_b32 s52, s52, 12
	v_add_u32_e32 v197, s52, v184
	s_waitcnt lgkmcnt(0)
	v_fma_f32 v198, v180, v4, v5
	v_cndmask_b32_e64 v199, v180, v198, s[24:25]
	v_fma_f32 v180, v198, v6, v7
	v_fma_f32 v200, v199, v164, v246
	v_cndmask_b32_e64 v199, v199, v200, s[16:17]
	v_fma_f32 v200, v199, v165, v247
	v_cndmask_b32_e64 v199, v199, v200, s[20:21]
	v_fma_f32 v200, v199, v166, v248
	v_cndmask_b32_e64 v199, v199, v200, s[22:23]
	v_fma_f32 v214, v120, v199, v170
	v_fma_f32 v215, v121, v214, v171
	v_fma_f32 v216, v122, v215, v172
	v_fma_f32 v217, v123, v216, v173
	v_fma_f32 v218, v124, v217, v174
	v_fma_f32 v219, v125, v218, v175
	v_fma_f32 v220, v126, v219, v176
	v_fma_f32 v221, v127, v220, v177
	v_cvt_pk_bf16_f32 v206, v214, v215
	v_cvt_pk_bf16_f32 v208, v216, v217
	v_cvt_pk_bf16_f32 v210, v218, v219
	v_cvt_pk_bf16_f32 v212, v220, v221
	ds_write_b16 v197, v206 offset:0
	ds_write_b16_d16_hi v197, v206 offset:64
	ds_write_b16 v197, v208 offset:128
	ds_write_b16_d16_hi v197, v208 offset:192
	ds_write_b16 v197, v210 offset:256
	ds_write_b16_d16_hi v197, v210 offset:320
	ds_write_b16 v197, v212 offset:384
	ds_write_b16_d16_hi v197, v212 offset:448
	ds_read_b128 v[198:201], v130 offset:0
	ds_read_b128 v[214:217], v130 offset:576
	ds_read_b128 v[202:205], v131 offset:0
	ds_read_b128 v[218:221], v131 offset:576
	ds_read_b128 v[206:209], v130 offset:144
	ds_read_b128 v[222:225], v130 offset:720
	ds_read_b128 v[210:213], v131 offset:144
	s_waitcnt lgkmcnt(14)
	ds_read_b128 v[226:229], v131 offset:720
	s_waitcnt lgkmcnt(6)
	v_mfma_f32_16x16x32_bf16 v[100:103], v[198:201], v[20:23], v[12:15]
	v_mfma_f32_16x16x32_bf16 v[104:107], v[198:201], v[52:55], v[16:19]
	v_mfma_f32_16x16x32_bf16 v[108:111], v[198:201], v[84:87], v[242:245]
	v_mfma_f32_16x16x32_bf16 v[112:115], v[214:217], v[20:23], v[12:15]
	v_mfma_f32_16x16x32_bf16 v[138:141], v[214:217], v[52:55], v[16:19]
	v_mfma_f32_16x16x32_bf16 v[142:145], v[214:217], v[84:87], v[242:245]
	s_waitcnt lgkmcnt(4)
	v_mfma_f32_16x16x32_bf16 v[100:103], v[202:205], v[24:27], v[100:103]
	v_mfma_f32_16x16x32_bf16 v[104:107], v[202:205], v[56:59], v[104:107]
	v_mfma_f32_16x16x32_bf16 v[112:115], v[218:221], v[24:27], v[112:115]
	v_mfma_f32_16x16x32_bf16 v[138:141], v[218:221], v[56:59], v[138:141]
	ds_read_b128 v[198:201], v130 offset:288
	ds_read_b128 v[214:217], v130 offset:864
	ds_read_b128 v[202:205], v131 offset:288
	ds_read_b128 v[218:221], v131 offset:864
	s_waitcnt lgkmcnt(6)
	v_mfma_f32_16x16x32_bf16 v[100:103], v[206:209], v[28:31], v[100:103]
	v_mfma_f32_16x16x32_bf16 v[104:107], v[206:209], v[60:63], v[104:107]
	v_mfma_f32_16x16x32_bf16 v[108:111], v[206:209], v[88:91], v[108:111]
	v_mfma_f32_16x16x32_bf16 v[112:115], v[222:225], v[28:31], v[112:115]
	v_mfma_f32_16x16x32_bf16 v[138:141], v[222:225], v[60:63], v[138:141]
	v_mfma_f32_16x16x32_bf16 v[142:145], v[222:225], v[88:91], v[142:145]
	s_waitcnt lgkmcnt(4)
	v_mfma_f32_16x16x32_bf16 v[100:103], v[210:213], v[32:35], v[100:103]
	v_mfma_f32_16x16x32_bf16 v[104:107], v[210:213], v[64:67], v[104:107]
	v_mfma_f32_16x16x32_bf16 v[112:115], v[226:229], v[32:35], v[112:115]
	v_mfma_f32_16x16x32_bf16 v[138:141], v[226:229], v[64:67], v[138:141]
	ds_read_b128 v[206:209], v130 offset:432
	ds_read_b128 v[222:225], v130 offset:1008
	ds_read_b128 v[210:213], v131 offset:432
	ds_read_b128 v[226:229], v131 offset:1008
	s_waitcnt lgkmcnt(6)
	v_mfma_f32_16x16x32_bf16 v[100:103], v[198:201], v[36:39], v[100:103]
	v_mfma_f32_16x16x32_bf16 v[104:107], v[198:201], v[68:71], v[104:107]
	v_mfma_f32_16x16x32_bf16 v[108:111], v[198:201], v[92:95], v[108:111]
	v_mfma_f32_16x16x32_bf16 v[112:115], v[214:217], v[36:39], v[112:115]
	v_mfma_f32_16x16x32_bf16 v[138:141], v[214:217], v[68:71], v[138:141]
	v_mfma_f32_16x16x32_bf16 v[142:145], v[214:217], v[92:95], v[142:145]
	s_waitcnt lgkmcnt(4)
	v_mfma_f32_16x16x32_bf16 v[100:103], v[202:205], v[40:43], v[100:103]
	v_mfma_f32_16x16x32_bf16 v[104:107], v[202:205], v[72:75], v[104:107]
	v_mfma_f32_16x16x32_bf16 v[112:115], v[218:221], v[40:43], v[112:115]
	v_mfma_f32_16x16x32_bf16 v[138:141], v[218:221], v[72:75], v[138:141]
	s_waitcnt lgkmcnt(2)
	v_mfma_f32_16x16x32_bf16 v[100:103], v[206:209], v[44:47], v[100:103]
	v_mfma_f32_16x16x32_bf16 v[104:107], v[206:209], v[76:79], v[104:107]
	v_mfma_f32_16x16x32_bf16 v[108:111], v[206:209], v[96:99], v[108:111]
	v_mfma_f32_16x16x32_bf16 v[112:115], v[222:225], v[44:47], v[112:115]
	v_mfma_f32_16x16x32_bf16 v[138:141], v[222:225], v[76:79], v[138:141]
	v_mfma_f32_16x16x32_bf16 v[142:145], v[222:225], v[96:99], v[142:145]
	s_waitcnt lgkmcnt(0)
	v_mfma_f32_16x16x32_bf16 v[100:103], v[210:213], v[48:51], v[100:103]
	v_mfma_f32_16x16x32_bf16 v[104:107], v[210:213], v[80:83], v[104:107]
	v_mfma_f32_16x16x32_bf16 v[112:115], v[226:229], v[48:51], v[112:115]
	v_mfma_f32_16x16x32_bf16 v[138:141], v[226:229], v[80:83], v[138:141]
	s_waitcnt lgkmcnt(0)
	s_barrier
	s_waitcnt vmcnt(3)
	ds_write_b128 v134, v[230:233]
	ds_write_b128 v134, v[234:237] offset:4608
	ds_write_b128 v135, v[238:241]
	s_add_i32 s52, s4, 4
	s_min_u32 s52, s52, 31
	s_lshl_b32 s52, s52, 13
	s_add_u32 s26, s50, s52
	s_addc_u32 s27, s51, 0
	global_load_dwordx4 v[230:233], v154, s[26:27]
	global_load_dwordx4 v[234:237], v155, s[26:27]
	global_load_dwordx4 v[238:241], v159, s[26:27]
	v_exp_f32_e32 v198, v100
	v_exp_f32_e32 v199, v101
	v_exp_f32_e32 v200, v102
	v_exp_f32_e32 v201, v103
	v_exp_f32_e32 v202, v112
	v_exp_f32_e32 v203, v113
	v_exp_f32_e32 v204, v114
	v_exp_f32_e32 v205, v115
	v_exp_f32_e32 v214, v104
	v_add_f32_e32 v198, 1.0, v198
	v_exp_f32_e32 v215, v105
	v_add_f32_e32 v199, 1.0, v199
	v_exp_f32_e32 v216, v106
	v_add_f32_e32 v200, 1.0, v200
	v_exp_f32_e32 v217, v107
	v_add_f32_e32 v201, 1.0, v201
	v_exp_f32_e32 v218, v138
	v_add_f32_e32 v202, 1.0, v202
	v_exp_f32_e32 v219, v139
	v_add_f32_e32 v203, 1.0, v203
	v_exp_f32_e32 v220, v140
	v_add_f32_e32 v204, 1.0, v204
	v_exp_f32_e32 v221, v141
	v_add_f32_e32 v205, 1.0, v205
	v_rcp_f32_e32 v198, v198
	v_add_f32_e32 v214, 1.0, v214
	v_rcp_f32_e32 v199, v199
	v_add_f32_e32 v215, 1.0, v215
	v_rcp_f32_e32 v200, v200
	v_add_f32_e32 v216, 1.0, v216
	v_rcp_f32_e32 v201, v201
	v_add_f32_e32 v217, 1.0, v217
	v_rcp_f32_e32 v202, v202
	v_add_f32_e32 v218, 1.0, v218
	v_rcp_f32_e32 v203, v203
	v_add_f32_e32 v219, 1.0, v219
	v_rcp_f32_e32 v204, v204
	v_add_f32_e32 v220, 1.0, v220
	v_rcp_f32_e32 v205, v205
	v_add_f32_e32 v221, 1.0, v221
	v_mul_f32_e32 v198, v179, v198
	v_mul_f32_e32 v199, v179, v199
	v_mul_f32_e32 v200, v179, v200
	v_mul_f32_e32 v201, v179, v201
	v_mul_f32_e32 v202, v179, v202
	v_mul_f32_e32 v203, v179, v203
	v_mul_f32_e32 v204, v179, v204
	v_mul_f32_e32 v205, v179, v205
	v_exp_f32_e32 v120, v198
	v_exp_f32_e32 v121, v199
	v_exp_f32_e32 v122, v200
	v_exp_f32_e32 v123, v201
	v_exp_f32_e32 v124, v202
	v_exp_f32_e32 v125, v203
	v_exp_f32_e32 v126, v204
	v_exp_f32_e32 v127, v205
	v_fma_f32 v206, -v120, v120, 1.0
	v_fma_f32 v207, -v121, v121, 1.0
	v_fma_f32 v208, -v122, v122, 1.0
	v_fma_f32 v209, -v123, v123, 1.0
	v_fma_f32 v210, -v124, v124, 1.0
	v_fma_f32 v211, -v125, v125, 1.0
	v_fma_f32 v212, -v126, v126, 1.0
	v_fma_f32 v213, -v127, v127, 1.0
	v_max_f32_e32 v206, 0xda24260, v206
	v_max_f32_e32 v207, 0xda24260, v207
	v_max_f32_e32 v208, 0xda24260, v208
	v_max_f32_e32 v209, 0xda24260, v209
	v_max_f32_e32 v210, 0xda24260, v210
	v_max_f32_e32 v211, 0xda24260, v211
	v_max_f32_e32 v212, 0xda24260, v212
	v_max_f32_e32 v213, 0xda24260, v213
	v_mul_f32_e32 v198, v214, v206
	v_mul_f32_e32 v199, v215, v207
	v_mul_f32_e32 v200, v216, v208
	v_mul_f32_e32 v201, v217, v209
	v_mul_f32_e32 v202, v218, v210
	v_mul_f32_e32 v203, v219, v211
	v_mul_f32_e32 v204, v220, v212
	v_mul_f32_e32 v205, v221, v213
	v_mul_f32_e32 v214, v214, v198
	v_mul_f32_e32 v215, v215, v199
	v_mul_f32_e32 v216, v216, v200
	v_mul_f32_e32 v217, v217, v201
	v_mul_f32_e32 v218, v218, v202
	v_mul_f32_e32 v219, v219, v203
	v_mul_f32_e32 v220, v220, v204
	v_mul_f32_e32 v221, v221, v205
	v_rsq_f32_e32 v214, v214
	v_mul_f32_e32 v222, v108, v206
	v_rsq_f32_e32 v215, v215
	v_mul_f32_e32 v223, v109, v207
	v_rsq_f32_e32 v216, v216
	v_mul_f32_e32 v224, v110, v208
	v_rsq_f32_e32 v217, v217
	v_mul_f32_e32 v225, v111, v209
	v_rsq_f32_e32 v218, v218
	v_mul_f32_e32 v226, v142, v210
	v_rsq_f32_e32 v219, v219
	v_mul_f32_e32 v227, v143, v211
	v_rsq_f32_e32 v220, v220
	v_mul_f32_e32 v228, v144, v212
	v_rsq_f32_e32 v221, v221
	v_mul_f32_e32 v229, v145, v213
	v_mul_f32_e32 v170, v222, v214
	v_mul_f32_e32 v171, v223, v215
	v_mul_f32_e32 v172, v224, v216
	v_mul_f32_e32 v173, v225, v217
	v_mul_f32_e32 v174, v226, v218
	v_mul_f32_e32 v175, v227, v219
	v_mul_f32_e32 v176, v228, v220
	v_mul_f32_e32 v177, v229, v221
	v_mov_b32_e32 v198, v170
	v_mov_b32_e32 v199, v120
	v_fma_f32 v198, v121, v198, v171
	v_mul_f32_e32 v199, v199, v121
	v_fma_f32 v198, v122, v198, v172
	v_mul_f32_e32 v199, v199, v122
	v_fma_f32 v198, v123, v198, v173
	v_mul_f32_e32 v199, v199, v123
	v_fma_f32 v198, v124, v198, v174
	v_mul_f32_e32 v199, v199, v124
	v_fma_f32 v198, v125, v198, v175
	v_mul_f32_e32 v199, v199, v125
	v_fma_f32 v198, v126, v198, v176
	v_mul_f32_e32 v199, v199, v126
	v_fma_f32 v198, v127, v198, v177
	v_mul_f32_e32 v199, v199, v127
	v_mov_b32_e32 v164, v199
	v_mov_b32_e32 v166, v199
	v_mov_b32_e32 v246, v198
	v_mov_b32_e32 v248, v198
	s_nop 1
	v_permlane32_swap_b32 v164, v166
	v_permlane32_swap_b32 v246, v248
	s_nop 1
	v_mov_b32_e32 v165, v164
	v_mov_b32_e32 v167, v166
	v_mov_b32_e32 v247, v246
	v_mov_b32_e32 v249, v248
	s_nop 1
	v_permlane16_swap_b32 v164, v165
	v_permlane16_swap_b32 v166, v167
	v_permlane16_swap_b32 v246, v247
	v_permlane16_swap_b32 v248, v249
	s_nop 1
	v_mov_b32_e32 v251, v246
	v_mov_b32_e32 v250, v164
	v_fma_f32 v251, v251, v165, v247
	v_mul_f32_e32 v250, v250, v165
	v_fma_f32 v251, v251, v166, v248
	v_mul_f32_e32 v250, v250, v166
	v_fma_f32 v251, v251, v167, v249
	v_mul_f32_e32 v250, v250, v167
	s_mov_b64 exec, s[10:11]
	ds_write_b64 v182, v[250:251] offset:1024
	s_mov_b64 exec, -1
	s_waitcnt lgkmcnt(0)
	s_barrier
	ds_read2_b64 v[4:7], v183 offset0:128 offset1:144
	s_add_i32 s52, s4, 1
	s_lshl_b32 s52, s52, 12
	v_add_u32_e32 v197, s52, v184
	s_waitcnt lgkmcnt(0)
	v_fma_f32 v198, v180, v4, v5
	v_cndmask_b32_e64 v199, v180, v198, s[24:25]
	v_fma_f32 v180, v198, v6, v7
	v_fma_f32 v200, v199, v164, v246
	v_cndmask_b32_e64 v199, v199, v200, s[16:17]
	v_fma_f32 v200, v199, v165, v247
	v_cndmask_b32_e64 v199, v199, v200, s[20:21]
	v_fma_f32 v200, v199, v166, v248
	v_cndmask_b32_e64 v199, v199, v200, s[22:23]
	v_fma_f32 v214, v120, v199, v170
	v_fma_f32 v215, v121, v214, v171
	v_fma_f32 v216, v122, v215, v172
	v_fma_f32 v217, v123, v216, v173
	v_fma_f32 v218, v124, v217, v174
	v_fma_f32 v219, v125, v218, v175
	v_fma_f32 v220, v126, v219, v176
	v_fma_f32 v221, v127, v220, v177
	v_cvt_pk_bf16_f32 v206, v214, v215
	v_cvt_pk_bf16_f32 v208, v216, v217
	v_cvt_pk_bf16_f32 v210, v218, v219
	v_cvt_pk_bf16_f32 v212, v220, v221
	ds_write_b16 v197, v206 offset:0
	ds_write_b16_d16_hi v197, v206 offset:64
	ds_write_b16 v197, v208 offset:128
	ds_write_b16_d16_hi v197, v208 offset:192
	ds_write_b16 v197, v210 offset:256
	ds_write_b16_d16_hi v197, v210 offset:320
	ds_write_b16 v197, v212 offset:384
	ds_write_b16_d16_hi v197, v212 offset:448
	s_add_i32 s4, s4, 2
	s_cmp_lt_u32 s4, 16
	s_cbranch_scc1 .Lrec2_loopA_d0
	ds_read_b128 v[198:201], v130 offset:0
	ds_read_b128 v[214:217], v130 offset:576
	ds_read_b128 v[202:205], v131 offset:0
	ds_read_b128 v[218:221], v131 offset:576
	ds_read_b128 v[206:209], v130 offset:144
	ds_read_b128 v[222:225], v130 offset:720
	ds_read_b128 v[210:213], v131 offset:144
	s_waitcnt lgkmcnt(14)
	ds_read_b128 v[226:229], v131 offset:720
	s_waitcnt lgkmcnt(6)
	v_mfma_f32_16x16x32_bf16 v[100:103], v[198:201], v[20:23], v[12:15]
	v_mfma_f32_16x16x32_bf16 v[104:107], v[198:201], v[52:55], v[16:19]
	v_mfma_f32_16x16x32_bf16 v[108:111], v[198:201], v[84:87], v[242:245]
	v_mfma_f32_16x16x32_bf16 v[112:115], v[214:217], v[20:23], v[12:15]
	v_mfma_f32_16x16x32_bf16 v[138:141], v[214:217], v[52:55], v[16:19]
	v_mfma_f32_16x16x32_bf16 v[142:145], v[214:217], v[84:87], v[242:245]
	s_waitcnt lgkmcnt(4)
	v_mfma_f32_16x16x32_bf16 v[100:103], v[202:205], v[24:27], v[100:103]
	v_mfma_f32_16x16x32_bf16 v[104:107], v[202:205], v[56:59], v[104:107]
	v_mfma_f32_16x16x32_bf16 v[112:115], v[218:221], v[24:27], v[112:115]
	v_mfma_f32_16x16x32_bf16 v[138:141], v[218:221], v[56:59], v[138:141]
	ds_read_b128 v[198:201], v130 offset:288
	ds_read_b128 v[214:217], v130 offset:864
	ds_read_b128 v[202:205], v131 offset:288
	ds_read_b128 v[218:221], v131 offset:864
	s_waitcnt lgkmcnt(6)
	v_mfma_f32_16x16x32_bf16 v[100:103], v[206:209], v[28:31], v[100:103]
	v_mfma_f32_16x16x32_bf16 v[104:107], v[206:209], v[60:63], v[104:107]
	v_mfma_f32_16x16x32_bf16 v[108:111], v[206:209], v[88:91], v[108:111]
	v_mfma_f32_16x16x32_bf16 v[112:115], v[222:225], v[28:31], v[112:115]
	v_mfma_f32_16x16x32_bf16 v[138:141], v[222:225], v[60:63], v[138:141]
	v_mfma_f32_16x16x32_bf16 v[142:145], v[222:225], v[88:91], v[142:145]
	s_waitcnt lgkmcnt(4)
	v_mfma_f32_16x16x32_bf16 v[100:103], v[210:213], v[32:35], v[100:103]
	v_mfma_f32_16x16x32_bf16 v[104:107], v[210:213], v[64:67], v[104:107]
	v_mfma_f32_16x16x32_bf16 v[112:115], v[226:229], v[32:35], v[112:115]
	v_mfma_f32_16x16x32_bf16 v[138:141], v[226:229], v[64:67], v[138:141]
	ds_read_b128 v[206:209], v130 offset:432
	ds_read_b128 v[222:225], v130 offset:1008
	ds_read_b128 v[210:213], v131 offset:432
	ds_read_b128 v[226:229], v131 offset:1008
	s_waitcnt lgkmcnt(6)
	v_mfma_f32_16x16x32_bf16 v[100:103], v[198:201], v[36:39], v[100:103]
	v_mfma_f32_16x16x32_bf16 v[104:107], v[198:201], v[68:71], v[104:107]
	v_mfma_f32_16x16x32_bf16 v[108:111], v[198:201], v[92:95], v[108:111]
	v_mfma_f32_16x16x32_bf16 v[112:115], v[214:217], v[36:39], v[112:115]
	v_mfma_f32_16x16x32_bf16 v[138:141], v[214:217], v[68:71], v[138:141]
	v_mfma_f32_16x16x32_bf16 v[142:145], v[214:217], v[92:95], v[142:145]
	s_waitcnt lgkmcnt(4)
	v_mfma_f32_16x16x32_bf16 v[100:103], v[202:205], v[40:43], v[100:103]
	v_mfma_f32_16x16x32_bf16 v[104:107], v[202:205], v[72:75], v[104:107]
	v_mfma_f32_16x16x32_bf16 v[112:115], v[218:221], v[40:43], v[112:115]
	v_mfma_f32_16x16x32_bf16 v[138:141], v[218:221], v[72:75], v[138:141]
	s_waitcnt lgkmcnt(2)
	v_mfma_f32_16x16x32_bf16 v[100:103], v[206:209], v[44:47], v[100:103]
	v_mfma_f32_16x16x32_bf16 v[104:107], v[206:209], v[76:79], v[104:107]
	v_mfma_f32_16x16x32_bf16 v[108:111], v[206:209], v[96:99], v[108:111]
	v_mfma_f32_16x16x32_bf16 v[112:115], v[222:225], v[44:47], v[112:115]
	v_mfma_f32_16x16x32_bf16 v[138:141], v[222:225], v[76:79], v[138:141]
	v_mfma_f32_16x16x32_bf16 v[142:145], v[222:225], v[96:99], v[142:145]
	s_waitcnt lgkmcnt(0)
	v_mfma_f32_16x16x32_bf16 v[100:103], v[210:213], v[48:51], v[100:103]
	v_mfma_f32_16x16x32_bf16 v[104:107], v[210:213], v[80:83], v[104:107]
	v_mfma_f32_16x16x32_bf16 v[112:115], v[226:229], v[48:51], v[112:115]
	v_mfma_f32_16x16x32_bf16 v[138:141], v[226:229], v[80:83], v[138:141]
	s_waitcnt lgkmcnt(0)
	s_barrier
	s_waitcnt vmcnt(3)
	ds_write_b128 v134, v[146:149]
	ds_write_b128 v134, v[150:153] offset:4608
	ds_write_b128 v135, v[160:163]
	s_add_i32 s64, s4, 0
	s_mul_i32 s71, s64, 0x30000
	s_add_u32 s38, s60, s71
	s_addc_u32 s39, s61, 0
	s_lshl_b32 s64, s64, 12
	global_load_dwordx4 v[8:11], v255, s[38:39]
	s_add_i32 s52, s4, 3
	s_min_u32 s52, s52, 31
	s_lshl_b32 s52, s52, 13
	s_add_u32 s26, s50, s52
	s_addc_u32 s27, s51, 0
	global_load_dwordx4 v[146:149], v154, s[26:27]
	global_load_dwordx4 v[150:153], v155, s[26:27]
	global_load_dwordx4 v[160:163], v159, s[26:27]
	v_exp_f32_e32 v198, v100
	v_exp_f32_e32 v199, v101
	v_exp_f32_e32 v200, v102
	v_exp_f32_e32 v201, v103
	v_exp_f32_e32 v202, v112
	v_exp_f32_e32 v203, v113
	v_exp_f32_e32 v204, v114
	v_exp_f32_e32 v205, v115
	v_exp_f32_e32 v214, v104
	v_add_f32_e32 v198, 1.0, v198
	v_exp_f32_e32 v215, v105
	v_add_f32_e32 v199, 1.0, v199
	v_exp_f32_e32 v216, v106
	v_add_f32_e32 v200, 1.0, v200
	v_exp_f32_e32 v217, v107
	v_add_f32_e32 v201, 1.0, v201
	v_exp_f32_e32 v218, v138
	v_add_f32_e32 v202, 1.0, v202
	v_exp_f32_e32 v219, v139
	v_add_f32_e32 v203, 1.0, v203
	v_exp_f32_e32 v220, v140
	v_add_f32_e32 v204, 1.0, v204
	v_exp_f32_e32 v221, v141
	v_add_f32_e32 v205, 1.0, v205
	v_rcp_f32_e32 v198, v198
	v_add_f32_e32 v214, 1.0, v214
	v_rcp_f32_e32 v199, v199
	v_add_f32_e32 v215, 1.0, v215
	v_rcp_f32_e32 v200, v200
	v_add_f32_e32 v216, 1.0, v216
	v_rcp_f32_e32 v201, v201
	v_add_f32_e32 v217, 1.0, v217
	v_rcp_f32_e32 v202, v202
	v_add_f32_e32 v218, 1.0, v218
	v_rcp_f32_e32 v203, v203
	v_add_f32_e32 v219, 1.0, v219
	v_rcp_f32_e32 v204, v204
	v_add_f32_e32 v220, 1.0, v220
	v_rcp_f32_e32 v205, v205
	v_add_f32_e32 v221, 1.0, v221
	v_mul_f32_e32 v198, v179, v198
	v_mul_f32_e32 v199, v179, v199
	v_mul_f32_e32 v200, v179, v200
	v_mul_f32_e32 v201, v179, v201
	v_mul_f32_e32 v202, v179, v202
	v_mul_f32_e32 v203, v179, v203
	v_mul_f32_e32 v204, v179, v204
	v_mul_f32_e32 v205, v179, v205
	v_exp_f32_e32 v120, v198
	v_exp_f32_e32 v121, v199
	v_exp_f32_e32 v122, v200
	v_exp_f32_e32 v123, v201
	v_exp_f32_e32 v124, v202
	v_exp_f32_e32 v125, v203
	v_exp_f32_e32 v126, v204
	v_exp_f32_e32 v127, v205
	v_fma_f32 v206, -v120, v120, 1.0
	v_fma_f32 v207, -v121, v121, 1.0
	v_fma_f32 v208, -v122, v122, 1.0
	v_fma_f32 v209, -v123, v123, 1.0
	v_fma_f32 v210, -v124, v124, 1.0
	v_fma_f32 v211, -v125, v125, 1.0
	v_fma_f32 v212, -v126, v126, 1.0
	v_fma_f32 v213, -v127, v127, 1.0
	v_max_f32_e32 v206, 0xda24260, v206
	v_max_f32_e32 v207, 0xda24260, v207
	v_max_f32_e32 v208, 0xda24260, v208
	v_max_f32_e32 v209, 0xda24260, v209
	v_max_f32_e32 v210, 0xda24260, v210
	v_max_f32_e32 v211, 0xda24260, v211
	v_max_f32_e32 v212, 0xda24260, v212
	v_max_f32_e32 v213, 0xda24260, v213
	v_mul_f32_e32 v198, v214, v206
	v_mul_f32_e32 v199, v215, v207
	v_mul_f32_e32 v200, v216, v208
	v_mul_f32_e32 v201, v217, v209
	v_mul_f32_e32 v202, v218, v210
	v_mul_f32_e32 v203, v219, v211
	v_mul_f32_e32 v204, v220, v212
	v_mul_f32_e32 v205, v221, v213
	v_mul_f32_e32 v214, v214, v198
	v_mul_f32_e32 v215, v215, v199
	v_mul_f32_e32 v216, v216, v200
	v_mul_f32_e32 v217, v217, v201
	v_mul_f32_e32 v218, v218, v202
	v_mul_f32_e32 v219, v219, v203
	v_mul_f32_e32 v220, v220, v204
	v_mul_f32_e32 v221, v221, v205
	v_rsq_f32_e32 v214, v214
	v_mul_f32_e32 v222, v108, v206
	v_rsq_f32_e32 v215, v215
	v_mul_f32_e32 v223, v109, v207
	v_rsq_f32_e32 v216, v216
	v_mul_f32_e32 v224, v110, v208
	v_rsq_f32_e32 v217, v217
	v_mul_f32_e32 v225, v111, v209
	v_rsq_f32_e32 v218, v218
	v_mul_f32_e32 v226, v142, v210
	v_rsq_f32_e32 v219, v219
	v_mul_f32_e32 v227, v143, v211
	v_rsq_f32_e32 v220, v220
	v_mul_f32_e32 v228, v144, v212
	v_rsq_f32_e32 v221, v221
	v_mul_f32_e32 v229, v145, v213
	v_mul_f32_e32 v170, v222, v214
	v_mul_f32_e32 v171, v223, v215
	v_mul_f32_e32 v172, v224, v216
	v_mul_f32_e32 v173, v225, v217
	v_mul_f32_e32 v174, v226, v218
	v_mul_f32_e32 v175, v227, v219
	v_mul_f32_e32 v176, v228, v220
	v_mul_f32_e32 v177, v229, v221
	v_mov_b32_e32 v198, v170
	v_mov_b32_e32 v199, v120
	v_fma_f32 v198, v121, v198, v171
	v_mul_f32_e32 v199, v199, v121
	v_fma_f32 v198, v122, v198, v172
	v_mul_f32_e32 v199, v199, v122
	v_fma_f32 v198, v123, v198, v173
	v_mul_f32_e32 v199, v199, v123
	v_fma_f32 v198, v124, v198, v174
	v_mul_f32_e32 v199, v199, v124
	v_fma_f32 v198, v125, v198, v175
	v_mul_f32_e32 v199, v199, v125
	v_fma_f32 v198, v126, v198, v176
	v_mul_f32_e32 v199, v199, v126
	v_fma_f32 v198, v127, v198, v177
	v_mul_f32_e32 v199, v199, v127
	v_mov_b32_e32 v164, v199
	v_mov_b32_e32 v166, v199
	v_mov_b32_e32 v246, v198
	v_mov_b32_e32 v248, v198
	s_nop 1
	v_permlane32_swap_b32 v164, v166
	v_permlane32_swap_b32 v246, v248
	s_nop 1
	v_mov_b32_e32 v165, v164
	v_mov_b32_e32 v167, v166
	v_mov_b32_e32 v247, v246
	v_mov_b32_e32 v249, v248
	s_nop 1
	v_permlane16_swap_b32 v164, v165
	v_permlane16_swap_b32 v166, v167
	v_permlane16_swap_b32 v246, v247
	v_permlane16_swap_b32 v248, v249
	s_nop 1
	v_mov_b32_e32 v251, v246
	v_mov_b32_e32 v250, v164
	v_fma_f32 v251, v251, v165, v247
	v_mul_f32_e32 v250, v250, v165
	v_fma_f32 v251, v251, v166, v248
	v_mul_f32_e32 v250, v250, v166
	v_fma_f32 v251, v251, v167, v249
	v_mul_f32_e32 v250, v250, v167
	s_mov_b64 exec, s[10:11]
	ds_write_b64 v182, v[250:251] offset:0
	s_mov_b64 exec, -1
	s_waitcnt lgkmcnt(0)
	s_barrier
	ds_read2_b64 v[4:7], v183 offset0:0 offset1:16
	s_add_i32 s52, s4, 0
	s_lshl_b32 s52, s52, 12
	v_add_u32_e32 v197, s52, v184
	s_waitcnt lgkmcnt(0)
	v_fma_f32 v198, v180, v4, v5
	v_cndmask_b32_e64 v199, v180, v198, s[24:25]
	v_fma_f32 v180, v198, v6, v7
	v_fma_f32 v200, v199, v164, v246
	v_cndmask_b32_e64 v199, v199, v200, s[16:17]
	v_fma_f32 v200, v199, v165, v247
	v_cndmask_b32_e64 v199, v199, v200, s[20:21]
	v_fma_f32 v200, v199, v166, v248
	v_cndmask_b32_e64 v199, v199, v200, s[22:23]
	v_fma_f32 v214, v120, v199, v170
	v_fma_f32 v215, v121, v214, v171
	v_fma_f32 v216, v122, v215, v172
	v_fma_f32 v217, v123, v216, v173
	v_fma_f32 v218, v124, v217, v174
	v_fma_f32 v219, v125, v218, v175
	v_fma_f32 v220, v126, v219, v176
	v_fma_f32 v221, v127, v220, v177
	ds_read_u16 v206, v197 offset:0
	ds_read_u16 v207, v197 offset:64
	ds_read_u16 v208, v197 offset:128
	ds_read_u16 v209, v197 offset:192
	ds_read_u16 v210, v197 offset:256
	ds_read_u16 v211, v197 offset:320
	ds_read_u16 v212, v197 offset:384
	ds_read_u16 v213, v197 offset:448
	s_waitcnt lgkmcnt(0)
	v_lshlrev_b32_e32 v206, 16, v206
	v_lshlrev_b32_e32 v207, 16, v207
	v_lshlrev_b32_e32 v208, 16, v208
	v_lshlrev_b32_e32 v209, 16, v209
	v_lshlrev_b32_e32 v210, 16, v210
	v_lshlrev_b32_e32 v211, 16, v211
	v_lshlrev_b32_e32 v212, 16, v212
	v_lshlrev_b32_e32 v213, 16, v213
	v_add_f32_e32 v214, v214, v206
	v_add_f32_e32 v215, v215, v207
	v_add_f32_e32 v216, v216, v208
	v_add_f32_e32 v217, v217, v209
	v_add_f32_e32 v218, v218, v210
	v_add_f32_e32 v219, v219, v211
	v_add_f32_e32 v220, v220, v212
	v_add_f32_e32 v221, v221, v213
	v_cvt_pk_bf16_f32 v206, v214, v215
	v_cvt_pk_bf16_f32 v208, v216, v217
	v_cvt_pk_bf16_f32 v210, v218, v219
	v_cvt_pk_bf16_f32 v212, v220, v221
	ds_write_b16 v197, v206 offset:0
	ds_write_b16_d16_hi v197, v206 offset:64
	ds_write_b16 v197, v208 offset:128
	ds_write_b16_d16_hi v197, v208 offset:192
	ds_write_b16 v197, v210 offset:256
	ds_write_b16_d16_hi v197, v210 offset:320
	ds_write_b16 v197, v212 offset:384
	ds_write_b16_d16_hi v197, v212 offset:448
	ds_read_b128 v[198:201], v130 offset:0
	ds_read_b128 v[214:217], v130 offset:576
	ds_read_b128 v[202:205], v131 offset:0
	ds_read_b128 v[218:221], v131 offset:576
	ds_read_b128 v[206:209], v130 offset:144
	ds_read_b128 v[222:225], v130 offset:720
	ds_read_b128 v[210:213], v131 offset:144
	s_waitcnt lgkmcnt(14)
	ds_read_b128 v[226:229], v131 offset:720
	s_waitcnt lgkmcnt(6)
	v_mfma_f32_16x16x32_bf16 v[100:103], v[198:201], v[20:23], v[12:15]
	v_mfma_f32_16x16x32_bf16 v[104:107], v[198:201], v[52:55], v[16:19]
	v_mfma_f32_16x16x32_bf16 v[108:111], v[198:201], v[84:87], v[242:245]
	v_mfma_f32_16x16x32_bf16 v[112:115], v[214:217], v[20:23], v[12:15]
	v_mfma_f32_16x16x32_bf16 v[138:141], v[214:217], v[52:55], v[16:19]
	v_mfma_f32_16x16x32_bf16 v[142:145], v[214:217], v[84:87], v[242:245]
	s_waitcnt lgkmcnt(4)
	v_mfma_f32_16x16x32_bf16 v[100:103], v[202:205], v[24:27], v[100:103]
	v_mfma_f32_16x16x32_bf16 v[104:107], v[202:205], v[56:59], v[104:107]
	v_mfma_f32_16x16x32_bf16 v[112:115], v[218:221], v[24:27], v[112:115]
	v_mfma_f32_16x16x32_bf16 v[138:141], v[218:221], v[56:59], v[138:141]
	ds_read_b128 v[198:201], v130 offset:288
	ds_read_b128 v[214:217], v130 offset:864
	ds_read_b128 v[202:205], v131 offset:288
	ds_read_b128 v[218:221], v131 offset:864
	s_waitcnt lgkmcnt(6)
	v_mfma_f32_16x16x32_bf16 v[100:103], v[206:209], v[28:31], v[100:103]
	v_mfma_f32_16x16x32_bf16 v[104:107], v[206:209], v[60:63], v[104:107]
	v_mfma_f32_16x16x32_bf16 v[108:111], v[206:209], v[88:91], v[108:111]
	v_mfma_f32_16x16x32_bf16 v[112:115], v[222:225], v[28:31], v[112:115]
	v_mfma_f32_16x16x32_bf16 v[138:141], v[222:225], v[60:63], v[138:141]
	v_mfma_f32_16x16x32_bf16 v[142:145], v[222:225], v[88:91], v[142:145]
	s_waitcnt lgkmcnt(4)
	v_mfma_f32_16x16x32_bf16 v[100:103], v[210:213], v[32:35], v[100:103]
	v_mfma_f32_16x16x32_bf16 v[104:107], v[210:213], v[64:67], v[104:107]
	v_mfma_f32_16x16x32_bf16 v[112:115], v[226:229], v[32:35], v[112:115]
	v_mfma_f32_16x16x32_bf16 v[138:141], v[226:229], v[64:67], v[138:141]
	ds_read_b128 v[206:209], v130 offset:432
	ds_read_b128 v[222:225], v130 offset:1008
	ds_read_b128 v[210:213], v131 offset:432
	ds_read_b128 v[226:229], v131 offset:1008
	s_waitcnt lgkmcnt(6)
	v_mfma_f32_16x16x32_bf16 v[100:103], v[198:201], v[36:39], v[100:103]
	v_mfma_f32_16x16x32_bf16 v[104:107], v[198:201], v[68:71], v[104:107]
	v_mfma_f32_16x16x32_bf16 v[108:111], v[198:201], v[92:95], v[108:111]
	v_mfma_f32_16x16x32_bf16 v[112:115], v[214:217], v[36:39], v[112:115]
	v_mfma_f32_16x16x32_bf16 v[138:141], v[214:217], v[68:71], v[138:141]
	v_mfma_f32_16x16x32_bf16 v[142:145], v[214:217], v[92:95], v[142:145]
	s_waitcnt lgkmcnt(4)
	v_mfma_f32_16x16x32_bf16 v[100:103], v[202:205], v[40:43], v[100:103]
	v_mfma_f32_16x16x32_bf16 v[104:107], v[202:205], v[72:75], v[104:107]
	v_mfma_f32_16x16x32_bf16 v[112:115], v[218:221], v[40:43], v[112:115]
	v_mfma_f32_16x16x32_bf16 v[138:141], v[218:221], v[72:75], v[138:141]
	s_waitcnt lgkmcnt(2)
	v_mfma_f32_16x16x32_bf16 v[100:103], v[206:209], v[44:47], v[100:103]
	v_mfma_f32_16x16x32_bf16 v[104:107], v[206:209], v[76:79], v[104:107]
	v_mfma_f32_16x16x32_bf16 v[108:111], v[206:209], v[96:99], v[108:111]
	v_mfma_f32_16x16x32_bf16 v[112:115], v[222:225], v[44:47], v[112:115]
	v_mfma_f32_16x16x32_bf16 v[138:141], v[222:225], v[76:79], v[138:141]
	v_mfma_f32_16x16x32_bf16 v[142:145], v[222:225], v[96:99], v[142:145]
	s_waitcnt lgkmcnt(0)
	v_mfma_f32_16x16x32_bf16 v[100:103], v[210:213], v[48:51], v[100:103]
	v_mfma_f32_16x16x32_bf16 v[104:107], v[210:213], v[80:83], v[104:107]
	v_mfma_f32_16x16x32_bf16 v[112:115], v[226:229], v[48:51], v[112:115]
	v_mfma_f32_16x16x32_bf16 v[138:141], v[226:229], v[80:83], v[138:141]
	s_waitcnt lgkmcnt(0)
	s_barrier
	s_waitcnt vmcnt(4)
	ds_write_b128 v134, v[230:233]
	ds_write_b128 v134, v[234:237] offset:4608
	ds_write_b128 v135, v[238:241]
	s_add_i32 s64, s4, 0
	s_mul_i32 s71, s64, 0x30000
	s_add_u32 s38, s60, s71
	s_addc_u32 s39, s61, 0
	s_lshl_b32 s64, s64, 12
	v_add_u32_e32 v136, s64, v195
	ds_read_b128 v[116:119], v136
	s_waitcnt vmcnt(3)
	s_waitcnt lgkmcnt(0)
	v_lshlrev_b32_e32 v136, 16, v116
	v_lshlrev_b32_e32 v137, 16, v8
	v_and_b32_e32 v168, 0xffff0000, v116
	v_and_b32_e32 v169, 0xffff0000, v8
	v_mul_f32_e32 v136, v136, v137
	v_mul_f32_e32 v168, v168, v169
	v_cvt_pk_bf16_f32 v116, v136, v168
	v_lshlrev_b32_e32 v136, 16, v117
	v_lshlrev_b32_e32 v137, 16, v9
	v_and_b32_e32 v168, 0xffff0000, v117
	v_and_b32_e32 v169, 0xffff0000, v9
	v_mul_f32_e32 v136, v136, v137
	v_mul_f32_e32 v168, v168, v169
	v_cvt_pk_bf16_f32 v117, v136, v168
	v_lshlrev_b32_e32 v136, 16, v118
	v_lshlrev_b32_e32 v137, 16, v10
	v_and_b32_e32 v168, 0xffff0000, v118
	v_and_b32_e32 v169, 0xffff0000, v10
	v_mul_f32_e32 v136, v136, v137
	v_mul_f32_e32 v168, v168, v169
	v_cvt_pk_bf16_f32 v118, v136, v168
	v_lshlrev_b32_e32 v136, 16, v119
	v_lshlrev_b32_e32 v137, 16, v11
	v_and_b32_e32 v168, 0xffff0000, v119
	v_and_b32_e32 v169, 0xffff0000, v11
	v_mul_f32_e32 v136, v136, v137
	v_mul_f32_e32 v168, v168, v169
	v_cvt_pk_bf16_f32 v119, v136, v168
	global_store_dwordx4 v255, v[116:119], s[38:39]
	s_add_i32 s64, s4, 1
	s_mul_i32 s71, s64, 0x30000
	s_add_u32 s38, s60, s71
	s_addc_u32 s39, s61, 0
	s_lshl_b32 s64, s64, 12
	global_load_dwordx4 v[8:11], v255, s[38:39]
	s_add_i32 s52, s4, 4
	s_min_u32 s52, s52, 31
	s_lshl_b32 s52, s52, 13
	s_add_u32 s26, s50, s52
	s_addc_u32 s27, s51, 0
	global_load_dwordx4 v[230:233], v154, s[26:27]
	global_load_dwordx4 v[234:237], v155, s[26:27]
	global_load_dwordx4 v[238:241], v159, s[26:27]
	v_exp_f32_e32 v198, v100
	v_exp_f32_e32 v199, v101
	v_exp_f32_e32 v200, v102
	v_exp_f32_e32 v201, v103
	v_exp_f32_e32 v202, v112
	v_exp_f32_e32 v203, v113
	v_exp_f32_e32 v204, v114
	v_exp_f32_e32 v205, v115
	v_exp_f32_e32 v214, v104
	v_add_f32_e32 v198, 1.0, v198
	v_exp_f32_e32 v215, v105
	v_add_f32_e32 v199, 1.0, v199
	v_exp_f32_e32 v216, v106
	v_add_f32_e32 v200, 1.0, v200
	v_exp_f32_e32 v217, v107
	v_add_f32_e32 v201, 1.0, v201
	v_exp_f32_e32 v218, v138
	v_add_f32_e32 v202, 1.0, v202
	v_exp_f32_e32 v219, v139
	v_add_f32_e32 v203, 1.0, v203
	v_exp_f32_e32 v220, v140
	v_add_f32_e32 v204, 1.0, v204
	v_exp_f32_e32 v221, v141
	v_add_f32_e32 v205, 1.0, v205
	v_rcp_f32_e32 v198, v198
	v_add_f32_e32 v214, 1.0, v214
	v_rcp_f32_e32 v199, v199
	v_add_f32_e32 v215, 1.0, v215
	v_rcp_f32_e32 v200, v200
	v_add_f32_e32 v216, 1.0, v216
	v_rcp_f32_e32 v201, v201
	v_add_f32_e32 v217, 1.0, v217
	v_rcp_f32_e32 v202, v202
	v_add_f32_e32 v218, 1.0, v218
	v_rcp_f32_e32 v203, v203
	v_add_f32_e32 v219, 1.0, v219
	v_rcp_f32_e32 v204, v204
	v_add_f32_e32 v220, 1.0, v220
	v_rcp_f32_e32 v205, v205
	v_add_f32_e32 v221, 1.0, v221
	v_mul_f32_e32 v198, v179, v198
	v_mul_f32_e32 v199, v179, v199
	v_mul_f32_e32 v200, v179, v200
	v_mul_f32_e32 v201, v179, v201
	v_mul_f32_e32 v202, v179, v202
	v_mul_f32_e32 v203, v179, v203
	v_mul_f32_e32 v204, v179, v204
	v_mul_f32_e32 v205, v179, v205
	v_exp_f32_e32 v120, v198
	v_exp_f32_e32 v121, v199
	v_exp_f32_e32 v122, v200
	v_exp_f32_e32 v123, v201
	v_exp_f32_e32 v124, v202
	v_exp_f32_e32 v125, v203
	v_exp_f32_e32 v126, v204
	v_exp_f32_e32 v127, v205
	v_fma_f32 v206, -v120, v120, 1.0
	v_fma_f32 v207, -v121, v121, 1.0
	v_fma_f32 v208, -v122, v122, 1.0
	v_fma_f32 v209, -v123, v123, 1.0
	v_fma_f32 v210, -v124, v124, 1.0
	v_fma_f32 v211, -v125, v125, 1.0
	v_fma_f32 v212, -v126, v126, 1.0
	v_fma_f32 v213, -v127, v127, 1.0
	v_max_f32_e32 v206, 0xda24260, v206
	v_max_f32_e32 v207, 0xda24260, v207
	v_max_f32_e32 v208, 0xda24260, v208
	v_max_f32_e32 v209, 0xda24260, v209
	v_max_f32_e32 v210, 0xda24260, v210
	v_max_f32_e32 v211, 0xda24260, v211
	v_max_f32_e32 v212, 0xda24260, v212
	v_max_f32_e32 v213, 0xda24260, v213
	v_mul_f32_e32 v198, v214, v206
	v_mul_f32_e32 v199, v215, v207
	v_mul_f32_e32 v200, v216, v208
	v_mul_f32_e32 v201, v217, v209
	v_mul_f32_e32 v202, v218, v210
	v_mul_f32_e32 v203, v219, v211
	v_mul_f32_e32 v204, v220, v212
	v_mul_f32_e32 v205, v221, v213
	v_mul_f32_e32 v214, v214, v198
	v_mul_f32_e32 v215, v215, v199
	v_mul_f32_e32 v216, v216, v200
	v_mul_f32_e32 v217, v217, v201
	v_mul_f32_e32 v218, v218, v202
	v_mul_f32_e32 v219, v219, v203
	v_mul_f32_e32 v220, v220, v204
	v_mul_f32_e32 v221, v221, v205
	v_rsq_f32_e32 v214, v214
	v_mul_f32_e32 v222, v108, v206
	v_rsq_f32_e32 v215, v215
	v_mul_f32_e32 v223, v109, v207
	v_rsq_f32_e32 v216, v216
	v_mul_f32_e32 v224, v110, v208
	v_rsq_f32_e32 v217, v217
	v_mul_f32_e32 v225, v111, v209
	v_rsq_f32_e32 v218, v218
	v_mul_f32_e32 v226, v142, v210
	v_rsq_f32_e32 v219, v219
	v_mul_f32_e32 v227, v143, v211
	v_rsq_f32_e32 v220, v220
	v_mul_f32_e32 v228, v144, v212
	v_rsq_f32_e32 v221, v221
	v_mul_f32_e32 v229, v145, v213
	v_mul_f32_e32 v170, v222, v214
	v_mul_f32_e32 v171, v223, v215
	v_mul_f32_e32 v172, v224, v216
	v_mul_f32_e32 v173, v225, v217
	v_mul_f32_e32 v174, v226, v218
	v_mul_f32_e32 v175, v227, v219
	v_mul_f32_e32 v176, v228, v220
	v_mul_f32_e32 v177, v229, v221
	v_mov_b32_e32 v198, v170
	v_mov_b32_e32 v199, v120
	v_fma_f32 v198, v121, v198, v171
	v_mul_f32_e32 v199, v199, v121
	v_fma_f32 v198, v122, v198, v172
	v_mul_f32_e32 v199, v199, v122
	v_fma_f32 v198, v123, v198, v173
	v_mul_f32_e32 v199, v199, v123
	v_fma_f32 v198, v124, v198, v174
	v_mul_f32_e32 v199, v199, v124
	v_fma_f32 v198, v125, v198, v175
	v_mul_f32_e32 v199, v199, v125
	v_fma_f32 v198, v126, v198, v176
	v_mul_f32_e32 v199, v199, v126
	v_fma_f32 v198, v127, v198, v177
	v_mul_f32_e32 v199, v199, v127
	v_mov_b32_e32 v164, v199
	v_mov_b32_e32 v166, v199
	v_mov_b32_e32 v246, v198
	v_mov_b32_e32 v248, v198
	s_nop 1
	v_permlane32_swap_b32 v164, v166
	v_permlane32_swap_b32 v246, v248
	s_nop 1
	v_mov_b32_e32 v165, v164
	v_mov_b32_e32 v167, v166
	v_mov_b32_e32 v247, v246
	v_mov_b32_e32 v249, v248
	s_nop 1
	v_permlane16_swap_b32 v164, v165
	v_permlane16_swap_b32 v166, v167
	v_permlane16_swap_b32 v246, v247
	v_permlane16_swap_b32 v248, v249
	s_nop 1
	v_mov_b32_e32 v251, v246
	v_mov_b32_e32 v250, v164
	v_fma_f32 v251, v251, v165, v247
	v_mul_f32_e32 v250, v250, v165
	v_fma_f32 v251, v251, v166, v248
	v_mul_f32_e32 v250, v250, v166
	v_fma_f32 v251, v251, v167, v249
	v_mul_f32_e32 v250, v250, v167
	s_mov_b64 exec, s[10:11]
	ds_write_b64 v182, v[250:251] offset:1024
	s_mov_b64 exec, -1
	s_waitcnt lgkmcnt(0)
	s_barrier
	ds_read2_b64 v[4:7], v183 offset0:128 offset1:144
	s_add_i32 s52, s4, 1
	s_lshl_b32 s52, s52, 12
	v_add_u32_e32 v197, s52, v184
	s_waitcnt lgkmcnt(0)
	v_fma_f32 v198, v180, v4, v5
	v_cndmask_b32_e64 v199, v180, v198, s[24:25]
	v_fma_f32 v180, v198, v6, v7
	v_fma_f32 v200, v199, v164, v246
	v_cndmask_b32_e64 v199, v199, v200, s[16:17]
	v_fma_f32 v200, v199, v165, v247
	v_cndmask_b32_e64 v199, v199, v200, s[20:21]
	v_fma_f32 v200, v199, v166, v248
	v_cndmask_b32_e64 v199, v199, v200, s[22:23]
	v_fma_f32 v214, v120, v199, v170
	v_fma_f32 v215, v121, v214, v171
	v_fma_f32 v216, v122, v215, v172
	v_fma_f32 v217, v123, v216, v173
	v_fma_f32 v218, v124, v217, v174
	v_fma_f32 v219, v125, v218, v175
	v_fma_f32 v220, v126, v219, v176
	v_fma_f32 v221, v127, v220, v177
	ds_read_u16 v206, v197 offset:0
	ds_read_u16 v207, v197 offset:64
	ds_read_u16 v208, v197 offset:128
	ds_read_u16 v209, v197 offset:192
	ds_read_u16 v210, v197 offset:256
	ds_read_u16 v211, v197 offset:320
	ds_read_u16 v212, v197 offset:384
	ds_read_u16 v213, v197 offset:448
	s_waitcnt lgkmcnt(0)
	v_lshlrev_b32_e32 v206, 16, v206
	v_lshlrev_b32_e32 v207, 16, v207
	v_lshlrev_b32_e32 v208, 16, v208
	v_lshlrev_b32_e32 v209, 16, v209
	v_lshlrev_b32_e32 v210, 16, v210
	v_lshlrev_b32_e32 v211, 16, v211
	v_lshlrev_b32_e32 v212, 16, v212
	v_lshlrev_b32_e32 v213, 16, v213
	v_add_f32_e32 v214, v214, v206
	v_add_f32_e32 v215, v215, v207
	v_add_f32_e32 v216, v216, v208
	v_add_f32_e32 v217, v217, v209
	v_add_f32_e32 v218, v218, v210
	v_add_f32_e32 v219, v219, v211
	v_add_f32_e32 v220, v220, v212
	v_add_f32_e32 v221, v221, v213
	v_cvt_pk_bf16_f32 v206, v214, v215
	v_cvt_pk_bf16_f32 v208, v216, v217
	v_cvt_pk_bf16_f32 v210, v218, v219
	v_cvt_pk_bf16_f32 v212, v220, v221
	ds_write_b16 v197, v206 offset:0
	ds_write_b16_d16_hi v197, v206 offset:64
	ds_write_b16 v197, v208 offset:128
	ds_write_b16_d16_hi v197, v208 offset:192
	ds_write_b16 v197, v210 offset:256
	ds_write_b16_d16_hi v197, v210 offset:320
	ds_write_b16 v197, v212 offset:384
	ds_write_b16_d16_hi v197, v212 offset:448
	s_add_i32 s4, s4, 2
.Lrec2_loopB_d0:
	ds_read_b128 v[198:201], v130 offset:0
	ds_read_b128 v[214:217], v130 offset:576
	ds_read_b128 v[202:205], v131 offset:0
	ds_read_b128 v[218:221], v131 offset:576
	ds_read_b128 v[206:209], v130 offset:144
	ds_read_b128 v[222:225], v130 offset:720
	ds_read_b128 v[210:213], v131 offset:144
	s_waitcnt lgkmcnt(14)
	ds_read_b128 v[226:229], v131 offset:720
	s_waitcnt lgkmcnt(6)
	v_mfma_f32_16x16x32_bf16 v[100:103], v[198:201], v[20:23], v[12:15]
	v_mfma_f32_16x16x32_bf16 v[104:107], v[198:201], v[52:55], v[16:19]
	v_mfma_f32_16x16x32_bf16 v[108:111], v[198:201], v[84:87], v[242:245]
	v_mfma_f32_16x16x32_bf16 v[112:115], v[214:217], v[20:23], v[12:15]
	v_mfma_f32_16x16x32_bf16 v[138:141], v[214:217], v[52:55], v[16:19]
	v_mfma_f32_16x16x32_bf16 v[142:145], v[214:217], v[84:87], v[242:245]
	s_waitcnt lgkmcnt(4)
	v_mfma_f32_16x16x32_bf16 v[100:103], v[202:205], v[24:27], v[100:103]
	v_mfma_f32_16x16x32_bf16 v[104:107], v[202:205], v[56:59], v[104:107]
	v_mfma_f32_16x16x32_bf16 v[112:115], v[218:221], v[24:27], v[112:115]
	v_mfma_f32_16x16x32_bf16 v[138:141], v[218:221], v[56:59], v[138:141]
	ds_read_b128 v[198:201], v130 offset:288
	ds_read_b128 v[214:217], v130 offset:864
	ds_read_b128 v[202:205], v131 offset:288
	ds_read_b128 v[218:221], v131 offset:864
	s_waitcnt lgkmcnt(6)
	v_mfma_f32_16x16x32_bf16 v[100:103], v[206:209], v[28:31], v[100:103]
	v_mfma_f32_16x16x32_bf16 v[104:107], v[206:209], v[60:63], v[104:107]
	v_mfma_f32_16x16x32_bf16 v[108:111], v[206:209], v[88:91], v[108:111]
	v_mfma_f32_16x16x32_bf16 v[112:115], v[222:225], v[28:31], v[112:115]
	v_mfma_f32_16x16x32_bf16 v[138:141], v[222:225], v[60:63], v[138:141]
	v_mfma_f32_16x16x32_bf16 v[142:145], v[222:225], v[88:91], v[142:145]
	s_waitcnt lgkmcnt(4)
	v_mfma_f32_16x16x32_bf16 v[100:103], v[210:213], v[32:35], v[100:103]
	v_mfma_f32_16x16x32_bf16 v[104:107], v[210:213], v[64:67], v[104:107]
	v_mfma_f32_16x16x32_bf16 v[112:115], v[226:229], v[32:35], v[112:115]
	v_mfma_f32_16x16x32_bf16 v[138:141], v[226:229], v[64:67], v[138:141]
	ds_read_b128 v[206:209], v130 offset:432
	ds_read_b128 v[222:225], v130 offset:1008
	ds_read_b128 v[210:213], v131 offset:432
	ds_read_b128 v[226:229], v131 offset:1008
	s_waitcnt lgkmcnt(6)
	v_mfma_f32_16x16x32_bf16 v[100:103], v[198:201], v[36:39], v[100:103]
	v_mfma_f32_16x16x32_bf16 v[104:107], v[198:201], v[68:71], v[104:107]
	v_mfma_f32_16x16x32_bf16 v[108:111], v[198:201], v[92:95], v[108:111]
	v_mfma_f32_16x16x32_bf16 v[112:115], v[214:217], v[36:39], v[112:115]
	v_mfma_f32_16x16x32_bf16 v[138:141], v[214:217], v[68:71], v[138:141]
	v_mfma_f32_16x16x32_bf16 v[142:145], v[214:217], v[92:95], v[142:145]
	s_waitcnt lgkmcnt(4)
	v_mfma_f32_16x16x32_bf16 v[100:103], v[202:205], v[40:43], v[100:103]
	v_mfma_f32_16x16x32_bf16 v[104:107], v[202:205], v[72:75], v[104:107]
	v_mfma_f32_16x16x32_bf16 v[112:115], v[218:221], v[40:43], v[112:115]
	v_mfma_f32_16x16x32_bf16 v[138:141], v[218:221], v[72:75], v[138:141]
	s_waitcnt lgkmcnt(2)
	v_mfma_f32_16x16x32_bf16 v[100:103], v[206:209], v[44:47], v[100:103]
	v_mfma_f32_16x16x32_bf16 v[104:107], v[206:209], v[76:79], v[104:107]
	v_mfma_f32_16x16x32_bf16 v[108:111], v[206:209], v[96:99], v[108:111]
	v_mfma_f32_16x16x32_bf16 v[112:115], v[222:225], v[44:47], v[112:115]
	v_mfma_f32_16x16x32_bf16 v[138:141], v[222:225], v[76:79], v[138:141]
	v_mfma_f32_16x16x32_bf16 v[142:145], v[222:225], v[96:99], v[142:145]
	s_waitcnt lgkmcnt(0)
	v_mfma_f32_16x16x32_bf16 v[100:103], v[210:213], v[48:51], v[100:103]
	v_mfma_f32_16x16x32_bf16 v[104:107], v[210:213], v[80:83], v[104:107]
	v_mfma_f32_16x16x32_bf16 v[112:115], v[226:229], v[48:51], v[112:115]
	v_mfma_f32_16x16x32_bf16 v[138:141], v[226:229], v[80:83], v[138:141]
	s_waitcnt lgkmcnt(0)
	s_barrier
	s_waitcnt vmcnt(5)
	ds_write_b128 v134, v[146:149]
	ds_write_b128 v134, v[150:153] offset:4608
	ds_write_b128 v135, v[160:163]
	s_add_i32 s64, s4, -1
	s_mul_i32 s71, s64, 0x30000
	s_add_u32 s38, s60, s71
	s_addc_u32 s39, s61, 0
	s_lshl_b32 s64, s64, 12
	v_add_u32_e32 v136, s64, v195
	ds_read_b128 v[116:119], v136
	s_waitcnt vmcnt(3)
	s_waitcnt lgkmcnt(0)
	v_lshlrev_b32_e32 v136, 16, v116
	v_lshlrev_b32_e32 v137, 16, v8
	v_and_b32_e32 v168, 0xffff0000, v116
	v_and_b32_e32 v169, 0xffff0000, v8
	v_mul_f32_e32 v136, v136, v137
	v_mul_f32_e32 v168, v168, v169
	v_cvt_pk_bf16_f32 v116, v136, v168
	v_lshlrev_b32_e32 v136, 16, v117
	v_lshlrev_b32_e32 v137, 16, v9
	v_and_b32_e32 v168, 0xffff0000, v117
	v_and_b32_e32 v169, 0xffff0000, v9
	v_mul_f32_e32 v136, v136, v137
	v_mul_f32_e32 v168, v168, v169
	v_cvt_pk_bf16_f32 v117, v136, v168
	v_lshlrev_b32_e32 v136, 16, v118
	v_lshlrev_b32_e32 v137, 16, v10
	v_and_b32_e32 v168, 0xffff0000, v118
	v_and_b32_e32 v169, 0xffff0000, v10
	v_mul_f32_e32 v136, v136, v137
	v_mul_f32_e32 v168, v168, v169
	v_cvt_pk_bf16_f32 v118, v136, v168
	v_lshlrev_b32_e32 v136, 16, v119
	v_lshlrev_b32_e32 v137, 16, v11
	v_and_b32_e32 v168, 0xffff0000, v119
	v_and_b32_e32 v169, 0xffff0000, v11
	v_mul_f32_e32 v136, v136, v137
	v_mul_f32_e32 v168, v168, v169
	v_cvt_pk_bf16_f32 v119, v136, v168
	global_store_dwordx4 v255, v[116:119], s[38:39]
	s_add_i32 s64, s4, 0
	s_mul_i32 s71, s64, 0x30000
	s_add_u32 s38, s60, s71
	s_addc_u32 s39, s61, 0
	s_lshl_b32 s64, s64, 12
	global_load_dwordx4 v[8:11], v255, s[38:39]
	s_add_i32 s52, s4, 3
	s_min_u32 s52, s52, 31
	s_lshl_b32 s52, s52, 13
	s_add_u32 s26, s50, s52
	s_addc_u32 s27, s51, 0
	global_load_dwordx4 v[146:149], v154, s[26:27]
	global_load_dwordx4 v[150:153], v155, s[26:27]
	global_load_dwordx4 v[160:163], v159, s[26:27]
	v_exp_f32_e32 v198, v100
	v_exp_f32_e32 v199, v101
	v_exp_f32_e32 v200, v102
	v_exp_f32_e32 v201, v103
	v_exp_f32_e32 v202, v112
	v_exp_f32_e32 v203, v113
	v_exp_f32_e32 v204, v114
	v_exp_f32_e32 v205, v115
	v_exp_f32_e32 v214, v104
	v_add_f32_e32 v198, 1.0, v198
	v_exp_f32_e32 v215, v105
	v_add_f32_e32 v199, 1.0, v199
	v_exp_f32_e32 v216, v106
	v_add_f32_e32 v200, 1.0, v200
	v_exp_f32_e32 v217, v107
	v_add_f32_e32 v201, 1.0, v201
	v_exp_f32_e32 v218, v138
	v_add_f32_e32 v202, 1.0, v202
	v_exp_f32_e32 v219, v139
	v_add_f32_e32 v203, 1.0, v203
	v_exp_f32_e32 v220, v140
	v_add_f32_e32 v204, 1.0, v204
	v_exp_f32_e32 v221, v141
	v_add_f32_e32 v205, 1.0, v205
	v_rcp_f32_e32 v198, v198
	v_add_f32_e32 v214, 1.0, v214
	v_rcp_f32_e32 v199, v199
	v_add_f32_e32 v215, 1.0, v215
	v_rcp_f32_e32 v200, v200
	v_add_f32_e32 v216, 1.0, v216
	v_rcp_f32_e32 v201, v201
	v_add_f32_e32 v217, 1.0, v217
	v_rcp_f32_e32 v202, v202
	v_add_f32_e32 v218, 1.0, v218
	v_rcp_f32_e32 v203, v203
	v_add_f32_e32 v219, 1.0, v219
	v_rcp_f32_e32 v204, v204
	v_add_f32_e32 v220, 1.0, v220
	v_rcp_f32_e32 v205, v205
	v_add_f32_e32 v221, 1.0, v221
	v_mul_f32_e32 v198, v179, v198
	v_mul_f32_e32 v199, v179, v199
	v_mul_f32_e32 v200, v179, v200
	v_mul_f32_e32 v201, v179, v201
	v_mul_f32_e32 v202, v179, v202
	v_mul_f32_e32 v203, v179, v203
	v_mul_f32_e32 v204, v179, v204
	v_mul_f32_e32 v205, v179, v205
	v_exp_f32_e32 v120, v198
	v_exp_f32_e32 v121, v199
	v_exp_f32_e32 v122, v200
	v_exp_f32_e32 v123, v201
	v_exp_f32_e32 v124, v202
	v_exp_f32_e32 v125, v203
	v_exp_f32_e32 v126, v204
	v_exp_f32_e32 v127, v205
	v_fma_f32 v206, -v120, v120, 1.0
	v_fma_f32 v207, -v121, v121, 1.0
	v_fma_f32 v208, -v122, v122, 1.0
	v_fma_f32 v209, -v123, v123, 1.0
	v_fma_f32 v210, -v124, v124, 1.0
	v_fma_f32 v211, -v125, v125, 1.0
	v_fma_f32 v212, -v126, v126, 1.0
	v_fma_f32 v213, -v127, v127, 1.0
	v_max_f32_e32 v206, 0xda24260, v206
	v_max_f32_e32 v207, 0xda24260, v207
	v_max_f32_e32 v208, 0xda24260, v208
	v_max_f32_e32 v209, 0xda24260, v209
	v_max_f32_e32 v210, 0xda24260, v210
	v_max_f32_e32 v211, 0xda24260, v211
	v_max_f32_e32 v212, 0xda24260, v212
	v_max_f32_e32 v213, 0xda24260, v213
	v_mul_f32_e32 v198, v214, v206
	v_mul_f32_e32 v199, v215, v207
	v_mul_f32_e32 v200, v216, v208
	v_mul_f32_e32 v201, v217, v209
	v_mul_f32_e32 v202, v218, v210
	v_mul_f32_e32 v203, v219, v211
	v_mul_f32_e32 v204, v220, v212
	v_mul_f32_e32 v205, v221, v213
	v_mul_f32_e32 v214, v214, v198
	v_mul_f32_e32 v215, v215, v199
	v_mul_f32_e32 v216, v216, v200
	v_mul_f32_e32 v217, v217, v201
	v_mul_f32_e32 v218, v218, v202
	v_mul_f32_e32 v219, v219, v203
	v_mul_f32_e32 v220, v220, v204
	v_mul_f32_e32 v221, v221, v205
	v_rsq_f32_e32 v214, v214
	v_mul_f32_e32 v222, v108, v206
	v_rsq_f32_e32 v215, v215
	v_mul_f32_e32 v223, v109, v207
	v_rsq_f32_e32 v216, v216
	v_mul_f32_e32 v224, v110, v208
	v_rsq_f32_e32 v217, v217
	v_mul_f32_e32 v225, v111, v209
	v_rsq_f32_e32 v218, v218
	v_mul_f32_e32 v226, v142, v210
	v_rsq_f32_e32 v219, v219
	v_mul_f32_e32 v227, v143, v211
	v_rsq_f32_e32 v220, v220
	v_mul_f32_e32 v228, v144, v212
	v_rsq_f32_e32 v221, v221
	v_mul_f32_e32 v229, v145, v213
	v_mul_f32_e32 v170, v222, v214
	v_mul_f32_e32 v171, v223, v215
	v_mul_f32_e32 v172, v224, v216
	v_mul_f32_e32 v173, v225, v217
	v_mul_f32_e32 v174, v226, v218
	v_mul_f32_e32 v175, v227, v219
	v_mul_f32_e32 v176, v228, v220
	v_mul_f32_e32 v177, v229, v221
	v_mov_b32_e32 v198, v170
	v_mov_b32_e32 v199, v120
	v_fma_f32 v198, v121, v198, v171
	v_mul_f32_e32 v199, v199, v121
	v_fma_f32 v198, v122, v198, v172
	v_mul_f32_e32 v199, v199, v122
	v_fma_f32 v198, v123, v198, v173
	v_mul_f32_e32 v199, v199, v123
	v_fma_f32 v198, v124, v198, v174
	v_mul_f32_e32 v199, v199, v124
	v_fma_f32 v198, v125, v198, v175
	v_mul_f32_e32 v199, v199, v125
	v_fma_f32 v198, v126, v198, v176
	v_mul_f32_e32 v199, v199, v126
	v_fma_f32 v198, v127, v198, v177
	v_mul_f32_e32 v199, v199, v127
	v_mov_b32_e32 v164, v199
	v_mov_b32_e32 v166, v199
	v_mov_b32_e32 v246, v198
	v_mov_b32_e32 v248, v198
	s_nop 1
	v_permlane32_swap_b32 v164, v166
	v_permlane32_swap_b32 v246, v248
	s_nop 1
	v_mov_b32_e32 v165, v164
	v_mov_b32_e32 v167, v166
	v_mov_b32_e32 v247, v246
	v_mov_b32_e32 v249, v248
	s_nop 1
	v_permlane16_swap_b32 v164, v165
	v_permlane16_swap_b32 v166, v167
	v_permlane16_swap_b32 v246, v247
	v_permlane16_swap_b32 v248, v249
	s_nop 1
	v_mov_b32_e32 v251, v246
	v_mov_b32_e32 v250, v164
	v_fma_f32 v251, v251, v165, v247
	v_mul_f32_e32 v250, v250, v165
	v_fma_f32 v251, v251, v166, v248
	v_mul_f32_e32 v250, v250, v166
	v_fma_f32 v251, v251, v167, v249
	v_mul_f32_e32 v250, v250, v167
	s_mov_b64 exec, s[10:11]
	ds_write_b64 v182, v[250:251] offset:0
	s_mov_b64 exec, -1
	s_waitcnt lgkmcnt(0)
	s_barrier
	ds_read2_b64 v[4:7], v183 offset0:0 offset1:16
	s_add_i32 s52, s4, 0
	s_lshl_b32 s52, s52, 12
	v_add_u32_e32 v197, s52, v184
	s_waitcnt lgkmcnt(0)
	v_fma_f32 v198, v180, v4, v5
	v_cndmask_b32_e64 v199, v180, v198, s[24:25]
	v_fma_f32 v180, v198, v6, v7
	v_fma_f32 v200, v199, v164, v246
	v_cndmask_b32_e64 v199, v199, v200, s[16:17]
	v_fma_f32 v200, v199, v165, v247
	v_cndmask_b32_e64 v199, v199, v200, s[20:21]
	v_fma_f32 v200, v199, v166, v248
	v_cndmask_b32_e64 v199, v199, v200, s[22:23]
	v_fma_f32 v214, v120, v199, v170
	v_fma_f32 v215, v121, v214, v171
	v_fma_f32 v216, v122, v215, v172
	v_fma_f32 v217, v123, v216, v173
	v_fma_f32 v218, v124, v217, v174
	v_fma_f32 v219, v125, v218, v175
	v_fma_f32 v220, v126, v219, v176
	v_fma_f32 v221, v127, v220, v177
	ds_read_u16 v206, v197 offset:0
	ds_read_u16 v207, v197 offset:64
	ds_read_u16 v208, v197 offset:128
	ds_read_u16 v209, v197 offset:192
	ds_read_u16 v210, v197 offset:256
	ds_read_u16 v211, v197 offset:320
	ds_read_u16 v212, v197 offset:384
	ds_read_u16 v213, v197 offset:448
	s_waitcnt lgkmcnt(0)
	v_lshlrev_b32_e32 v206, 16, v206
	v_lshlrev_b32_e32 v207, 16, v207
	v_lshlrev_b32_e32 v208, 16, v208
	v_lshlrev_b32_e32 v209, 16, v209
	v_lshlrev_b32_e32 v210, 16, v210
	v_lshlrev_b32_e32 v211, 16, v211
	v_lshlrev_b32_e32 v212, 16, v212
	v_lshlrev_b32_e32 v213, 16, v213
	v_add_f32_e32 v214, v214, v206
	v_add_f32_e32 v215, v215, v207
	v_add_f32_e32 v216, v216, v208
	v_add_f32_e32 v217, v217, v209
	v_add_f32_e32 v218, v218, v210
	v_add_f32_e32 v219, v219, v211
	v_add_f32_e32 v220, v220, v212
	v_add_f32_e32 v221, v221, v213
	v_cvt_pk_bf16_f32 v206, v214, v215
	v_cvt_pk_bf16_f32 v208, v216, v217
	v_cvt_pk_bf16_f32 v210, v218, v219
	v_cvt_pk_bf16_f32 v212, v220, v221
	ds_write_b16 v197, v206 offset:0
	ds_write_b16_d16_hi v197, v206 offset:64
	ds_write_b16 v197, v208 offset:128
	ds_write_b16_d16_hi v197, v208 offset:192
	ds_write_b16 v197, v210 offset:256
	ds_write_b16_d16_hi v197, v210 offset:320
	ds_write_b16 v197, v212 offset:384
	ds_write_b16_d16_hi v197, v212 offset:448
	ds_read_b128 v[198:201], v130 offset:0
	ds_read_b128 v[214:217], v130 offset:576
	ds_read_b128 v[202:205], v131 offset:0
	ds_read_b128 v[218:221], v131 offset:576
	ds_read_b128 v[206:209], v130 offset:144
	ds_read_b128 v[222:225], v130 offset:720
	ds_read_b128 v[210:213], v131 offset:144
	s_waitcnt lgkmcnt(14)
	ds_read_b128 v[226:229], v131 offset:720
	s_waitcnt lgkmcnt(6)
	v_mfma_f32_16x16x32_bf16 v[100:103], v[198:201], v[20:23], v[12:15]
	v_mfma_f32_16x16x32_bf16 v[104:107], v[198:201], v[52:55], v[16:19]
	v_mfma_f32_16x16x32_bf16 v[108:111], v[198:201], v[84:87], v[242:245]
	v_mfma_f32_16x16x32_bf16 v[112:115], v[214:217], v[20:23], v[12:15]
	v_mfma_f32_16x16x32_bf16 v[138:141], v[214:217], v[52:55], v[16:19]
	v_mfma_f32_16x16x32_bf16 v[142:145], v[214:217], v[84:87], v[242:245]
	s_waitcnt lgkmcnt(4)
	v_mfma_f32_16x16x32_bf16 v[100:103], v[202:205], v[24:27], v[100:103]
	v_mfma_f32_16x16x32_bf16 v[104:107], v[202:205], v[56:59], v[104:107]
	v_mfma_f32_16x16x32_bf16 v[112:115], v[218:221], v[24:27], v[112:115]
	v_mfma_f32_16x16x32_bf16 v[138:141], v[218:221], v[56:59], v[138:141]
	ds_read_b128 v[198:201], v130 offset:288
	ds_read_b128 v[214:217], v130 offset:864
	ds_read_b128 v[202:205], v131 offset:288
	ds_read_b128 v[218:221], v131 offset:864
	s_waitcnt lgkmcnt(6)
	v_mfma_f32_16x16x32_bf16 v[100:103], v[206:209], v[28:31], v[100:103]
	v_mfma_f32_16x16x32_bf16 v[104:107], v[206:209], v[60:63], v[104:107]
	v_mfma_f32_16x16x32_bf16 v[108:111], v[206:209], v[88:91], v[108:111]
	v_mfma_f32_16x16x32_bf16 v[112:115], v[222:225], v[28:31], v[112:115]
	v_mfma_f32_16x16x32_bf16 v[138:141], v[222:225], v[60:63], v[138:141]
	v_mfma_f32_16x16x32_bf16 v[142:145], v[222:225], v[88:91], v[142:145]
	s_waitcnt lgkmcnt(4)
	v_mfma_f32_16x16x32_bf16 v[100:103], v[210:213], v[32:35], v[100:103]
	v_mfma_f32_16x16x32_bf16 v[104:107], v[210:213], v[64:67], v[104:107]
	v_mfma_f32_16x16x32_bf16 v[112:115], v[226:229], v[32:35], v[112:115]
	v_mfma_f32_16x16x32_bf16 v[138:141], v[226:229], v[64:67], v[138:141]
	ds_read_b128 v[206:209], v130 offset:432
	ds_read_b128 v[222:225], v130 offset:1008
	ds_read_b128 v[210:213], v131 offset:432
	ds_read_b128 v[226:229], v131 offset:1008
	s_waitcnt lgkmcnt(6)
	v_mfma_f32_16x16x32_bf16 v[100:103], v[198:201], v[36:39], v[100:103]
	v_mfma_f32_16x16x32_bf16 v[104:107], v[198:201], v[68:71], v[104:107]
	v_mfma_f32_16x16x32_bf16 v[108:111], v[198:201], v[92:95], v[108:111]
	v_mfma_f32_16x16x32_bf16 v[112:115], v[214:217], v[36:39], v[112:115]
	v_mfma_f32_16x16x32_bf16 v[138:141], v[214:217], v[68:71], v[138:141]
	v_mfma_f32_16x16x32_bf16 v[142:145], v[214:217], v[92:95], v[142:145]
	s_waitcnt lgkmcnt(4)
	v_mfma_f32_16x16x32_bf16 v[100:103], v[202:205], v[40:43], v[100:103]
	v_mfma_f32_16x16x32_bf16 v[104:107], v[202:205], v[72:75], v[104:107]
	v_mfma_f32_16x16x32_bf16 v[112:115], v[218:221], v[40:43], v[112:115]
	v_mfma_f32_16x16x32_bf16 v[138:141], v[218:221], v[72:75], v[138:141]
	s_waitcnt lgkmcnt(2)
	v_mfma_f32_16x16x32_bf16 v[100:103], v[206:209], v[44:47], v[100:103]
	v_mfma_f32_16x16x32_bf16 v[104:107], v[206:209], v[76:79], v[104:107]
	v_mfma_f32_16x16x32_bf16 v[108:111], v[206:209], v[96:99], v[108:111]
	v_mfma_f32_16x16x32_bf16 v[112:115], v[222:225], v[44:47], v[112:115]
	v_mfma_f32_16x16x32_bf16 v[138:141], v[222:225], v[76:79], v[138:141]
	v_mfma_f32_16x16x32_bf16 v[142:145], v[222:225], v[96:99], v[142:145]
	s_waitcnt lgkmcnt(0)
	v_mfma_f32_16x16x32_bf16 v[100:103], v[210:213], v[48:51], v[100:103]
	v_mfma_f32_16x16x32_bf16 v[104:107], v[210:213], v[80:83], v[104:107]
	v_mfma_f32_16x16x32_bf16 v[112:115], v[226:229], v[48:51], v[112:115]
	v_mfma_f32_16x16x32_bf16 v[138:141], v[226:229], v[80:83], v[138:141]
	s_waitcnt lgkmcnt(0)
	s_barrier
	s_waitcnt vmcnt(5)
	ds_write_b128 v134, v[230:233]
	ds_write_b128 v134, v[234:237] offset:4608
	ds_write_b128 v135, v[238:241]
	s_add_i32 s64, s4, 0
	s_mul_i32 s71, s64, 0x30000
	s_add_u32 s38, s60, s71
	s_addc_u32 s39, s61, 0
	s_lshl_b32 s64, s64, 12
	v_add_u32_e32 v136, s64, v195
	ds_read_b128 v[116:119], v136
	s_waitcnt vmcnt(3)
	s_waitcnt lgkmcnt(0)
	v_lshlrev_b32_e32 v136, 16, v116
	v_lshlrev_b32_e32 v137, 16, v8
	v_and_b32_e32 v168, 0xffff0000, v116
	v_and_b32_e32 v169, 0xffff0000, v8
	v_mul_f32_e32 v136, v136, v137
	v_mul_f32_e32 v168, v168, v169
	v_cvt_pk_bf16_f32 v116, v136, v168
	v_lshlrev_b32_e32 v136, 16, v117
	v_lshlrev_b32_e32 v137, 16, v9
	v_and_b32_e32 v168, 0xffff0000, v117
	v_and_b32_e32 v169, 0xffff0000, v9
	v_mul_f32_e32 v136, v136, v137
	v_mul_f32_e32 v168, v168, v169
	v_cvt_pk_bf16_f32 v117, v136, v168
	v_lshlrev_b32_e32 v136, 16, v118
	v_lshlrev_b32_e32 v137, 16, v10
	v_and_b32_e32 v168, 0xffff0000, v118
	v_and_b32_e32 v169, 0xffff0000, v10
	v_mul_f32_e32 v136, v136, v137
	v_mul_f32_e32 v168, v168, v169
	v_cvt_pk_bf16_f32 v118, v136, v168
	v_lshlrev_b32_e32 v136, 16, v119
	v_lshlrev_b32_e32 v137, 16, v11
	v_and_b32_e32 v168, 0xffff0000, v119
	v_and_b32_e32 v169, 0xffff0000, v11
	v_mul_f32_e32 v136, v136, v137
	v_mul_f32_e32 v168, v168, v169
	v_cvt_pk_bf16_f32 v119, v136, v168
	global_store_dwordx4 v255, v[116:119], s[38:39]
	s_add_i32 s64, s4, 1
	s_mul_i32 s71, s64, 0x30000
	s_add_u32 s38, s60, s71
	s_addc_u32 s39, s61, 0
	s_lshl_b32 s64, s64, 12
	global_load_dwordx4 v[8:11], v255, s[38:39]
	s_add_i32 s52, s4, 4
	s_min_u32 s52, s52, 31
	s_lshl_b32 s52, s52, 13
	s_add_u32 s26, s50, s52
	s_addc_u32 s27, s51, 0
	global_load_dwordx4 v[230:233], v154, s[26:27]
	global_load_dwordx4 v[234:237], v155, s[26:27]
	global_load_dwordx4 v[238:241], v159, s[26:27]
	v_exp_f32_e32 v198, v100
	v_exp_f32_e32 v199, v101
	v_exp_f32_e32 v200, v102
	v_exp_f32_e32 v201, v103
	v_exp_f32_e32 v202, v112
	v_exp_f32_e32 v203, v113
	v_exp_f32_e32 v204, v114
	v_exp_f32_e32 v205, v115
	v_exp_f32_e32 v214, v104
	v_add_f32_e32 v198, 1.0, v198
	v_exp_f32_e32 v215, v105
	v_add_f32_e32 v199, 1.0, v199
	v_exp_f32_e32 v216, v106
	v_add_f32_e32 v200, 1.0, v200
	v_exp_f32_e32 v217, v107
	v_add_f32_e32 v201, 1.0, v201
	v_exp_f32_e32 v218, v138
	v_add_f32_e32 v202, 1.0, v202
	v_exp_f32_e32 v219, v139
	v_add_f32_e32 v203, 1.0, v203
	v_exp_f32_e32 v220, v140
	v_add_f32_e32 v204, 1.0, v204
	v_exp_f32_e32 v221, v141
	v_add_f32_e32 v205, 1.0, v205
	v_rcp_f32_e32 v198, v198
	v_add_f32_e32 v214, 1.0, v214
	v_rcp_f32_e32 v199, v199
	v_add_f32_e32 v215, 1.0, v215
	v_rcp_f32_e32 v200, v200
	v_add_f32_e32 v216, 1.0, v216
	v_rcp_f32_e32 v201, v201
	v_add_f32_e32 v217, 1.0, v217
	v_rcp_f32_e32 v202, v202
	v_add_f32_e32 v218, 1.0, v218
	v_rcp_f32_e32 v203, v203
	v_add_f32_e32 v219, 1.0, v219
	v_rcp_f32_e32 v204, v204
	v_add_f32_e32 v220, 1.0, v220
	v_rcp_f32_e32 v205, v205
	v_add_f32_e32 v221, 1.0, v221
	v_mul_f32_e32 v198, v179, v198
	v_mul_f32_e32 v199, v179, v199
	v_mul_f32_e32 v200, v179, v200
	v_mul_f32_e32 v201, v179, v201
	v_mul_f32_e32 v202, v179, v202
	v_mul_f32_e32 v203, v179, v203
	v_mul_f32_e32 v204, v179, v204
	v_mul_f32_e32 v205, v179, v205
	v_exp_f32_e32 v120, v198
	v_exp_f32_e32 v121, v199
	v_exp_f32_e32 v122, v200
	v_exp_f32_e32 v123, v201
	v_exp_f32_e32 v124, v202
	v_exp_f32_e32 v125, v203
	v_exp_f32_e32 v126, v204
	v_exp_f32_e32 v127, v205
	v_fma_f32 v206, -v120, v120, 1.0
	v_fma_f32 v207, -v121, v121, 1.0
	v_fma_f32 v208, -v122, v122, 1.0
	v_fma_f32 v209, -v123, v123, 1.0
	v_fma_f32 v210, -v124, v124, 1.0
	v_fma_f32 v211, -v125, v125, 1.0
	v_fma_f32 v212, -v126, v126, 1.0
	v_fma_f32 v213, -v127, v127, 1.0
	v_max_f32_e32 v206, 0xda24260, v206
	v_max_f32_e32 v207, 0xda24260, v207
	v_max_f32_e32 v208, 0xda24260, v208
	v_max_f32_e32 v209, 0xda24260, v209
	v_max_f32_e32 v210, 0xda24260, v210
	v_max_f32_e32 v211, 0xda24260, v211
	v_max_f32_e32 v212, 0xda24260, v212
	v_max_f32_e32 v213, 0xda24260, v213
	v_mul_f32_e32 v198, v214, v206
	v_mul_f32_e32 v199, v215, v207
	v_mul_f32_e32 v200, v216, v208
	v_mul_f32_e32 v201, v217, v209
	v_mul_f32_e32 v202, v218, v210
	v_mul_f32_e32 v203, v219, v211
	v_mul_f32_e32 v204, v220, v212
	v_mul_f32_e32 v205, v221, v213
	v_mul_f32_e32 v214, v214, v198
	v_mul_f32_e32 v215, v215, v199
	v_mul_f32_e32 v216, v216, v200
	v_mul_f32_e32 v217, v217, v201
	v_mul_f32_e32 v218, v218, v202
	v_mul_f32_e32 v219, v219, v203
	v_mul_f32_e32 v220, v220, v204
	v_mul_f32_e32 v221, v221, v205
	v_rsq_f32_e32 v214, v214
	v_mul_f32_e32 v222, v108, v206
	v_rsq_f32_e32 v215, v215
	v_mul_f32_e32 v223, v109, v207
	v_rsq_f32_e32 v216, v216
	v_mul_f32_e32 v224, v110, v208
	v_rsq_f32_e32 v217, v217
	v_mul_f32_e32 v225, v111, v209
	v_rsq_f32_e32 v218, v218
	v_mul_f32_e32 v226, v142, v210
	v_rsq_f32_e32 v219, v219
	v_mul_f32_e32 v227, v143, v211
	v_rsq_f32_e32 v220, v220
	v_mul_f32_e32 v228, v144, v212
	v_rsq_f32_e32 v221, v221
	v_mul_f32_e32 v229, v145, v213
	v_mul_f32_e32 v170, v222, v214
	v_mul_f32_e32 v171, v223, v215
	v_mul_f32_e32 v172, v224, v216
	v_mul_f32_e32 v173, v225, v217
	v_mul_f32_e32 v174, v226, v218
	v_mul_f32_e32 v175, v227, v219
	v_mul_f32_e32 v176, v228, v220
	v_mul_f32_e32 v177, v229, v221
	v_mov_b32_e32 v198, v170
	v_mov_b32_e32 v199, v120
	v_fma_f32 v198, v121, v198, v171
	v_mul_f32_e32 v199, v199, v121
	v_fma_f32 v198, v122, v198, v172
	v_mul_f32_e32 v199, v199, v122
	v_fma_f32 v198, v123, v198, v173
	v_mul_f32_e32 v199, v199, v123
	v_fma_f32 v198, v124, v198, v174
	v_mul_f32_e32 v199, v199, v124
	v_fma_f32 v198, v125, v198, v175
	v_mul_f32_e32 v199, v199, v125
	v_fma_f32 v198, v126, v198, v176
	v_mul_f32_e32 v199, v199, v126
	v_fma_f32 v198, v127, v198, v177
	v_mul_f32_e32 v199, v199, v127
	v_mov_b32_e32 v164, v199
	v_mov_b32_e32 v166, v199
	v_mov_b32_e32 v246, v198
	v_mov_b32_e32 v248, v198
	s_nop 1
	v_permlane32_swap_b32 v164, v166
	v_permlane32_swap_b32 v246, v248
	s_nop 1
	v_mov_b32_e32 v165, v164
	v_mov_b32_e32 v167, v166
	v_mov_b32_e32 v247, v246
	v_mov_b32_e32 v249, v248
	s_nop 1
	v_permlane16_swap_b32 v164, v165
	v_permlane16_swap_b32 v166, v167
	v_permlane16_swap_b32 v246, v247
	v_permlane16_swap_b32 v248, v249
	s_nop 1
	v_mov_b32_e32 v251, v246
	v_mov_b32_e32 v250, v164
	v_fma_f32 v251, v251, v165, v247
	v_mul_f32_e32 v250, v250, v165
	v_fma_f32 v251, v251, v166, v248
	v_mul_f32_e32 v250, v250, v166
	v_fma_f32 v251, v251, v167, v249
	v_mul_f32_e32 v250, v250, v167
	s_mov_b64 exec, s[10:11]
	ds_write_b64 v182, v[250:251] offset:1024
	s_mov_b64 exec, -1
	s_waitcnt lgkmcnt(0)
	s_barrier
	ds_read2_b64 v[4:7], v183 offset0:128 offset1:144
	s_add_i32 s52, s4, 1
	s_lshl_b32 s52, s52, 12
	v_add_u32_e32 v197, s52, v184
	s_waitcnt lgkmcnt(0)
	v_fma_f32 v198, v180, v4, v5
	v_cndmask_b32_e64 v199, v180, v198, s[24:25]
	v_fma_f32 v180, v198, v6, v7
	v_fma_f32 v200, v199, v164, v246
	v_cndmask_b32_e64 v199, v199, v200, s[16:17]
	v_fma_f32 v200, v199, v165, v247
	v_cndmask_b32_e64 v199, v199, v200, s[20:21]
	v_fma_f32 v200, v199, v166, v248
	v_cndmask_b32_e64 v199, v199, v200, s[22:23]
	v_fma_f32 v214, v120, v199, v170
	v_fma_f32 v215, v121, v214, v171
	v_fma_f32 v216, v122, v215, v172
	v_fma_f32 v217, v123, v216, v173
	v_fma_f32 v218, v124, v217, v174
	v_fma_f32 v219, v125, v218, v175
	v_fma_f32 v220, v126, v219, v176
	v_fma_f32 v221, v127, v220, v177
	ds_read_u16 v206, v197 offset:0
	ds_read_u16 v207, v197 offset:64
	ds_read_u16 v208, v197 offset:128
	ds_read_u16 v209, v197 offset:192
	ds_read_u16 v210, v197 offset:256
	ds_read_u16 v211, v197 offset:320
	ds_read_u16 v212, v197 offset:384
	ds_read_u16 v213, v197 offset:448
	s_waitcnt lgkmcnt(0)
	v_lshlrev_b32_e32 v206, 16, v206
	v_lshlrev_b32_e32 v207, 16, v207
	v_lshlrev_b32_e32 v208, 16, v208
	v_lshlrev_b32_e32 v209, 16, v209
	v_lshlrev_b32_e32 v210, 16, v210
	v_lshlrev_b32_e32 v211, 16, v211
	v_lshlrev_b32_e32 v212, 16, v212
	v_lshlrev_b32_e32 v213, 16, v213
	v_add_f32_e32 v214, v214, v206
	v_add_f32_e32 v215, v215, v207
	v_add_f32_e32 v216, v216, v208
	v_add_f32_e32 v217, v217, v209
	v_add_f32_e32 v218, v218, v210
	v_add_f32_e32 v219, v219, v211
	v_add_f32_e32 v220, v220, v212
	v_add_f32_e32 v221, v221, v213
	v_cvt_pk_bf16_f32 v206, v214, v215
	v_cvt_pk_bf16_f32 v208, v216, v217
	v_cvt_pk_bf16_f32 v210, v218, v219
	v_cvt_pk_bf16_f32 v212, v220, v221
	ds_write_b16 v197, v206 offset:0
	ds_write_b16_d16_hi v197, v206 offset:64
	ds_write_b16 v197, v208 offset:128
	ds_write_b16_d16_hi v197, v208 offset:192
	ds_write_b16 v197, v210 offset:256
	ds_write_b16_d16_hi v197, v210 offset:320
	ds_write_b16 v197, v212 offset:384
	ds_write_b16_d16_hi v197, v212 offset:448
	s_add_i32 s4, s4, 2
	s_cmp_lt_u32 s4, 32
	s_cbranch_scc1 .Lrec2_loopB_d0
	s_waitcnt lgkmcnt(0)
	s_barrier
	s_add_i32 s64, s4, -1
	s_mul_i32 s71, s64, 0x30000
	s_add_u32 s38, s60, s71
	s_addc_u32 s39, s61, 0
	s_lshl_b32 s64, s64, 12
	v_add_u32_e32 v136, s64, v195
	ds_read_b128 v[116:119], v136
	s_waitcnt vmcnt(3)
	s_waitcnt lgkmcnt(0)
	v_lshlrev_b32_e32 v136, 16, v116
	v_lshlrev_b32_e32 v137, 16, v8
	v_and_b32_e32 v168, 0xffff0000, v116
	v_and_b32_e32 v169, 0xffff0000, v8
	v_mul_f32_e32 v136, v136, v137
	v_mul_f32_e32 v168, v168, v169
	v_cvt_pk_bf16_f32 v116, v136, v168
	v_lshlrev_b32_e32 v136, 16, v117
	v_lshlrev_b32_e32 v137, 16, v9
	v_and_b32_e32 v168, 0xffff0000, v117
	v_and_b32_e32 v169, 0xffff0000, v9
	v_mul_f32_e32 v136, v136, v137
	v_mul_f32_e32 v168, v168, v169
	v_cvt_pk_bf16_f32 v117, v136, v168
	v_lshlrev_b32_e32 v136, 16, v118
	v_lshlrev_b32_e32 v137, 16, v10
	v_and_b32_e32 v168, 0xffff0000, v118
	v_and_b32_e32 v169, 0xffff0000, v10
	v_mul_f32_e32 v136, v136, v137
	v_mul_f32_e32 v168, v168, v169
	v_cvt_pk_bf16_f32 v118, v136, v168
	v_lshlrev_b32_e32 v136, 16, v119
	v_lshlrev_b32_e32 v137, 16, v11
	v_and_b32_e32 v168, 0xffff0000, v119
	v_and_b32_e32 v169, 0xffff0000, v11
	v_mul_f32_e32 v136, v136, v137
	v_mul_f32_e32 v168, v168, v169
	v_cvt_pk_bf16_f32 v119, v136, v168
	global_store_dwordx4 v255, v[116:119], s[38:39]
	s_barrier
	s_branch .Lrec2_done

.Lrec2_loopA_d1:
	ds_read_b128 v[198:201], v130 offset:0
	ds_read_b128 v[214:217], v130 offset:576
	ds_read_b128 v[202:205], v131 offset:0
	ds_read_b128 v[218:221], v131 offset:576
	ds_read_b128 v[206:209], v130 offset:144
	ds_read_b128 v[222:225], v130 offset:720
	ds_read_b128 v[210:213], v131 offset:144
	s_waitcnt lgkmcnt(14)
	ds_read_b128 v[226:229], v131 offset:720
	s_waitcnt lgkmcnt(6)
	v_mfma_f32_16x16x32_bf16 v[100:103], v[198:201], v[20:23], v[12:15]
	v_mfma_f32_16x16x32_bf16 v[104:107], v[198:201], v[52:55], v[16:19]
	v_mfma_f32_16x16x32_bf16 v[108:111], v[198:201], v[84:87], v[242:245]
	v_mfma_f32_16x16x32_bf16 v[112:115], v[214:217], v[20:23], v[12:15]
	v_mfma_f32_16x16x32_bf16 v[138:141], v[214:217], v[52:55], v[16:19]
	v_mfma_f32_16x16x32_bf16 v[142:145], v[214:217], v[84:87], v[242:245]
	s_waitcnt lgkmcnt(4)
	v_mfma_f32_16x16x32_bf16 v[100:103], v[202:205], v[24:27], v[100:103]
	v_mfma_f32_16x16x32_bf16 v[104:107], v[202:205], v[56:59], v[104:107]
	v_mfma_f32_16x16x32_bf16 v[112:115], v[218:221], v[24:27], v[112:115]
	v_mfma_f32_16x16x32_bf16 v[138:141], v[218:221], v[56:59], v[138:141]
	ds_read_b128 v[198:201], v130 offset:288
	ds_read_b128 v[214:217], v130 offset:864
	ds_read_b128 v[202:205], v131 offset:288
	ds_read_b128 v[218:221], v131 offset:864
	s_waitcnt lgkmcnt(6)
	v_mfma_f32_16x16x32_bf16 v[100:103], v[206:209], v[28:31], v[100:103]
	v_mfma_f32_16x16x32_bf16 v[104:107], v[206:209], v[60:63], v[104:107]
	v_mfma_f32_16x16x32_bf16 v[108:111], v[206:209], v[88:91], v[108:111]
	v_mfma_f32_16x16x32_bf16 v[112:115], v[222:225], v[28:31], v[112:115]
	v_mfma_f32_16x16x32_bf16 v[138:141], v[222:225], v[60:63], v[138:141]
	v_mfma_f32_16x16x32_bf16 v[142:145], v[222:225], v[88:91], v[142:145]
	s_waitcnt lgkmcnt(4)
	v_mfma_f32_16x16x32_bf16 v[100:103], v[210:213], v[32:35], v[100:103]
	v_mfma_f32_16x16x32_bf16 v[104:107], v[210:213], v[64:67], v[104:107]
	v_mfma_f32_16x16x32_bf16 v[112:115], v[226:229], v[32:35], v[112:115]
	v_mfma_f32_16x16x32_bf16 v[138:141], v[226:229], v[64:67], v[138:141]
	ds_read_b128 v[206:209], v130 offset:432
	ds_read_b128 v[222:225], v130 offset:1008
	ds_read_b128 v[210:213], v131 offset:432
	ds_read_b128 v[226:229], v131 offset:1008
	s_waitcnt lgkmcnt(6)
	v_mfma_f32_16x16x32_bf16 v[100:103], v[198:201], v[36:39], v[100:103]
	v_mfma_f32_16x16x32_bf16 v[104:107], v[198:201], v[68:71], v[104:107]
	v_mfma_f32_16x16x32_bf16 v[108:111], v[198:201], v[92:95], v[108:111]
	v_mfma_f32_16x16x32_bf16 v[112:115], v[214:217], v[36:39], v[112:115]
	v_mfma_f32_16x16x32_bf16 v[138:141], v[214:217], v[68:71], v[138:141]
	v_mfma_f32_16x16x32_bf16 v[142:145], v[214:217], v[92:95], v[142:145]
	s_waitcnt lgkmcnt(4)
	v_mfma_f32_16x16x32_bf16 v[100:103], v[202:205], v[40:43], v[100:103]
	v_mfma_f32_16x16x32_bf16 v[104:107], v[202:205], v[72:75], v[104:107]
	v_mfma_f32_16x16x32_bf16 v[112:115], v[218:221], v[40:43], v[112:115]
	v_mfma_f32_16x16x32_bf16 v[138:141], v[218:221], v[72:75], v[138:141]
	s_waitcnt lgkmcnt(2)
	v_mfma_f32_16x16x32_bf16 v[100:103], v[206:209], v[44:47], v[100:103]
	v_mfma_f32_16x16x32_bf16 v[104:107], v[206:209], v[76:79], v[104:107]
	v_mfma_f32_16x16x32_bf16 v[108:111], v[206:209], v[96:99], v[108:111]
	v_mfma_f32_16x16x32_bf16 v[112:115], v[222:225], v[44:47], v[112:115]
	v_mfma_f32_16x16x32_bf16 v[138:141], v[222:225], v[76:79], v[138:141]
	v_mfma_f32_16x16x32_bf16 v[142:145], v[222:225], v[96:99], v[142:145]
	s_waitcnt lgkmcnt(0)
	v_mfma_f32_16x16x32_bf16 v[100:103], v[210:213], v[48:51], v[100:103]
	v_mfma_f32_16x16x32_bf16 v[104:107], v[210:213], v[80:83], v[104:107]
	v_mfma_f32_16x16x32_bf16 v[112:115], v[226:229], v[48:51], v[112:115]
	v_mfma_f32_16x16x32_bf16 v[138:141], v[226:229], v[80:83], v[138:141]
	s_waitcnt lgkmcnt(0)
	s_barrier
	s_waitcnt vmcnt(3)
	ds_write_b128 v134, v[146:149]
	ds_write_b128 v134, v[150:153] offset:4608
	ds_write_b128 v135, v[160:163]
	s_add_i32 s52, s4, 3
	s_min_u32 s52, s52, 31
	s_sub_i32 s52, 31, s52
	s_lshl_b32 s52, s52, 13
	s_add_u32 s26, s50, s52
	s_addc_u32 s27, s51, 0
	global_load_dwordx4 v[146:149], v154, s[26:27]
	global_load_dwordx4 v[150:153], v155, s[26:27]
	global_load_dwordx4 v[160:163], v159, s[26:27]
	v_exp_f32_e32 v198, v100
	v_exp_f32_e32 v199, v101
	v_exp_f32_e32 v200, v102
	v_exp_f32_e32 v201, v103
	v_exp_f32_e32 v202, v112
	v_exp_f32_e32 v203, v113
	v_exp_f32_e32 v204, v114
	v_exp_f32_e32 v205, v115
	v_exp_f32_e32 v214, v104
	v_add_f32_e32 v198, 1.0, v198
	v_exp_f32_e32 v215, v105
	v_add_f32_e32 v199, 1.0, v199
	v_exp_f32_e32 v216, v106
	v_add_f32_e32 v200, 1.0, v200
	v_exp_f32_e32 v217, v107
	v_add_f32_e32 v201, 1.0, v201
	v_exp_f32_e32 v218, v138
	v_add_f32_e32 v202, 1.0, v202
	v_exp_f32_e32 v219, v139
	v_add_f32_e32 v203, 1.0, v203
	v_exp_f32_e32 v220, v140
	v_add_f32_e32 v204, 1.0, v204
	v_exp_f32_e32 v221, v141
	v_add_f32_e32 v205, 1.0, v205
	v_rcp_f32_e32 v198, v198
	v_add_f32_e32 v214, 1.0, v214
	v_rcp_f32_e32 v199, v199
	v_add_f32_e32 v215, 1.0, v215
	v_rcp_f32_e32 v200, v200
	v_add_f32_e32 v216, 1.0, v216
	v_rcp_f32_e32 v201, v201
	v_add_f32_e32 v217, 1.0, v217
	v_rcp_f32_e32 v202, v202
	v_add_f32_e32 v218, 1.0, v218
	v_rcp_f32_e32 v203, v203
	v_add_f32_e32 v219, 1.0, v219
	v_rcp_f32_e32 v204, v204
	v_add_f32_e32 v220, 1.0, v220
	v_rcp_f32_e32 v205, v205
	v_add_f32_e32 v221, 1.0, v221
	v_mul_f32_e32 v198, v179, v198
	v_mul_f32_e32 v199, v179, v199
	v_mul_f32_e32 v200, v179, v200
	v_mul_f32_e32 v201, v179, v201
	v_mul_f32_e32 v202, v179, v202
	v_mul_f32_e32 v203, v179, v203
	v_mul_f32_e32 v204, v179, v204
	v_mul_f32_e32 v205, v179, v205
	v_exp_f32_e32 v120, v198
	v_exp_f32_e32 v121, v199
	v_exp_f32_e32 v122, v200
	v_exp_f32_e32 v123, v201
	v_exp_f32_e32 v124, v202
	v_exp_f32_e32 v125, v203
	v_exp_f32_e32 v126, v204
	v_exp_f32_e32 v127, v205
	v_fma_f32 v206, -v120, v120, 1.0
	v_fma_f32 v207, -v121, v121, 1.0
	v_fma_f32 v208, -v122, v122, 1.0
	v_fma_f32 v209, -v123, v123, 1.0
	v_fma_f32 v210, -v124, v124, 1.0
	v_fma_f32 v211, -v125, v125, 1.0
	v_fma_f32 v212, -v126, v126, 1.0
	v_fma_f32 v213, -v127, v127, 1.0
	v_max_f32_e32 v206, 0xda24260, v206
	v_max_f32_e32 v207, 0xda24260, v207
	v_max_f32_e32 v208, 0xda24260, v208
	v_max_f32_e32 v209, 0xda24260, v209
	v_max_f32_e32 v210, 0xda24260, v210
	v_max_f32_e32 v211, 0xda24260, v211
	v_max_f32_e32 v212, 0xda24260, v212
	v_max_f32_e32 v213, 0xda24260, v213
	v_mul_f32_e32 v198, v214, v206
	v_mul_f32_e32 v199, v215, v207
	v_mul_f32_e32 v200, v216, v208
	v_mul_f32_e32 v201, v217, v209
	v_mul_f32_e32 v202, v218, v210
	v_mul_f32_e32 v203, v219, v211
	v_mul_f32_e32 v204, v220, v212
	v_mul_f32_e32 v205, v221, v213
	v_mul_f32_e32 v214, v214, v198
	v_mul_f32_e32 v215, v215, v199
	v_mul_f32_e32 v216, v216, v200
	v_mul_f32_e32 v217, v217, v201
	v_mul_f32_e32 v218, v218, v202
	v_mul_f32_e32 v219, v219, v203
	v_mul_f32_e32 v220, v220, v204
	v_mul_f32_e32 v221, v221, v205
	v_rsq_f32_e32 v214, v214
	v_mul_f32_e32 v222, v108, v206
	v_rsq_f32_e32 v215, v215
	v_mul_f32_e32 v223, v109, v207
	v_rsq_f32_e32 v216, v216
	v_mul_f32_e32 v224, v110, v208
	v_rsq_f32_e32 v217, v217
	v_mul_f32_e32 v225, v111, v209
	v_rsq_f32_e32 v218, v218
	v_mul_f32_e32 v226, v142, v210
	v_rsq_f32_e32 v219, v219
	v_mul_f32_e32 v227, v143, v211
	v_rsq_f32_e32 v220, v220
	v_mul_f32_e32 v228, v144, v212
	v_rsq_f32_e32 v221, v221
	v_mul_f32_e32 v229, v145, v213
	v_mul_f32_e32 v170, v222, v214
	v_mul_f32_e32 v171, v223, v215
	v_mul_f32_e32 v172, v224, v216
	v_mul_f32_e32 v173, v225, v217
	v_mul_f32_e32 v174, v226, v218
	v_mul_f32_e32 v175, v227, v219
	v_mul_f32_e32 v176, v228, v220
	v_mul_f32_e32 v177, v229, v221
	v_mov_b32_e32 v198, v177
	v_mov_b32_e32 v199, v127
	v_fma_f32 v198, v126, v198, v176
	v_mul_f32_e32 v199, v199, v126
	v_fma_f32 v198, v125, v198, v175
	v_mul_f32_e32 v199, v199, v125
	v_fma_f32 v198, v124, v198, v174
	v_mul_f32_e32 v199, v199, v124
	v_fma_f32 v198, v123, v198, v173
	v_mul_f32_e32 v199, v199, v123
	v_fma_f32 v198, v122, v198, v172
	v_mul_f32_e32 v199, v199, v122
	v_fma_f32 v198, v121, v198, v171
	v_mul_f32_e32 v199, v199, v121
	v_fma_f32 v198, v120, v198, v170
	v_mul_f32_e32 v199, v199, v120
	v_mov_b32_e32 v164, v199
	v_mov_b32_e32 v166, v199
	v_mov_b32_e32 v246, v198
	v_mov_b32_e32 v248, v198
	s_nop 1
	v_permlane32_swap_b32 v164, v166
	v_permlane32_swap_b32 v246, v248
	s_nop 1
	v_mov_b32_e32 v165, v164
	v_mov_b32_e32 v167, v166
	v_mov_b32_e32 v247, v246
	v_mov_b32_e32 v249, v248
	s_nop 1
	v_permlane16_swap_b32 v164, v165
	v_permlane16_swap_b32 v166, v167
	v_permlane16_swap_b32 v246, v247
	v_permlane16_swap_b32 v248, v249
	s_nop 1
	v_mov_b32_e32 v251, v249
	v_mov_b32_e32 v250, v167
	v_fma_f32 v251, v251, v166, v248
	v_mul_f32_e32 v250, v250, v166
	v_fma_f32 v251, v251, v165, v247
	v_mul_f32_e32 v250, v250, v165
	v_fma_f32 v251, v251, v164, v246
	v_mul_f32_e32 v250, v250, v164
	s_mov_b64 exec, s[10:11]
	ds_write_b64 v182, v[250:251] offset:0
	s_mov_b64 exec, -1
	s_waitcnt lgkmcnt(0)
	s_barrier
	ds_read2_b64 v[4:7], v183 offset0:0 offset1:16
	s_add_i32 s52, s4, 0
	s_sub_i32 s52, 31, s52
	s_lshl_b32 s52, s52, 12
	v_add_u32_e32 v197, s52, v184
	s_waitcnt lgkmcnt(0)
	v_fma_f32 v198, v180, v6, v7
	v_cndmask_b32_e64 v199, v180, v198, s[24:25]
	v_fma_f32 v180, v198, v4, v5
	v_fma_f32 v200, v199, v167, v249
	v_cndmask_b32_e64 v199, v199, v200, s[16:17]
	v_fma_f32 v200, v199, v166, v248
	v_cndmask_b32_e64 v199, v199, v200, s[20:21]
	v_fma_f32 v200, v199, v165, v247
	v_cndmask_b32_e64 v199, v199, v200, s[22:23]
	v_fma_f32 v221, v127, v199, v177
	v_fma_f32 v220, v126, v221, v176
	v_fma_f32 v219, v125, v220, v175
	v_fma_f32 v218, v124, v219, v174
	v_fma_f32 v217, v123, v218, v173
	v_fma_f32 v216, v122, v217, v172
	v_fma_f32 v215, v121, v216, v171
	v_fma_f32 v214, v120, v215, v170
	v_cvt_pk_bf16_f32 v206, v214, v215
	v_cvt_pk_bf16_f32 v208, v216, v217
	v_cvt_pk_bf16_f32 v210, v218, v219
	v_cvt_pk_bf16_f32 v212, v220, v221
	ds_write_b16 v197, v206 offset:0
	ds_write_b16_d16_hi v197, v206 offset:64
	ds_write_b16 v197, v208 offset:128
	ds_write_b16_d16_hi v197, v208 offset:192
	ds_write_b16 v197, v210 offset:256
	ds_write_b16_d16_hi v197, v210 offset:320
	ds_write_b16 v197, v212 offset:384
	ds_write_b16_d16_hi v197, v212 offset:448
	ds_read_b128 v[198:201], v130 offset:0
	ds_read_b128 v[214:217], v130 offset:576
	ds_read_b128 v[202:205], v131 offset:0
	ds_read_b128 v[218:221], v131 offset:576
	ds_read_b128 v[206:209], v130 offset:144
	ds_read_b128 v[222:225], v130 offset:720
	ds_read_b128 v[210:213], v131 offset:144
	s_waitcnt lgkmcnt(14)
	ds_read_b128 v[226:229], v131 offset:720
	s_waitcnt lgkmcnt(6)
	v_mfma_f32_16x16x32_bf16 v[100:103], v[198:201], v[20:23], v[12:15]
	v_mfma_f32_16x16x32_bf16 v[104:107], v[198:201], v[52:55], v[16:19]
	v_mfma_f32_16x16x32_bf16 v[108:111], v[198:201], v[84:87], v[242:245]
	v_mfma_f32_16x16x32_bf16 v[112:115], v[214:217], v[20:23], v[12:15]
	v_mfma_f32_16x16x32_bf16 v[138:141], v[214:217], v[52:55], v[16:19]
	v_mfma_f32_16x16x32_bf16 v[142:145], v[214:217], v[84:87], v[242:245]
	s_waitcnt lgkmcnt(4)
	v_mfma_f32_16x16x32_bf16 v[100:103], v[202:205], v[24:27], v[100:103]
	v_mfma_f32_16x16x32_bf16 v[104:107], v[202:205], v[56:59], v[104:107]
	v_mfma_f32_16x16x32_bf16 v[112:115], v[218:221], v[24:27], v[112:115]
	v_mfma_f32_16x16x32_bf16 v[138:141], v[218:221], v[56:59], v[138:141]
	ds_read_b128 v[198:201], v130 offset:288
	ds_read_b128 v[214:217], v130 offset:864
	ds_read_b128 v[202:205], v131 offset:288
	ds_read_b128 v[218:221], v131 offset:864
	s_waitcnt lgkmcnt(6)
	v_mfma_f32_16x16x32_bf16 v[100:103], v[206:209], v[28:31], v[100:103]
	v_mfma_f32_16x16x32_bf16 v[104:107], v[206:209], v[60:63], v[104:107]
	v_mfma_f32_16x16x32_bf16 v[108:111], v[206:209], v[88:91], v[108:111]
	v_mfma_f32_16x16x32_bf16 v[112:115], v[222:225], v[28:31], v[112:115]
	v_mfma_f32_16x16x32_bf16 v[138:141], v[222:225], v[60:63], v[138:141]
	v_mfma_f32_16x16x32_bf16 v[142:145], v[222:225], v[88:91], v[142:145]
	s_waitcnt lgkmcnt(4)
	v_mfma_f32_16x16x32_bf16 v[100:103], v[210:213], v[32:35], v[100:103]
	v_mfma_f32_16x16x32_bf16 v[104:107], v[210:213], v[64:67], v[104:107]
	v_mfma_f32_16x16x32_bf16 v[112:115], v[226:229], v[32:35], v[112:115]
	v_mfma_f32_16x16x32_bf16 v[138:141], v[226:229], v[64:67], v[138:141]
	ds_read_b128 v[206:209], v130 offset:432
	ds_read_b128 v[222:225], v130 offset:1008
	ds_read_b128 v[210:213], v131 offset:432
	ds_read_b128 v[226:229], v131 offset:1008
	s_waitcnt lgkmcnt(6)
	v_mfma_f32_16x16x32_bf16 v[100:103], v[198:201], v[36:39], v[100:103]
	v_mfma_f32_16x16x32_bf16 v[104:107], v[198:201], v[68:71], v[104:107]
	v_mfma_f32_16x16x32_bf16 v[108:111], v[198:201], v[92:95], v[108:111]
	v_mfma_f32_16x16x32_bf16 v[112:115], v[214:217], v[36:39], v[112:115]
	v_mfma_f32_16x16x32_bf16 v[138:141], v[214:217], v[68:71], v[138:141]
	v_mfma_f32_16x16x32_bf16 v[142:145], v[214:217], v[92:95], v[142:145]
	s_waitcnt lgkmcnt(4)
	v_mfma_f32_16x16x32_bf16 v[100:103], v[202:205], v[40:43], v[100:103]
	v_mfma_f32_16x16x32_bf16 v[104:107], v[202:205], v[72:75], v[104:107]
	v_mfma_f32_16x16x32_bf16 v[112:115], v[218:221], v[40:43], v[112:115]
	v_mfma_f32_16x16x32_bf16 v[138:141], v[218:221], v[72:75], v[138:141]
	s_waitcnt lgkmcnt(2)
	v_mfma_f32_16x16x32_bf16 v[100:103], v[206:209], v[44:47], v[100:103]
	v_mfma_f32_16x16x32_bf16 v[104:107], v[206:209], v[76:79], v[104:107]
	v_mfma_f32_16x16x32_bf16 v[108:111], v[206:209], v[96:99], v[108:111]
	v_mfma_f32_16x16x32_bf16 v[112:115], v[222:225], v[44:47], v[112:115]
	v_mfma_f32_16x16x32_bf16 v[138:141], v[222:225], v[76:79], v[138:141]
	v_mfma_f32_16x16x32_bf16 v[142:145], v[222:225], v[96:99], v[142:145]
	s_waitcnt lgkmcnt(0)
	v_mfma_f32_16x16x32_bf16 v[100:103], v[210:213], v[48:51], v[100:103]
	v_mfma_f32_16x16x32_bf16 v[104:107], v[210:213], v[80:83], v[104:107]
	v_mfma_f32_16x16x32_bf16 v[112:115], v[226:229], v[48:51], v[112:115]
	v_mfma_f32_16x16x32_bf16 v[138:141], v[226:229], v[80:83], v[138:141]
	s_waitcnt lgkmcnt(0)
	s_barrier
	s_waitcnt vmcnt(3)
	ds_write_b128 v134, v[230:233]
	ds_write_b128 v134, v[234:237] offset:4608
	ds_write_b128 v135, v[238:241]
	s_add_i32 s52, s4, 4
	s_min_u32 s52, s52, 31
	s_sub_i32 s52, 31, s52
	s_lshl_b32 s52, s52, 13
	s_add_u32 s26, s50, s52
	s_addc_u32 s27, s51, 0
	global_load_dwordx4 v[230:233], v154, s[26:27]
	global_load_dwordx4 v[234:237], v155, s[26:27]
	global_load_dwordx4 v[238:241], v159, s[26:27]
	v_exp_f32_e32 v198, v100
	v_exp_f32_e32 v199, v101
	v_exp_f32_e32 v200, v102
	v_exp_f32_e32 v201, v103
	v_exp_f32_e32 v202, v112
	v_exp_f32_e32 v203, v113
	v_exp_f32_e32 v204, v114
	v_exp_f32_e32 v205, v115
	v_exp_f32_e32 v214, v104
	v_add_f32_e32 v198, 1.0, v198
	v_exp_f32_e32 v215, v105
	v_add_f32_e32 v199, 1.0, v199
	v_exp_f32_e32 v216, v106
	v_add_f32_e32 v200, 1.0, v200
	v_exp_f32_e32 v217, v107
	v_add_f32_e32 v201, 1.0, v201
	v_exp_f32_e32 v218, v138
	v_add_f32_e32 v202, 1.0, v202
	v_exp_f32_e32 v219, v139
	v_add_f32_e32 v203, 1.0, v203
	v_exp_f32_e32 v220, v140
	v_add_f32_e32 v204, 1.0, v204
	v_exp_f32_e32 v221, v141
	v_add_f32_e32 v205, 1.0, v205
	v_rcp_f32_e32 v198, v198
	v_add_f32_e32 v214, 1.0, v214
	v_rcp_f32_e32 v199, v199
	v_add_f32_e32 v215, 1.0, v215
	v_rcp_f32_e32 v200, v200
	v_add_f32_e32 v216, 1.0, v216
	v_rcp_f32_e32 v201, v201
	v_add_f32_e32 v217, 1.0, v217
	v_rcp_f32_e32 v202, v202
	v_add_f32_e32 v218, 1.0, v218
	v_rcp_f32_e32 v203, v203
	v_add_f32_e32 v219, 1.0, v219
	v_rcp_f32_e32 v204, v204
	v_add_f32_e32 v220, 1.0, v220
	v_rcp_f32_e32 v205, v205
	v_add_f32_e32 v221, 1.0, v221
	v_mul_f32_e32 v198, v179, v198
	v_mul_f32_e32 v199, v179, v199
	v_mul_f32_e32 v200, v179, v200
	v_mul_f32_e32 v201, v179, v201
	v_mul_f32_e32 v202, v179, v202
	v_mul_f32_e32 v203, v179, v203
	v_mul_f32_e32 v204, v179, v204
	v_mul_f32_e32 v205, v179, v205
	v_exp_f32_e32 v120, v198
	v_exp_f32_e32 v121, v199
	v_exp_f32_e32 v122, v200
	v_exp_f32_e32 v123, v201
	v_exp_f32_e32 v124, v202
	v_exp_f32_e32 v125, v203
	v_exp_f32_e32 v126, v204
	v_exp_f32_e32 v127, v205
	v_fma_f32 v206, -v120, v120, 1.0
	v_fma_f32 v207, -v121, v121, 1.0
	v_fma_f32 v208, -v122, v122, 1.0
	v_fma_f32 v209, -v123, v123, 1.0
	v_fma_f32 v210, -v124, v124, 1.0
	v_fma_f32 v211, -v125, v125, 1.0
	v_fma_f32 v212, -v126, v126, 1.0
	v_fma_f32 v213, -v127, v127, 1.0
	v_max_f32_e32 v206, 0xda24260, v206
	v_max_f32_e32 v207, 0xda24260, v207
	v_max_f32_e32 v208, 0xda24260, v208
	v_max_f32_e32 v209, 0xda24260, v209
	v_max_f32_e32 v210, 0xda24260, v210
	v_max_f32_e32 v211, 0xda24260, v211
	v_max_f32_e32 v212, 0xda24260, v212
	v_max_f32_e32 v213, 0xda24260, v213
	v_mul_f32_e32 v198, v214, v206
	v_mul_f32_e32 v199, v215, v207
	v_mul_f32_e32 v200, v216, v208
	v_mul_f32_e32 v201, v217, v209
	v_mul_f32_e32 v202, v218, v210
	v_mul_f32_e32 v203, v219, v211
	v_mul_f32_e32 v204, v220, v212
	v_mul_f32_e32 v205, v221, v213
	v_mul_f32_e32 v214, v214, v198
	v_mul_f32_e32 v215, v215, v199
	v_mul_f32_e32 v216, v216, v200
	v_mul_f32_e32 v217, v217, v201
	v_mul_f32_e32 v218, v218, v202
	v_mul_f32_e32 v219, v219, v203
	v_mul_f32_e32 v220, v220, v204
	v_mul_f32_e32 v221, v221, v205
	v_rsq_f32_e32 v214, v214
	v_mul_f32_e32 v222, v108, v206
	v_rsq_f32_e32 v215, v215
	v_mul_f32_e32 v223, v109, v207
	v_rsq_f32_e32 v216, v216
	v_mul_f32_e32 v224, v110, v208
	v_rsq_f32_e32 v217, v217
	v_mul_f32_e32 v225, v111, v209
	v_rsq_f32_e32 v218, v218
	v_mul_f32_e32 v226, v142, v210
	v_rsq_f32_e32 v219, v219
	v_mul_f32_e32 v227, v143, v211
	v_rsq_f32_e32 v220, v220
	v_mul_f32_e32 v228, v144, v212
	v_rsq_f32_e32 v221, v221
	v_mul_f32_e32 v229, v145, v213
	v_mul_f32_e32 v170, v222, v214
	v_mul_f32_e32 v171, v223, v215
	v_mul_f32_e32 v172, v224, v216
	v_mul_f32_e32 v173, v225, v217
	v_mul_f32_e32 v174, v226, v218
	v_mul_f32_e32 v175, v227, v219
	v_mul_f32_e32 v176, v228, v220
	v_mul_f32_e32 v177, v229, v221
	v_mov_b32_e32 v198, v177
	v_mov_b32_e32 v199, v127
	v_fma_f32 v198, v126, v198, v176
	v_mul_f32_e32 v199, v199, v126
	v_fma_f32 v198, v125, v198, v175
	v_mul_f32_e32 v199, v199, v125
	v_fma_f32 v198, v124, v198, v174
	v_mul_f32_e32 v199, v199, v124
	v_fma_f32 v198, v123, v198, v173
	v_mul_f32_e32 v199, v199, v123
	v_fma_f32 v198, v122, v198, v172
	v_mul_f32_e32 v199, v199, v122
	v_fma_f32 v198, v121, v198, v171
	v_mul_f32_e32 v199, v199, v121
	v_fma_f32 v198, v120, v198, v170
	v_mul_f32_e32 v199, v199, v120
	v_mov_b32_e32 v164, v199
	v_mov_b32_e32 v166, v199
	v_mov_b32_e32 v246, v198
	v_mov_b32_e32 v248, v198
	s_nop 1
	v_permlane32_swap_b32 v164, v166
	v_permlane32_swap_b32 v246, v248
	s_nop 1
	v_mov_b32_e32 v165, v164
	v_mov_b32_e32 v167, v166
	v_mov_b32_e32 v247, v246
	v_mov_b32_e32 v249, v248
	s_nop 1
	v_permlane16_swap_b32 v164, v165
	v_permlane16_swap_b32 v166, v167
	v_permlane16_swap_b32 v246, v247
	v_permlane16_swap_b32 v248, v249
	s_nop 1
	v_mov_b32_e32 v251, v249
	v_mov_b32_e32 v250, v167
	v_fma_f32 v251, v251, v166, v248
	v_mul_f32_e32 v250, v250, v166
	v_fma_f32 v251, v251, v165, v247
	v_mul_f32_e32 v250, v250, v165
	v_fma_f32 v251, v251, v164, v246
	v_mul_f32_e32 v250, v250, v164
	s_mov_b64 exec, s[10:11]
	ds_write_b64 v182, v[250:251] offset:1024
	s_mov_b64 exec, -1
	s_waitcnt lgkmcnt(0)
	s_barrier
	ds_read2_b64 v[4:7], v183 offset0:128 offset1:144
	s_add_i32 s52, s4, 1
	s_sub_i32 s52, 31, s52
	s_lshl_b32 s52, s52, 12
	v_add_u32_e32 v197, s52, v184
	s_waitcnt lgkmcnt(0)
	v_fma_f32 v198, v180, v6, v7
	v_cndmask_b32_e64 v199, v180, v198, s[24:25]
	v_fma_f32 v180, v198, v4, v5
	v_fma_f32 v200, v199, v167, v249
	v_cndmask_b32_e64 v199, v199, v200, s[16:17]
	v_fma_f32 v200, v199, v166, v248
	v_cndmask_b32_e64 v199, v199, v200, s[20:21]
	v_fma_f32 v200, v199, v165, v247
	v_cndmask_b32_e64 v199, v199, v200, s[22:23]
	v_fma_f32 v221, v127, v199, v177
	v_fma_f32 v220, v126, v221, v176
	v_fma_f32 v219, v125, v220, v175
	v_fma_f32 v218, v124, v219, v174
	v_fma_f32 v217, v123, v218, v173
	v_fma_f32 v216, v122, v217, v172
	v_fma_f32 v215, v121, v216, v171
	v_fma_f32 v214, v120, v215, v170
	v_cvt_pk_bf16_f32 v206, v214, v215
	v_cvt_pk_bf16_f32 v208, v216, v217
	v_cvt_pk_bf16_f32 v210, v218, v219
	v_cvt_pk_bf16_f32 v212, v220, v221
	ds_write_b16 v197, v206 offset:0
	ds_write_b16_d16_hi v197, v206 offset:64
	ds_write_b16 v197, v208 offset:128
	ds_write_b16_d16_hi v197, v208 offset:192
	ds_write_b16 v197, v210 offset:256
	ds_write_b16_d16_hi v197, v210 offset:320
	ds_write_b16 v197, v212 offset:384
	ds_write_b16_d16_hi v197, v212 offset:448
	s_add_i32 s4, s4, 2
	s_cmp_lt_u32 s4, 16
	s_cbranch_scc1 .Lrec2_loopA_d1
	ds_read_b128 v[198:201], v130 offset:0
	ds_read_b128 v[214:217], v130 offset:576
	ds_read_b128 v[202:205], v131 offset:0
	ds_read_b128 v[218:221], v131 offset:576
	ds_read_b128 v[206:209], v130 offset:144
	ds_read_b128 v[222:225], v130 offset:720
	ds_read_b128 v[210:213], v131 offset:144
	s_waitcnt lgkmcnt(14)
	ds_read_b128 v[226:229], v131 offset:720
	s_waitcnt lgkmcnt(6)
	v_mfma_f32_16x16x32_bf16 v[100:103], v[198:201], v[20:23], v[12:15]
	v_mfma_f32_16x16x32_bf16 v[104:107], v[198:201], v[52:55], v[16:19]
	v_mfma_f32_16x16x32_bf16 v[108:111], v[198:201], v[84:87], v[242:245]
	v_mfma_f32_16x16x32_bf16 v[112:115], v[214:217], v[20:23], v[12:15]
	v_mfma_f32_16x16x32_bf16 v[138:141], v[214:217], v[52:55], v[16:19]
	v_mfma_f32_16x16x32_bf16 v[142:145], v[214:217], v[84:87], v[242:245]
	s_waitcnt lgkmcnt(4)
	v_mfma_f32_16x16x32_bf16 v[100:103], v[202:205], v[24:27], v[100:103]
	v_mfma_f32_16x16x32_bf16 v[104:107], v[202:205], v[56:59], v[104:107]
	v_mfma_f32_16x16x32_bf16 v[112:115], v[218:221], v[24:27], v[112:115]
	v_mfma_f32_16x16x32_bf16 v[138:141], v[218:221], v[56:59], v[138:141]
	ds_read_b128 v[198:201], v130 offset:288
	ds_read_b128 v[214:217], v130 offset:864
	ds_read_b128 v[202:205], v131 offset:288
	ds_read_b128 v[218:221], v131 offset:864
	s_waitcnt lgkmcnt(6)
	v_mfma_f32_16x16x32_bf16 v[100:103], v[206:209], v[28:31], v[100:103]
	v_mfma_f32_16x16x32_bf16 v[104:107], v[206:209], v[60:63], v[104:107]
	v_mfma_f32_16x16x32_bf16 v[108:111], v[206:209], v[88:91], v[108:111]
	v_mfma_f32_16x16x32_bf16 v[112:115], v[222:225], v[28:31], v[112:115]
	v_mfma_f32_16x16x32_bf16 v[138:141], v[222:225], v[60:63], v[138:141]
	v_mfma_f32_16x16x32_bf16 v[142:145], v[222:225], v[88:91], v[142:145]
	s_waitcnt lgkmcnt(4)
	v_mfma_f32_16x16x32_bf16 v[100:103], v[210:213], v[32:35], v[100:103]
	v_mfma_f32_16x16x32_bf16 v[104:107], v[210:213], v[64:67], v[104:107]
	v_mfma_f32_16x16x32_bf16 v[112:115], v[226:229], v[32:35], v[112:115]
	v_mfma_f32_16x16x32_bf16 v[138:141], v[226:229], v[64:67], v[138:141]
	ds_read_b128 v[206:209], v130 offset:432
	ds_read_b128 v[222:225], v130 offset:1008
	ds_read_b128 v[210:213], v131 offset:432
	ds_read_b128 v[226:229], v131 offset:1008
	s_waitcnt lgkmcnt(6)
	v_mfma_f32_16x16x32_bf16 v[100:103], v[198:201], v[36:39], v[100:103]
	v_mfma_f32_16x16x32_bf16 v[104:107], v[198:201], v[68:71], v[104:107]
	v_mfma_f32_16x16x32_bf16 v[108:111], v[198:201], v[92:95], v[108:111]
	v_mfma_f32_16x16x32_bf16 v[112:115], v[214:217], v[36:39], v[112:115]
	v_mfma_f32_16x16x32_bf16 v[138:141], v[214:217], v[68:71], v[138:141]
	v_mfma_f32_16x16x32_bf16 v[142:145], v[214:217], v[92:95], v[142:145]
	s_waitcnt lgkmcnt(4)
	v_mfma_f32_16x16x32_bf16 v[100:103], v[202:205], v[40:43], v[100:103]
	v_mfma_f32_16x16x32_bf16 v[104:107], v[202:205], v[72:75], v[104:107]
	v_mfma_f32_16x16x32_bf16 v[112:115], v[218:221], v[40:43], v[112:115]
	v_mfma_f32_16x16x32_bf16 v[138:141], v[218:221], v[72:75], v[138:141]
	s_waitcnt lgkmcnt(2)
	v_mfma_f32_16x16x32_bf16 v[100:103], v[206:209], v[44:47], v[100:103]
	v_mfma_f32_16x16x32_bf16 v[104:107], v[206:209], v[76:79], v[104:107]
	v_mfma_f32_16x16x32_bf16 v[108:111], v[206:209], v[96:99], v[108:111]
	v_mfma_f32_16x16x32_bf16 v[112:115], v[222:225], v[44:47], v[112:115]
	v_mfma_f32_16x16x32_bf16 v[138:141], v[222:225], v[76:79], v[138:141]
	v_mfma_f32_16x16x32_bf16 v[142:145], v[222:225], v[96:99], v[142:145]
	s_waitcnt lgkmcnt(0)
	v_mfma_f32_16x16x32_bf16 v[100:103], v[210:213], v[48:51], v[100:103]
	v_mfma_f32_16x16x32_bf16 v[104:107], v[210:213], v[80:83], v[104:107]
	v_mfma_f32_16x16x32_bf16 v[112:115], v[226:229], v[48:51], v[112:115]
	v_mfma_f32_16x16x32_bf16 v[138:141], v[226:229], v[80:83], v[138:141]
	s_waitcnt lgkmcnt(0)
	s_barrier
	s_waitcnt vmcnt(3)
	ds_write_b128 v134, v[146:149]
	ds_write_b128 v134, v[150:153] offset:4608
	ds_write_b128 v135, v[160:163]
	s_add_i32 s64, s4, 0
	s_sub_i32 s64, 31, s64
	s_mul_i32 s71, s64, 0x30000
	s_add_u32 s38, s60, s71
	s_addc_u32 s39, s61, 0
	s_lshl_b32 s64, s64, 12
	global_load_dwordx4 v[8:11], v255, s[38:39]
	s_add_i32 s52, s4, 3
	s_min_u32 s52, s52, 31
	s_sub_i32 s52, 31, s52
	s_lshl_b32 s52, s52, 13
	s_add_u32 s26, s50, s52
	s_addc_u32 s27, s51, 0
	global_load_dwordx4 v[146:149], v154, s[26:27]
	global_load_dwordx4 v[150:153], v155, s[26:27]
	global_load_dwordx4 v[160:163], v159, s[26:27]
	v_exp_f32_e32 v198, v100
	v_exp_f32_e32 v199, v101
	v_exp_f32_e32 v200, v102
	v_exp_f32_e32 v201, v103
	v_exp_f32_e32 v202, v112
	v_exp_f32_e32 v203, v113
	v_exp_f32_e32 v204, v114
	v_exp_f32_e32 v205, v115
	v_exp_f32_e32 v214, v104
	v_add_f32_e32 v198, 1.0, v198
	v_exp_f32_e32 v215, v105
	v_add_f32_e32 v199, 1.0, v199
	v_exp_f32_e32 v216, v106
	v_add_f32_e32 v200, 1.0, v200
	v_exp_f32_e32 v217, v107
	v_add_f32_e32 v201, 1.0, v201
	v_exp_f32_e32 v218, v138
	v_add_f32_e32 v202, 1.0, v202
	v_exp_f32_e32 v219, v139
	v_add_f32_e32 v203, 1.0, v203
	v_exp_f32_e32 v220, v140
	v_add_f32_e32 v204, 1.0, v204
	v_exp_f32_e32 v221, v141
	v_add_f32_e32 v205, 1.0, v205
	v_rcp_f32_e32 v198, v198
	v_add_f32_e32 v214, 1.0, v214
	v_rcp_f32_e32 v199, v199
	v_add_f32_e32 v215, 1.0, v215
	v_rcp_f32_e32 v200, v200
	v_add_f32_e32 v216, 1.0, v216
	v_rcp_f32_e32 v201, v201
	v_add_f32_e32 v217, 1.0, v217
	v_rcp_f32_e32 v202, v202
	v_add_f32_e32 v218, 1.0, v218
	v_rcp_f32_e32 v203, v203
	v_add_f32_e32 v219, 1.0, v219
	v_rcp_f32_e32 v204, v204
	v_add_f32_e32 v220, 1.0, v220
	v_rcp_f32_e32 v205, v205
	v_add_f32_e32 v221, 1.0, v221
	v_mul_f32_e32 v198, v179, v198
	v_mul_f32_e32 v199, v179, v199
	v_mul_f32_e32 v200, v179, v200
	v_mul_f32_e32 v201, v179, v201
	v_mul_f32_e32 v202, v179, v202
	v_mul_f32_e32 v203, v179, v203
	v_mul_f32_e32 v204, v179, v204
	v_mul_f32_e32 v205, v179, v205
	v_exp_f32_e32 v120, v198
	v_exp_f32_e32 v121, v199
	v_exp_f32_e32 v122, v200
	v_exp_f32_e32 v123, v201
	v_exp_f32_e32 v124, v202
	v_exp_f32_e32 v125, v203
	v_exp_f32_e32 v126, v204
	v_exp_f32_e32 v127, v205
	v_fma_f32 v206, -v120, v120, 1.0
	v_fma_f32 v207, -v121, v121, 1.0
	v_fma_f32 v208, -v122, v122, 1.0
	v_fma_f32 v209, -v123, v123, 1.0
	v_fma_f32 v210, -v124, v124, 1.0
	v_fma_f32 v211, -v125, v125, 1.0
	v_fma_f32 v212, -v126, v126, 1.0
	v_fma_f32 v213, -v127, v127, 1.0
	v_max_f32_e32 v206, 0xda24260, v206
	v_max_f32_e32 v207, 0xda24260, v207
	v_max_f32_e32 v208, 0xda24260, v208
	v_max_f32_e32 v209, 0xda24260, v209
	v_max_f32_e32 v210, 0xda24260, v210
	v_max_f32_e32 v211, 0xda24260, v211
	v_max_f32_e32 v212, 0xda24260, v212
	v_max_f32_e32 v213, 0xda24260, v213
	v_mul_f32_e32 v198, v214, v206
	v_mul_f32_e32 v199, v215, v207
	v_mul_f32_e32 v200, v216, v208
	v_mul_f32_e32 v201, v217, v209
	v_mul_f32_e32 v202, v218, v210
	v_mul_f32_e32 v203, v219, v211
	v_mul_f32_e32 v204, v220, v212
	v_mul_f32_e32 v205, v221, v213
	v_mul_f32_e32 v214, v214, v198
	v_mul_f32_e32 v215, v215, v199
	v_mul_f32_e32 v216, v216, v200
	v_mul_f32_e32 v217, v217, v201
	v_mul_f32_e32 v218, v218, v202
	v_mul_f32_e32 v219, v219, v203
	v_mul_f32_e32 v220, v220, v204
	v_mul_f32_e32 v221, v221, v205
	v_rsq_f32_e32 v214, v214
	v_mul_f32_e32 v222, v108, v206
	v_rsq_f32_e32 v215, v215
	v_mul_f32_e32 v223, v109, v207
	v_rsq_f32_e32 v216, v216
	v_mul_f32_e32 v224, v110, v208
	v_rsq_f32_e32 v217, v217
	v_mul_f32_e32 v225, v111, v209
	v_rsq_f32_e32 v218, v218
	v_mul_f32_e32 v226, v142, v210
	v_rsq_f32_e32 v219, v219
	v_mul_f32_e32 v227, v143, v211
	v_rsq_f32_e32 v220, v220
	v_mul_f32_e32 v228, v144, v212
	v_rsq_f32_e32 v221, v221
	v_mul_f32_e32 v229, v145, v213
	v_mul_f32_e32 v170, v222, v214
	v_mul_f32_e32 v171, v223, v215
	v_mul_f32_e32 v172, v224, v216
	v_mul_f32_e32 v173, v225, v217
	v_mul_f32_e32 v174, v226, v218
	v_mul_f32_e32 v175, v227, v219
	v_mul_f32_e32 v176, v228, v220
	v_mul_f32_e32 v177, v229, v221
	v_mov_b32_e32 v198, v177
	v_mov_b32_e32 v199, v127
	v_fma_f32 v198, v126, v198, v176
	v_mul_f32_e32 v199, v199, v126
	v_fma_f32 v198, v125, v198, v175
	v_mul_f32_e32 v199, v199, v125
	v_fma_f32 v198, v124, v198, v174
	v_mul_f32_e32 v199, v199, v124
	v_fma_f32 v198, v123, v198, v173
	v_mul_f32_e32 v199, v199, v123
	v_fma_f32 v198, v122, v198, v172
	v_mul_f32_e32 v199, v199, v122
	v_fma_f32 v198, v121, v198, v171
	v_mul_f32_e32 v199, v199, v121
	v_fma_f32 v198, v120, v198, v170
	v_mul_f32_e32 v199, v199, v120
	v_mov_b32_e32 v164, v199
	v_mov_b32_e32 v166, v199
	v_mov_b32_e32 v246, v198
	v_mov_b32_e32 v248, v198
	s_nop 1
	v_permlane32_swap_b32 v164, v166
	v_permlane32_swap_b32 v246, v248
	s_nop 1
	v_mov_b32_e32 v165, v164
	v_mov_b32_e32 v167, v166
	v_mov_b32_e32 v247, v246
	v_mov_b32_e32 v249, v248
	s_nop 1
	v_permlane16_swap_b32 v164, v165
	v_permlane16_swap_b32 v166, v167
	v_permlane16_swap_b32 v246, v247
	v_permlane16_swap_b32 v248, v249
	s_nop 1
	v_mov_b32_e32 v251, v249
	v_mov_b32_e32 v250, v167
	v_fma_f32 v251, v251, v166, v248
	v_mul_f32_e32 v250, v250, v166
	v_fma_f32 v251, v251, v165, v247
	v_mul_f32_e32 v250, v250, v165
	v_fma_f32 v251, v251, v164, v246
	v_mul_f32_e32 v250, v250, v164
	s_mov_b64 exec, s[10:11]
	ds_write_b64 v182, v[250:251] offset:0
	s_mov_b64 exec, -1
	s_waitcnt lgkmcnt(0)
	s_barrier
	ds_read2_b64 v[4:7], v183 offset0:0 offset1:16
	s_add_i32 s52, s4, 0
	s_sub_i32 s52, 31, s52
	s_lshl_b32 s52, s52, 12
	v_add_u32_e32 v197, s52, v184
	s_waitcnt lgkmcnt(0)
	v_fma_f32 v198, v180, v6, v7
	v_cndmask_b32_e64 v199, v180, v198, s[24:25]
	v_fma_f32 v180, v198, v4, v5
	v_fma_f32 v200, v199, v167, v249
	v_cndmask_b32_e64 v199, v199, v200, s[16:17]
	v_fma_f32 v200, v199, v166, v248
	v_cndmask_b32_e64 v199, v199, v200, s[20:21]
	v_fma_f32 v200, v199, v165, v247
	v_cndmask_b32_e64 v199, v199, v200, s[22:23]
	v_fma_f32 v221, v127, v199, v177
	v_fma_f32 v220, v126, v221, v176
	v_fma_f32 v219, v125, v220, v175
	v_fma_f32 v218, v124, v219, v174
	v_fma_f32 v217, v123, v218, v173
	v_fma_f32 v216, v122, v217, v172
	v_fma_f32 v215, v121, v216, v171
	v_fma_f32 v214, v120, v215, v170
	ds_read_u16 v206, v197 offset:0
	ds_read_u16 v207, v197 offset:64
	ds_read_u16 v208, v197 offset:128
	ds_read_u16 v209, v197 offset:192
	ds_read_u16 v210, v197 offset:256
	ds_read_u16 v211, v197 offset:320
	ds_read_u16 v212, v197 offset:384
	ds_read_u16 v213, v197 offset:448
	s_waitcnt lgkmcnt(0)
	v_lshlrev_b32_e32 v206, 16, v206
	v_lshlrev_b32_e32 v207, 16, v207
	v_lshlrev_b32_e32 v208, 16, v208
	v_lshlrev_b32_e32 v209, 16, v209
	v_lshlrev_b32_e32 v210, 16, v210
	v_lshlrev_b32_e32 v211, 16, v211
	v_lshlrev_b32_e32 v212, 16, v212
	v_lshlrev_b32_e32 v213, 16, v213
	v_add_f32_e32 v214, v214, v206
	v_add_f32_e32 v215, v215, v207
	v_add_f32_e32 v216, v216, v208
	v_add_f32_e32 v217, v217, v209
	v_add_f32_e32 v218, v218, v210
	v_add_f32_e32 v219, v219, v211
	v_add_f32_e32 v220, v220, v212
	v_add_f32_e32 v221, v221, v213
	v_cvt_pk_bf16_f32 v206, v214, v215
	v_cvt_pk_bf16_f32 v208, v216, v217
	v_cvt_pk_bf16_f32 v210, v218, v219
	v_cvt_pk_bf16_f32 v212, v220, v221
	ds_write_b16 v197, v206 offset:0
	ds_write_b16_d16_hi v197, v206 offset:64
	ds_write_b16 v197, v208 offset:128
	ds_write_b16_d16_hi v197, v208 offset:192
	ds_write_b16 v197, v210 offset:256
	ds_write_b16_d16_hi v197, v210 offset:320
	ds_write_b16 v197, v212 offset:384
	ds_write_b16_d16_hi v197, v212 offset:448
	ds_read_b128 v[198:201], v130 offset:0
	ds_read_b128 v[214:217], v130 offset:576
	ds_read_b128 v[202:205], v131 offset:0
	ds_read_b128 v[218:221], v131 offset:576
	ds_read_b128 v[206:209], v130 offset:144
	ds_read_b128 v[222:225], v130 offset:720
	ds_read_b128 v[210:213], v131 offset:144
	s_waitcnt lgkmcnt(14)
	ds_read_b128 v[226:229], v131 offset:720
	s_waitcnt lgkmcnt(6)
	v_mfma_f32_16x16x32_bf16 v[100:103], v[198:201], v[20:23], v[12:15]
	v_mfma_f32_16x16x32_bf16 v[104:107], v[198:201], v[52:55], v[16:19]
	v_mfma_f32_16x16x32_bf16 v[108:111], v[198:201], v[84:87], v[242:245]
	v_mfma_f32_16x16x32_bf16 v[112:115], v[214:217], v[20:23], v[12:15]
	v_mfma_f32_16x16x32_bf16 v[138:141], v[214:217], v[52:55], v[16:19]
	v_mfma_f32_16x16x32_bf16 v[142:145], v[214:217], v[84:87], v[242:245]
	s_waitcnt lgkmcnt(4)
	v_mfma_f32_16x16x32_bf16 v[100:103], v[202:205], v[24:27], v[100:103]
	v_mfma_f32_16x16x32_bf16 v[104:107], v[202:205], v[56:59], v[104:107]
	v_mfma_f32_16x16x32_bf16 v[112:115], v[218:221], v[24:27], v[112:115]
	v_mfma_f32_16x16x32_bf16 v[138:141], v[218:221], v[56:59], v[138:141]
	ds_read_b128 v[198:201], v130 offset:288
	ds_read_b128 v[214:217], v130 offset:864
	ds_read_b128 v[202:205], v131 offset:288
	ds_read_b128 v[218:221], v131 offset:864
	s_waitcnt lgkmcnt(6)
	v_mfma_f32_16x16x32_bf16 v[100:103], v[206:209], v[28:31], v[100:103]
	v_mfma_f32_16x16x32_bf16 v[104:107], v[206:209], v[60:63], v[104:107]
	v_mfma_f32_16x16x32_bf16 v[108:111], v[206:209], v[88:91], v[108:111]
	v_mfma_f32_16x16x32_bf16 v[112:115], v[222:225], v[28:31], v[112:115]
	v_mfma_f32_16x16x32_bf16 v[138:141], v[222:225], v[60:63], v[138:141]
	v_mfma_f32_16x16x32_bf16 v[142:145], v[222:225], v[88:91], v[142:145]
	s_waitcnt lgkmcnt(4)
	v_mfma_f32_16x16x32_bf16 v[100:103], v[210:213], v[32:35], v[100:103]
	v_mfma_f32_16x16x32_bf16 v[104:107], v[210:213], v[64:67], v[104:107]
	v_mfma_f32_16x16x32_bf16 v[112:115], v[226:229], v[32:35], v[112:115]
	v_mfma_f32_16x16x32_bf16 v[138:141], v[226:229], v[64:67], v[138:141]
	ds_read_b128 v[206:209], v130 offset:432
	ds_read_b128 v[222:225], v130 offset:1008
	ds_read_b128 v[210:213], v131 offset:432
	ds_read_b128 v[226:229], v131 offset:1008
	s_waitcnt lgkmcnt(6)
	v_mfma_f32_16x16x32_bf16 v[100:103], v[198:201], v[36:39], v[100:103]
	v_mfma_f32_16x16x32_bf16 v[104:107], v[198:201], v[68:71], v[104:107]
	v_mfma_f32_16x16x32_bf16 v[108:111], v[198:201], v[92:95], v[108:111]
	v_mfma_f32_16x16x32_bf16 v[112:115], v[214:217], v[36:39], v[112:115]
	v_mfma_f32_16x16x32_bf16 v[138:141], v[214:217], v[68:71], v[138:141]
	v_mfma_f32_16x16x32_bf16 v[142:145], v[214:217], v[92:95], v[142:145]
	s_waitcnt lgkmcnt(4)
	v_mfma_f32_16x16x32_bf16 v[100:103], v[202:205], v[40:43], v[100:103]
	v_mfma_f32_16x16x32_bf16 v[104:107], v[202:205], v[72:75], v[104:107]
	v_mfma_f32_16x16x32_bf16 v[112:115], v[218:221], v[40:43], v[112:115]
	v_mfma_f32_16x16x32_bf16 v[138:141], v[218:221], v[72:75], v[138:141]
	s_waitcnt lgkmcnt(2)
	v_mfma_f32_16x16x32_bf16 v[100:103], v[206:209], v[44:47], v[100:103]
	v_mfma_f32_16x16x32_bf16 v[104:107], v[206:209], v[76:79], v[104:107]
	v_mfma_f32_16x16x32_bf16 v[108:111], v[206:209], v[96:99], v[108:111]
	v_mfma_f32_16x16x32_bf16 v[112:115], v[222:225], v[44:47], v[112:115]
	v_mfma_f32_16x16x32_bf16 v[138:141], v[222:225], v[76:79], v[138:141]
	v_mfma_f32_16x16x32_bf16 v[142:145], v[222:225], v[96:99], v[142:145]
	s_waitcnt lgkmcnt(0)
	v_mfma_f32_16x16x32_bf16 v[100:103], v[210:213], v[48:51], v[100:103]
	v_mfma_f32_16x16x32_bf16 v[104:107], v[210:213], v[80:83], v[104:107]
	v_mfma_f32_16x16x32_bf16 v[112:115], v[226:229], v[48:51], v[112:115]
	v_mfma_f32_16x16x32_bf16 v[138:141], v[226:229], v[80:83], v[138:141]
	s_waitcnt lgkmcnt(0)
	s_barrier
	s_waitcnt vmcnt(4)
	ds_write_b128 v134, v[230:233]
	ds_write_b128 v134, v[234:237] offset:4608
	ds_write_b128 v135, v[238:241]
	s_add_i32 s64, s4, 0
	s_sub_i32 s64, 31, s64
	s_mul_i32 s71, s64, 0x30000
	s_add_u32 s38, s60, s71
	s_addc_u32 s39, s61, 0
	s_lshl_b32 s64, s64, 12
	v_add_u32_e32 v136, s64, v195
	ds_read_b128 v[116:119], v136
	s_waitcnt vmcnt(3)
	s_waitcnt lgkmcnt(0)
	v_lshlrev_b32_e32 v136, 16, v116
	v_lshlrev_b32_e32 v137, 16, v8
	v_and_b32_e32 v168, 0xffff0000, v116
	v_and_b32_e32 v169, 0xffff0000, v8
	v_mul_f32_e32 v136, v136, v137
	v_mul_f32_e32 v168, v168, v169
	v_cvt_pk_bf16_f32 v116, v136, v168
	v_lshlrev_b32_e32 v136, 16, v117
	v_lshlrev_b32_e32 v137, 16, v9
	v_and_b32_e32 v168, 0xffff0000, v117
	v_and_b32_e32 v169, 0xffff0000, v9
	v_mul_f32_e32 v136, v136, v137
	v_mul_f32_e32 v168, v168, v169
	v_cvt_pk_bf16_f32 v117, v136, v168
	v_lshlrev_b32_e32 v136, 16, v118
	v_lshlrev_b32_e32 v137, 16, v10
	v_and_b32_e32 v168, 0xffff0000, v118
	v_and_b32_e32 v169, 0xffff0000, v10
	v_mul_f32_e32 v136, v136, v137
	v_mul_f32_e32 v168, v168, v169
	v_cvt_pk_bf16_f32 v118, v136, v168
	v_lshlrev_b32_e32 v136, 16, v119
	v_lshlrev_b32_e32 v137, 16, v11
	v_and_b32_e32 v168, 0xffff0000, v119
	v_and_b32_e32 v169, 0xffff0000, v11
	v_mul_f32_e32 v136, v136, v137
	v_mul_f32_e32 v168, v168, v169
	v_cvt_pk_bf16_f32 v119, v136, v168
	global_store_dwordx4 v255, v[116:119], s[38:39]
	s_add_i32 s64, s4, 1
	s_sub_i32 s64, 31, s64
	s_mul_i32 s71, s64, 0x30000
	s_add_u32 s38, s60, s71
	s_addc_u32 s39, s61, 0
	s_lshl_b32 s64, s64, 12
	global_load_dwordx4 v[8:11], v255, s[38:39]
	s_add_i32 s52, s4, 4
	s_min_u32 s52, s52, 31
	s_sub_i32 s52, 31, s52
	s_lshl_b32 s52, s52, 13
	s_add_u32 s26, s50, s52
	s_addc_u32 s27, s51, 0
	global_load_dwordx4 v[230:233], v154, s[26:27]
	global_load_dwordx4 v[234:237], v155, s[26:27]
	global_load_dwordx4 v[238:241], v159, s[26:27]
	v_exp_f32_e32 v198, v100
	v_exp_f32_e32 v199, v101
	v_exp_f32_e32 v200, v102
	v_exp_f32_e32 v201, v103
	v_exp_f32_e32 v202, v112
	v_exp_f32_e32 v203, v113
	v_exp_f32_e32 v204, v114
	v_exp_f32_e32 v205, v115
	v_exp_f32_e32 v214, v104
	v_add_f32_e32 v198, 1.0, v198
	v_exp_f32_e32 v215, v105
	v_add_f32_e32 v199, 1.0, v199
	v_exp_f32_e32 v216, v106
	v_add_f32_e32 v200, 1.0, v200
	v_exp_f32_e32 v217, v107
	v_add_f32_e32 v201, 1.0, v201
	v_exp_f32_e32 v218, v138
	v_add_f32_e32 v202, 1.0, v202
	v_exp_f32_e32 v219, v139
	v_add_f32_e32 v203, 1.0, v203
	v_exp_f32_e32 v220, v140
	v_add_f32_e32 v204, 1.0, v204
	v_exp_f32_e32 v221, v141
	v_add_f32_e32 v205, 1.0, v205
	v_rcp_f32_e32 v198, v198
	v_add_f32_e32 v214, 1.0, v214
	v_rcp_f32_e32 v199, v199
	v_add_f32_e32 v215, 1.0, v215
	v_rcp_f32_e32 v200, v200
	v_add_f32_e32 v216, 1.0, v216
	v_rcp_f32_e32 v201, v201
	v_add_f32_e32 v217, 1.0, v217
	v_rcp_f32_e32 v202, v202
	v_add_f32_e32 v218, 1.0, v218
	v_rcp_f32_e32 v203, v203
	v_add_f32_e32 v219, 1.0, v219
	v_rcp_f32_e32 v204, v204
	v_add_f32_e32 v220, 1.0, v220
	v_rcp_f32_e32 v205, v205
	v_add_f32_e32 v221, 1.0, v221
	v_mul_f32_e32 v198, v179, v198
	v_mul_f32_e32 v199, v179, v199
	v_mul_f32_e32 v200, v179, v200
	v_mul_f32_e32 v201, v179, v201
	v_mul_f32_e32 v202, v179, v202
	v_mul_f32_e32 v203, v179, v203
	v_mul_f32_e32 v204, v179, v204
	v_mul_f32_e32 v205, v179, v205
	v_exp_f32_e32 v120, v198
	v_exp_f32_e32 v121, v199
	v_exp_f32_e32 v122, v200
	v_exp_f32_e32 v123, v201
	v_exp_f32_e32 v124, v202
	v_exp_f32_e32 v125, v203
	v_exp_f32_e32 v126, v204
	v_exp_f32_e32 v127, v205
	v_fma_f32 v206, -v120, v120, 1.0
	v_fma_f32 v207, -v121, v121, 1.0
	v_fma_f32 v208, -v122, v122, 1.0
	v_fma_f32 v209, -v123, v123, 1.0
	v_fma_f32 v210, -v124, v124, 1.0
	v_fma_f32 v211, -v125, v125, 1.0
	v_fma_f32 v212, -v126, v126, 1.0
	v_fma_f32 v213, -v127, v127, 1.0
	v_max_f32_e32 v206, 0xda24260, v206
	v_max_f32_e32 v207, 0xda24260, v207
	v_max_f32_e32 v208, 0xda24260, v208
	v_max_f32_e32 v209, 0xda24260, v209
	v_max_f32_e32 v210, 0xda24260, v210
	v_max_f32_e32 v211, 0xda24260, v211
	v_max_f32_e32 v212, 0xda24260, v212
	v_max_f32_e32 v213, 0xda24260, v213
	v_mul_f32_e32 v198, v214, v206
	v_mul_f32_e32 v199, v215, v207
	v_mul_f32_e32 v200, v216, v208
	v_mul_f32_e32 v201, v217, v209
	v_mul_f32_e32 v202, v218, v210
	v_mul_f32_e32 v203, v219, v211
	v_mul_f32_e32 v204, v220, v212
	v_mul_f32_e32 v205, v221, v213
	v_mul_f32_e32 v214, v214, v198
	v_mul_f32_e32 v215, v215, v199
	v_mul_f32_e32 v216, v216, v200
	v_mul_f32_e32 v217, v217, v201
	v_mul_f32_e32 v218, v218, v202
	v_mul_f32_e32 v219, v219, v203
	v_mul_f32_e32 v220, v220, v204
	v_mul_f32_e32 v221, v221, v205
	v_rsq_f32_e32 v214, v214
	v_mul_f32_e32 v222, v108, v206
	v_rsq_f32_e32 v215, v215
	v_mul_f32_e32 v223, v109, v207
	v_rsq_f32_e32 v216, v216
	v_mul_f32_e32 v224, v110, v208
	v_rsq_f32_e32 v217, v217
	v_mul_f32_e32 v225, v111, v209
	v_rsq_f32_e32 v218, v218
	v_mul_f32_e32 v226, v142, v210
	v_rsq_f32_e32 v219, v219
	v_mul_f32_e32 v227, v143, v211
	v_rsq_f32_e32 v220, v220
	v_mul_f32_e32 v228, v144, v212
	v_rsq_f32_e32 v221, v221
	v_mul_f32_e32 v229, v145, v213
	v_mul_f32_e32 v170, v222, v214
	v_mul_f32_e32 v171, v223, v215
	v_mul_f32_e32 v172, v224, v216
	v_mul_f32_e32 v173, v225, v217
	v_mul_f32_e32 v174, v226, v218
	v_mul_f32_e32 v175, v227, v219
	v_mul_f32_e32 v176, v228, v220
	v_mul_f32_e32 v177, v229, v221
	v_mov_b32_e32 v198, v177
	v_mov_b32_e32 v199, v127
	v_fma_f32 v198, v126, v198, v176
	v_mul_f32_e32 v199, v199, v126
	v_fma_f32 v198, v125, v198, v175
	v_mul_f32_e32 v199, v199, v125
	v_fma_f32 v198, v124, v198, v174
	v_mul_f32_e32 v199, v199, v124
	v_fma_f32 v198, v123, v198, v173
	v_mul_f32_e32 v199, v199, v123
	v_fma_f32 v198, v122, v198, v172
	v_mul_f32_e32 v199, v199, v122
	v_fma_f32 v198, v121, v198, v171
	v_mul_f32_e32 v199, v199, v121
	v_fma_f32 v198, v120, v198, v170
	v_mul_f32_e32 v199, v199, v120
	v_mov_b32_e32 v164, v199
	v_mov_b32_e32 v166, v199
	v_mov_b32_e32 v246, v198
	v_mov_b32_e32 v248, v198
	s_nop 1
	v_permlane32_swap_b32 v164, v166
	v_permlane32_swap_b32 v246, v248
	s_nop 1
	v_mov_b32_e32 v165, v164
	v_mov_b32_e32 v167, v166
	v_mov_b32_e32 v247, v246
	v_mov_b32_e32 v249, v248
	s_nop 1
	v_permlane16_swap_b32 v164, v165
	v_permlane16_swap_b32 v166, v167
	v_permlane16_swap_b32 v246, v247
	v_permlane16_swap_b32 v248, v249
	s_nop 1
	v_mov_b32_e32 v251, v249
	v_mov_b32_e32 v250, v167
	v_fma_f32 v251, v251, v166, v248
	v_mul_f32_e32 v250, v250, v166
	v_fma_f32 v251, v251, v165, v247
	v_mul_f32_e32 v250, v250, v165
	v_fma_f32 v251, v251, v164, v246
	v_mul_f32_e32 v250, v250, v164
	s_mov_b64 exec, s[10:11]
	ds_write_b64 v182, v[250:251] offset:1024
	s_mov_b64 exec, -1
	s_waitcnt lgkmcnt(0)
	s_barrier
	ds_read2_b64 v[4:7], v183 offset0:128 offset1:144
	s_add_i32 s52, s4, 1
	s_sub_i32 s52, 31, s52
	s_lshl_b32 s52, s52, 12
	v_add_u32_e32 v197, s52, v184
	s_waitcnt lgkmcnt(0)
	v_fma_f32 v198, v180, v6, v7
	v_cndmask_b32_e64 v199, v180, v198, s[24:25]
	v_fma_f32 v180, v198, v4, v5
	v_fma_f32 v200, v199, v167, v249
	v_cndmask_b32_e64 v199, v199, v200, s[16:17]
	v_fma_f32 v200, v199, v166, v248
	v_cndmask_b32_e64 v199, v199, v200, s[20:21]
	v_fma_f32 v200, v199, v165, v247
	v_cndmask_b32_e64 v199, v199, v200, s[22:23]
	v_fma_f32 v221, v127, v199, v177
	v_fma_f32 v220, v126, v221, v176
	v_fma_f32 v219, v125, v220, v175
	v_fma_f32 v218, v124, v219, v174
	v_fma_f32 v217, v123, v218, v173
	v_fma_f32 v216, v122, v217, v172
	v_fma_f32 v215, v121, v216, v171
	v_fma_f32 v214, v120, v215, v170
	ds_read_u16 v206, v197 offset:0
	ds_read_u16 v207, v197 offset:64
	ds_read_u16 v208, v197 offset:128
	ds_read_u16 v209, v197 offset:192
	ds_read_u16 v210, v197 offset:256
	ds_read_u16 v211, v197 offset:320
	ds_read_u16 v212, v197 offset:384
	ds_read_u16 v213, v197 offset:448
	s_waitcnt lgkmcnt(0)
	v_lshlrev_b32_e32 v206, 16, v206
	v_lshlrev_b32_e32 v207, 16, v207
	v_lshlrev_b32_e32 v208, 16, v208
	v_lshlrev_b32_e32 v209, 16, v209
	v_lshlrev_b32_e32 v210, 16, v210
	v_lshlrev_b32_e32 v211, 16, v211
	v_lshlrev_b32_e32 v212, 16, v212
	v_lshlrev_b32_e32 v213, 16, v213
	v_add_f32_e32 v214, v214, v206
	v_add_f32_e32 v215, v215, v207
	v_add_f32_e32 v216, v216, v208
	v_add_f32_e32 v217, v217, v209
	v_add_f32_e32 v218, v218, v210
	v_add_f32_e32 v219, v219, v211
	v_add_f32_e32 v220, v220, v212
	v_add_f32_e32 v221, v221, v213
	v_cvt_pk_bf16_f32 v206, v214, v215
	v_cvt_pk_bf16_f32 v208, v216, v217
	v_cvt_pk_bf16_f32 v210, v218, v219
	v_cvt_pk_bf16_f32 v212, v220, v221
	ds_write_b16 v197, v206 offset:0
	ds_write_b16_d16_hi v197, v206 offset:64
	ds_write_b16 v197, v208 offset:128
	ds_write_b16_d16_hi v197, v208 offset:192
	ds_write_b16 v197, v210 offset:256
	ds_write_b16_d16_hi v197, v210 offset:320
	ds_write_b16 v197, v212 offset:384
	ds_write_b16_d16_hi v197, v212 offset:448
	s_add_i32 s4, s4, 2
.Lrec2_loopB_d1:
	ds_read_b128 v[198:201], v130 offset:0
	ds_read_b128 v[214:217], v130 offset:576
	ds_read_b128 v[202:205], v131 offset:0
	ds_read_b128 v[218:221], v131 offset:576
	ds_read_b128 v[206:209], v130 offset:144
	ds_read_b128 v[222:225], v130 offset:720
	ds_read_b128 v[210:213], v131 offset:144
	s_waitcnt lgkmcnt(14)
	ds_read_b128 v[226:229], v131 offset:720
	s_waitcnt lgkmcnt(6)
	v_mfma_f32_16x16x32_bf16 v[100:103], v[198:201], v[20:23], v[12:15]
	v_mfma_f32_16x16x32_bf16 v[104:107], v[198:201], v[52:55], v[16:19]
	v_mfma_f32_16x16x32_bf16 v[108:111], v[198:201], v[84:87], v[242:245]
	v_mfma_f32_16x16x32_bf16 v[112:115], v[214:217], v[20:23], v[12:15]
	v_mfma_f32_16x16x32_bf16 v[138:141], v[214:217], v[52:55], v[16:19]
	v_mfma_f32_16x16x32_bf16 v[142:145], v[214:217], v[84:87], v[242:245]
	s_waitcnt lgkmcnt(4)
	v_mfma_f32_16x16x32_bf16 v[100:103], v[202:205], v[24:27], v[100:103]
	v_mfma_f32_16x16x32_bf16 v[104:107], v[202:205], v[56:59], v[104:107]
	v_mfma_f32_16x16x32_bf16 v[112:115], v[218:221], v[24:27], v[112:115]
	v_mfma_f32_16x16x32_bf16 v[138:141], v[218:221], v[56:59], v[138:141]
	ds_read_b128 v[198:201], v130 offset:288
	ds_read_b128 v[214:217], v130 offset:864
	ds_read_b128 v[202:205], v131 offset:288
	ds_read_b128 v[218:221], v131 offset:864
	s_waitcnt lgkmcnt(6)
	v_mfma_f32_16x16x32_bf16 v[100:103], v[206:209], v[28:31], v[100:103]
	v_mfma_f32_16x16x32_bf16 v[104:107], v[206:209], v[60:63], v[104:107]
	v_mfma_f32_16x16x32_bf16 v[108:111], v[206:209], v[88:91], v[108:111]
	v_mfma_f32_16x16x32_bf16 v[112:115], v[222:225], v[28:31], v[112:115]
	v_mfma_f32_16x16x32_bf16 v[138:141], v[222:225], v[60:63], v[138:141]
	v_mfma_f32_16x16x32_bf16 v[142:145], v[222:225], v[88:91], v[142:145]
	s_waitcnt lgkmcnt(4)
	v_mfma_f32_16x16x32_bf16 v[100:103], v[210:213], v[32:35], v[100:103]
	v_mfma_f32_16x16x32_bf16 v[104:107], v[210:213], v[64:67], v[104:107]
	v_mfma_f32_16x16x32_bf16 v[112:115], v[226:229], v[32:35], v[112:115]
	v_mfma_f32_16x16x32_bf16 v[138:141], v[226:229], v[64:67], v[138:141]
	ds_read_b128 v[206:209], v130 offset:432
	ds_read_b128 v[222:225], v130 offset:1008
	ds_read_b128 v[210:213], v131 offset:432
	ds_read_b128 v[226:229], v131 offset:1008
	s_waitcnt lgkmcnt(6)
	v_mfma_f32_16x16x32_bf16 v[100:103], v[198:201], v[36:39], v[100:103]
	v_mfma_f32_16x16x32_bf16 v[104:107], v[198:201], v[68:71], v[104:107]
	v_mfma_f32_16x16x32_bf16 v[108:111], v[198:201], v[92:95], v[108:111]
	v_mfma_f32_16x16x32_bf16 v[112:115], v[214:217], v[36:39], v[112:115]
	v_mfma_f32_16x16x32_bf16 v[138:141], v[214:217], v[68:71], v[138:141]
	v_mfma_f32_16x16x32_bf16 v[142:145], v[214:217], v[92:95], v[142:145]
	s_waitcnt lgkmcnt(4)
	v_mfma_f32_16x16x32_bf16 v[100:103], v[202:205], v[40:43], v[100:103]
	v_mfma_f32_16x16x32_bf16 v[104:107], v[202:205], v[72:75], v[104:107]
	v_mfma_f32_16x16x32_bf16 v[112:115], v[218:221], v[40:43], v[112:115]
	v_mfma_f32_16x16x32_bf16 v[138:141], v[218:221], v[72:75], v[138:141]
	s_waitcnt lgkmcnt(2)
	v_mfma_f32_16x16x32_bf16 v[100:103], v[206:209], v[44:47], v[100:103]
	v_mfma_f32_16x16x32_bf16 v[104:107], v[206:209], v[76:79], v[104:107]
	v_mfma_f32_16x16x32_bf16 v[108:111], v[206:209], v[96:99], v[108:111]
	v_mfma_f32_16x16x32_bf16 v[112:115], v[222:225], v[44:47], v[112:115]
	v_mfma_f32_16x16x32_bf16 v[138:141], v[222:225], v[76:79], v[138:141]
	v_mfma_f32_16x16x32_bf16 v[142:145], v[222:225], v[96:99], v[142:145]
	s_waitcnt lgkmcnt(0)
	v_mfma_f32_16x16x32_bf16 v[100:103], v[210:213], v[48:51], v[100:103]
	v_mfma_f32_16x16x32_bf16 v[104:107], v[210:213], v[80:83], v[104:107]
	v_mfma_f32_16x16x32_bf16 v[112:115], v[226:229], v[48:51], v[112:115]
	v_mfma_f32_16x16x32_bf16 v[138:141], v[226:229], v[80:83], v[138:141]
	s_waitcnt lgkmcnt(0)
	s_barrier
	s_waitcnt vmcnt(5)
	ds_write_b128 v134, v[146:149]
	ds_write_b128 v134, v[150:153] offset:4608
	ds_write_b128 v135, v[160:163]
	s_add_i32 s64, s4, -1
	s_sub_i32 s64, 31, s64
	s_mul_i32 s71, s64, 0x30000
	s_add_u32 s38, s60, s71
	s_addc_u32 s39, s61, 0
	s_lshl_b32 s64, s64, 12
	v_add_u32_e32 v136, s64, v195
	ds_read_b128 v[116:119], v136
	s_waitcnt vmcnt(3)
	s_waitcnt lgkmcnt(0)
	v_lshlrev_b32_e32 v136, 16, v116
	v_lshlrev_b32_e32 v137, 16, v8
	v_and_b32_e32 v168, 0xffff0000, v116
	v_and_b32_e32 v169, 0xffff0000, v8
	v_mul_f32_e32 v136, v136, v137
	v_mul_f32_e32 v168, v168, v169
	v_cvt_pk_bf16_f32 v116, v136, v168
	v_lshlrev_b32_e32 v136, 16, v117
	v_lshlrev_b32_e32 v137, 16, v9
	v_and_b32_e32 v168, 0xffff0000, v117
	v_and_b32_e32 v169, 0xffff0000, v9
	v_mul_f32_e32 v136, v136, v137
	v_mul_f32_e32 v168, v168, v169
	v_cvt_pk_bf16_f32 v117, v136, v168
	v_lshlrev_b32_e32 v136, 16, v118
	v_lshlrev_b32_e32 v137, 16, v10
	v_and_b32_e32 v168, 0xffff0000, v118
	v_and_b32_e32 v169, 0xffff0000, v10
	v_mul_f32_e32 v136, v136, v137
	v_mul_f32_e32 v168, v168, v169
	v_cvt_pk_bf16_f32 v118, v136, v168
	v_lshlrev_b32_e32 v136, 16, v119
	v_lshlrev_b32_e32 v137, 16, v11
	v_and_b32_e32 v168, 0xffff0000, v119
	v_and_b32_e32 v169, 0xffff0000, v11
	v_mul_f32_e32 v136, v136, v137
	v_mul_f32_e32 v168, v168, v169
	v_cvt_pk_bf16_f32 v119, v136, v168
	global_store_dwordx4 v255, v[116:119], s[38:39]
	s_add_i32 s64, s4, 0
	s_sub_i32 s64, 31, s64
	s_mul_i32 s71, s64, 0x30000
	s_add_u32 s38, s60, s71
	s_addc_u32 s39, s61, 0
	s_lshl_b32 s64, s64, 12
	global_load_dwordx4 v[8:11], v255, s[38:39]
	s_add_i32 s52, s4, 3
	s_min_u32 s52, s52, 31
	s_sub_i32 s52, 31, s52
	s_lshl_b32 s52, s52, 13
	s_add_u32 s26, s50, s52
	s_addc_u32 s27, s51, 0
	global_load_dwordx4 v[146:149], v154, s[26:27]
	global_load_dwordx4 v[150:153], v155, s[26:27]
	global_load_dwordx4 v[160:163], v159, s[26:27]
	v_exp_f32_e32 v198, v100
	v_exp_f32_e32 v199, v101
	v_exp_f32_e32 v200, v102
	v_exp_f32_e32 v201, v103
	v_exp_f32_e32 v202, v112
	v_exp_f32_e32 v203, v113
	v_exp_f32_e32 v204, v114
	v_exp_f32_e32 v205, v115
	v_exp_f32_e32 v214, v104
	v_add_f32_e32 v198, 1.0, v198
	v_exp_f32_e32 v215, v105
	v_add_f32_e32 v199, 1.0, v199
	v_exp_f32_e32 v216, v106
	v_add_f32_e32 v200, 1.0, v200
	v_exp_f32_e32 v217, v107
	v_add_f32_e32 v201, 1.0, v201
	v_exp_f32_e32 v218, v138
	v_add_f32_e32 v202, 1.0, v202
	v_exp_f32_e32 v219, v139
	v_add_f32_e32 v203, 1.0, v203
	v_exp_f32_e32 v220, v140
	v_add_f32_e32 v204, 1.0, v204
	v_exp_f32_e32 v221, v141
	v_add_f32_e32 v205, 1.0, v205
	v_rcp_f32_e32 v198, v198
	v_add_f32_e32 v214, 1.0, v214
	v_rcp_f32_e32 v199, v199
	v_add_f32_e32 v215, 1.0, v215
	v_rcp_f32_e32 v200, v200
	v_add_f32_e32 v216, 1.0, v216
	v_rcp_f32_e32 v201, v201
	v_add_f32_e32 v217, 1.0, v217
	v_rcp_f32_e32 v202, v202
	v_add_f32_e32 v218, 1.0, v218
	v_rcp_f32_e32 v203, v203
	v_add_f32_e32 v219, 1.0, v219
	v_rcp_f32_e32 v204, v204
	v_add_f32_e32 v220, 1.0, v220
	v_rcp_f32_e32 v205, v205
	v_add_f32_e32 v221, 1.0, v221
	v_mul_f32_e32 v198, v179, v198
	v_mul_f32_e32 v199, v179, v199
	v_mul_f32_e32 v200, v179, v200
	v_mul_f32_e32 v201, v179, v201
	v_mul_f32_e32 v202, v179, v202
	v_mul_f32_e32 v203, v179, v203
	v_mul_f32_e32 v204, v179, v204
	v_mul_f32_e32 v205, v179, v205
	v_exp_f32_e32 v120, v198
	v_exp_f32_e32 v121, v199
	v_exp_f32_e32 v122, v200
	v_exp_f32_e32 v123, v201
	v_exp_f32_e32 v124, v202
	v_exp_f32_e32 v125, v203
	v_exp_f32_e32 v126, v204
	v_exp_f32_e32 v127, v205
	v_fma_f32 v206, -v120, v120, 1.0
	v_fma_f32 v207, -v121, v121, 1.0
	v_fma_f32 v208, -v122, v122, 1.0
	v_fma_f32 v209, -v123, v123, 1.0
	v_fma_f32 v210, -v124, v124, 1.0
	v_fma_f32 v211, -v125, v125, 1.0
	v_fma_f32 v212, -v126, v126, 1.0
	v_fma_f32 v213, -v127, v127, 1.0
	v_max_f32_e32 v206, 0xda24260, v206
	v_max_f32_e32 v207, 0xda24260, v207
	v_max_f32_e32 v208, 0xda24260, v208
	v_max_f32_e32 v209, 0xda24260, v209
	v_max_f32_e32 v210, 0xda24260, v210
	v_max_f32_e32 v211, 0xda24260, v211
	v_max_f32_e32 v212, 0xda24260, v212
	v_max_f32_e32 v213, 0xda24260, v213
	v_mul_f32_e32 v198, v214, v206
	v_mul_f32_e32 v199, v215, v207
	v_mul_f32_e32 v200, v216, v208
	v_mul_f32_e32 v201, v217, v209
	v_mul_f32_e32 v202, v218, v210
	v_mul_f32_e32 v203, v219, v211
	v_mul_f32_e32 v204, v220, v212
	v_mul_f32_e32 v205, v221, v213
	v_mul_f32_e32 v214, v214, v198
	v_mul_f32_e32 v215, v215, v199
	v_mul_f32_e32 v216, v216, v200
	v_mul_f32_e32 v217, v217, v201
	v_mul_f32_e32 v218, v218, v202
	v_mul_f32_e32 v219, v219, v203
	v_mul_f32_e32 v220, v220, v204
	v_mul_f32_e32 v221, v221, v205
	v_rsq_f32_e32 v214, v214
	v_mul_f32_e32 v222, v108, v206
	v_rsq_f32_e32 v215, v215
	v_mul_f32_e32 v223, v109, v207
	v_rsq_f32_e32 v216, v216
	v_mul_f32_e32 v224, v110, v208
	v_rsq_f32_e32 v217, v217
	v_mul_f32_e32 v225, v111, v209
	v_rsq_f32_e32 v218, v218
	v_mul_f32_e32 v226, v142, v210
	v_rsq_f32_e32 v219, v219
	v_mul_f32_e32 v227, v143, v211
	v_rsq_f32_e32 v220, v220
	v_mul_f32_e32 v228, v144, v212
	v_rsq_f32_e32 v221, v221
	v_mul_f32_e32 v229, v145, v213
	v_mul_f32_e32 v170, v222, v214
	v_mul_f32_e32 v171, v223, v215
	v_mul_f32_e32 v172, v224, v216
	v_mul_f32_e32 v173, v225, v217
	v_mul_f32_e32 v174, v226, v218
	v_mul_f32_e32 v175, v227, v219
	v_mul_f32_e32 v176, v228, v220
	v_mul_f32_e32 v177, v229, v221
	v_mov_b32_e32 v198, v177
	v_mov_b32_e32 v199, v127
	v_fma_f32 v198, v126, v198, v176
	v_mul_f32_e32 v199, v199, v126
	v_fma_f32 v198, v125, v198, v175
	v_mul_f32_e32 v199, v199, v125
	v_fma_f32 v198, v124, v198, v174
	v_mul_f32_e32 v199, v199, v124
	v_fma_f32 v198, v123, v198, v173
	v_mul_f32_e32 v199, v199, v123
	v_fma_f32 v198, v122, v198, v172
	v_mul_f32_e32 v199, v199, v122
	v_fma_f32 v198, v121, v198, v171
	v_mul_f32_e32 v199, v199, v121
	v_fma_f32 v198, v120, v198, v170
	v_mul_f32_e32 v199, v199, v120
	v_mov_b32_e32 v164, v199
	v_mov_b32_e32 v166, v199
	v_mov_b32_e32 v246, v198
	v_mov_b32_e32 v248, v198
	s_nop 1
	v_permlane32_swap_b32 v164, v166
	v_permlane32_swap_b32 v246, v248
	s_nop 1
	v_mov_b32_e32 v165, v164
	v_mov_b32_e32 v167, v166
	v_mov_b32_e32 v247, v246
	v_mov_b32_e32 v249, v248
	s_nop 1
	v_permlane16_swap_b32 v164, v165
	v_permlane16_swap_b32 v166, v167
	v_permlane16_swap_b32 v246, v247
	v_permlane16_swap_b32 v248, v249
	s_nop 1
	v_mov_b32_e32 v251, v249
	v_mov_b32_e32 v250, v167
	v_fma_f32 v251, v251, v166, v248
	v_mul_f32_e32 v250, v250, v166
	v_fma_f32 v251, v251, v165, v247
	v_mul_f32_e32 v250, v250, v165
	v_fma_f32 v251, v251, v164, v246
	v_mul_f32_e32 v250, v250, v164
	s_mov_b64 exec, s[10:11]
	ds_write_b64 v182, v[250:251] offset:0
	s_mov_b64 exec, -1
	s_waitcnt lgkmcnt(0)
	s_barrier
	ds_read2_b64 v[4:7], v183 offset0:0 offset1:16
	s_add_i32 s52, s4, 0
	s_sub_i32 s52, 31, s52
	s_lshl_b32 s52, s52, 12
	v_add_u32_e32 v197, s52, v184
	s_waitcnt lgkmcnt(0)
	v_fma_f32 v198, v180, v6, v7
	v_cndmask_b32_e64 v199, v180, v198, s[24:25]
	v_fma_f32 v180, v198, v4, v5
	v_fma_f32 v200, v199, v167, v249
	v_cndmask_b32_e64 v199, v199, v200, s[16:17]
	v_fma_f32 v200, v199, v166, v248
	v_cndmask_b32_e64 v199, v199, v200, s[20:21]
	v_fma_f32 v200, v199, v165, v247
	v_cndmask_b32_e64 v199, v199, v200, s[22:23]
	v_fma_f32 v221, v127, v199, v177
	v_fma_f32 v220, v126, v221, v176
	v_fma_f32 v219, v125, v220, v175
	v_fma_f32 v218, v124, v219, v174
	v_fma_f32 v217, v123, v218, v173
	v_fma_f32 v216, v122, v217, v172
	v_fma_f32 v215, v121, v216, v171
	v_fma_f32 v214, v120, v215, v170
	ds_read_u16 v206, v197 offset:0
	ds_read_u16 v207, v197 offset:64
	ds_read_u16 v208, v197 offset:128
	ds_read_u16 v209, v197 offset:192
	ds_read_u16 v210, v197 offset:256
	ds_read_u16 v211, v197 offset:320
	ds_read_u16 v212, v197 offset:384
	ds_read_u16 v213, v197 offset:448
	s_waitcnt lgkmcnt(0)
	v_lshlrev_b32_e32 v206, 16, v206
	v_lshlrev_b32_e32 v207, 16, v207
	v_lshlrev_b32_e32 v208, 16, v208
	v_lshlrev_b32_e32 v209, 16, v209
	v_lshlrev_b32_e32 v210, 16, v210
	v_lshlrev_b32_e32 v211, 16, v211
	v_lshlrev_b32_e32 v212, 16, v212
	v_lshlrev_b32_e32 v213, 16, v213
	v_add_f32_e32 v214, v214, v206
	v_add_f32_e32 v215, v215, v207
	v_add_f32_e32 v216, v216, v208
	v_add_f32_e32 v217, v217, v209
	v_add_f32_e32 v218, v218, v210
	v_add_f32_e32 v219, v219, v211
	v_add_f32_e32 v220, v220, v212
	v_add_f32_e32 v221, v221, v213
	v_cvt_pk_bf16_f32 v206, v214, v215
	v_cvt_pk_bf16_f32 v208, v216, v217
	v_cvt_pk_bf16_f32 v210, v218, v219
	v_cvt_pk_bf16_f32 v212, v220, v221
	ds_write_b16 v197, v206 offset:0
	ds_write_b16_d16_hi v197, v206 offset:64
	ds_write_b16 v197, v208 offset:128
	ds_write_b16_d16_hi v197, v208 offset:192
	ds_write_b16 v197, v210 offset:256
	ds_write_b16_d16_hi v197, v210 offset:320
	ds_write_b16 v197, v212 offset:384
	ds_write_b16_d16_hi v197, v212 offset:448
	ds_read_b128 v[198:201], v130 offset:0
	ds_read_b128 v[214:217], v130 offset:576
	ds_read_b128 v[202:205], v131 offset:0
	ds_read_b128 v[218:221], v131 offset:576
	ds_read_b128 v[206:209], v130 offset:144
	ds_read_b128 v[222:225], v130 offset:720
	ds_read_b128 v[210:213], v131 offset:144
	s_waitcnt lgkmcnt(14)
	ds_read_b128 v[226:229], v131 offset:720
	s_waitcnt lgkmcnt(6)
	v_mfma_f32_16x16x32_bf16 v[100:103], v[198:201], v[20:23], v[12:15]
	v_mfma_f32_16x16x32_bf16 v[104:107], v[198:201], v[52:55], v[16:19]
	v_mfma_f32_16x16x32_bf16 v[108:111], v[198:201], v[84:87], v[242:245]
	v_mfma_f32_16x16x32_bf16 v[112:115], v[214:217], v[20:23], v[12:15]
	v_mfma_f32_16x16x32_bf16 v[138:141], v[214:217], v[52:55], v[16:19]
	v_mfma_f32_16x16x32_bf16 v[142:145], v[214:217], v[84:87], v[242:245]
	s_waitcnt lgkmcnt(4)
	v_mfma_f32_16x16x32_bf16 v[100:103], v[202:205], v[24:27], v[100:103]
	v_mfma_f32_16x16x32_bf16 v[104:107], v[202:205], v[56:59], v[104:107]
	v_mfma_f32_16x16x32_bf16 v[112:115], v[218:221], v[24:27], v[112:115]
	v_mfma_f32_16x16x32_bf16 v[138:141], v[218:221], v[56:59], v[138:141]
	ds_read_b128 v[198:201], v130 offset:288
	ds_read_b128 v[214:217], v130 offset:864
	ds_read_b128 v[202:205], v131 offset:288
	ds_read_b128 v[218:221], v131 offset:864
	s_waitcnt lgkmcnt(6)
	v_mfma_f32_16x16x32_bf16 v[100:103], v[206:209], v[28:31], v[100:103]
	v_mfma_f32_16x16x32_bf16 v[104:107], v[206:209], v[60:63], v[104:107]
	v_mfma_f32_16x16x32_bf16 v[108:111], v[206:209], v[88:91], v[108:111]
	v_mfma_f32_16x16x32_bf16 v[112:115], v[222:225], v[28:31], v[112:115]
	v_mfma_f32_16x16x32_bf16 v[138:141], v[222:225], v[60:63], v[138:141]
	v_mfma_f32_16x16x32_bf16 v[142:145], v[222:225], v[88:91], v[142:145]
	s_waitcnt lgkmcnt(4)
	v_mfma_f32_16x16x32_bf16 v[100:103], v[210:213], v[32:35], v[100:103]
	v_mfma_f32_16x16x32_bf16 v[104:107], v[210:213], v[64:67], v[104:107]
	v_mfma_f32_16x16x32_bf16 v[112:115], v[226:229], v[32:35], v[112:115]
	v_mfma_f32_16x16x32_bf16 v[138:141], v[226:229], v[64:67], v[138:141]
	ds_read_b128 v[206:209], v130 offset:432
	ds_read_b128 v[222:225], v130 offset:1008
	ds_read_b128 v[210:213], v131 offset:432
	ds_read_b128 v[226:229], v131 offset:1008
	s_waitcnt lgkmcnt(6)
	v_mfma_f32_16x16x32_bf16 v[100:103], v[198:201], v[36:39], v[100:103]
	v_mfma_f32_16x16x32_bf16 v[104:107], v[198:201], v[68:71], v[104:107]
	v_mfma_f32_16x16x32_bf16 v[108:111], v[198:201], v[92:95], v[108:111]
	v_mfma_f32_16x16x32_bf16 v[112:115], v[214:217], v[36:39], v[112:115]
	v_mfma_f32_16x16x32_bf16 v[138:141], v[214:217], v[68:71], v[138:141]
	v_mfma_f32_16x16x32_bf16 v[142:145], v[214:217], v[92:95], v[142:145]
	s_waitcnt lgkmcnt(4)
	v_mfma_f32_16x16x32_bf16 v[100:103], v[202:205], v[40:43], v[100:103]
	v_mfma_f32_16x16x32_bf16 v[104:107], v[202:205], v[72:75], v[104:107]
	v_mfma_f32_16x16x32_bf16 v[112:115], v[218:221], v[40:43], v[112:115]
	v_mfma_f32_16x16x32_bf16 v[138:141], v[218:221], v[72:75], v[138:141]
	s_waitcnt lgkmcnt(2)
	v_mfma_f32_16x16x32_bf16 v[100:103], v[206:209], v[44:47], v[100:103]
	v_mfma_f32_16x16x32_bf16 v[104:107], v[206:209], v[76:79], v[104:107]
	v_mfma_f32_16x16x32_bf16 v[108:111], v[206:209], v[96:99], v[108:111]
	v_mfma_f32_16x16x32_bf16 v[112:115], v[222:225], v[44:47], v[112:115]
	v_mfma_f32_16x16x32_bf16 v[138:141], v[222:225], v[76:79], v[138:141]
	v_mfma_f32_16x16x32_bf16 v[142:145], v[222:225], v[96:99], v[142:145]
	s_waitcnt lgkmcnt(0)
	v_mfma_f32_16x16x32_bf16 v[100:103], v[210:213], v[48:51], v[100:103]
	v_mfma_f32_16x16x32_bf16 v[104:107], v[210:213], v[80:83], v[104:107]
	v_mfma_f32_16x16x32_bf16 v[112:115], v[226:229], v[48:51], v[112:115]
	v_mfma_f32_16x16x32_bf16 v[138:141], v[226:229], v[80:83], v[138:141]
	s_waitcnt lgkmcnt(0)
	s_barrier
	s_waitcnt vmcnt(5)
	ds_write_b128 v134, v[230:233]
	ds_write_b128 v134, v[234:237] offset:4608
	ds_write_b128 v135, v[238:241]
	s_add_i32 s64, s4, 0
	s_sub_i32 s64, 31, s64
	s_mul_i32 s71, s64, 0x30000
	s_add_u32 s38, s60, s71
	s_addc_u32 s39, s61, 0
	s_lshl_b32 s64, s64, 12
	v_add_u32_e32 v136, s64, v195
	ds_read_b128 v[116:119], v136
	s_waitcnt vmcnt(3)
	s_waitcnt lgkmcnt(0)
	v_lshlrev_b32_e32 v136, 16, v116
	v_lshlrev_b32_e32 v137, 16, v8
	v_and_b32_e32 v168, 0xffff0000, v116
	v_and_b32_e32 v169, 0xffff0000, v8
	v_mul_f32_e32 v136, v136, v137
	v_mul_f32_e32 v168, v168, v169
	v_cvt_pk_bf16_f32 v116, v136, v168
	v_lshlrev_b32_e32 v136, 16, v117
	v_lshlrev_b32_e32 v137, 16, v9
	v_and_b32_e32 v168, 0xffff0000, v117
	v_and_b32_e32 v169, 0xffff0000, v9
	v_mul_f32_e32 v136, v136, v137
	v_mul_f32_e32 v168, v168, v169
	v_cvt_pk_bf16_f32 v117, v136, v168
	v_lshlrev_b32_e32 v136, 16, v118
	v_lshlrev_b32_e32 v137, 16, v10
	v_and_b32_e32 v168, 0xffff0000, v118
	v_and_b32_e32 v169, 0xffff0000, v10
	v_mul_f32_e32 v136, v136, v137
	v_mul_f32_e32 v168, v168, v169
	v_cvt_pk_bf16_f32 v118, v136, v168
	v_lshlrev_b32_e32 v136, 16, v119
	v_lshlrev_b32_e32 v137, 16, v11
	v_and_b32_e32 v168, 0xffff0000, v119
	v_and_b32_e32 v169, 0xffff0000, v11
	v_mul_f32_e32 v136, v136, v137
	v_mul_f32_e32 v168, v168, v169
	v_cvt_pk_bf16_f32 v119, v136, v168
	global_store_dwordx4 v255, v[116:119], s[38:39]
	s_add_i32 s64, s4, 1
	s_sub_i32 s64, 31, s64
	s_mul_i32 s71, s64, 0x30000
	s_add_u32 s38, s60, s71
	s_addc_u32 s39, s61, 0
	s_lshl_b32 s64, s64, 12
	global_load_dwordx4 v[8:11], v255, s[38:39]
	s_add_i32 s52, s4, 4
	s_min_u32 s52, s52, 31
	s_sub_i32 s52, 31, s52
	s_lshl_b32 s52, s52, 13
	s_add_u32 s26, s50, s52
	s_addc_u32 s27, s51, 0
	global_load_dwordx4 v[230:233], v154, s[26:27]
	global_load_dwordx4 v[234:237], v155, s[26:27]
	global_load_dwordx4 v[238:241], v159, s[26:27]
	v_exp_f32_e32 v198, v100
	v_exp_f32_e32 v199, v101
	v_exp_f32_e32 v200, v102
	v_exp_f32_e32 v201, v103
	v_exp_f32_e32 v202, v112
	v_exp_f32_e32 v203, v113
	v_exp_f32_e32 v204, v114
	v_exp_f32_e32 v205, v115
	v_exp_f32_e32 v214, v104
	v_add_f32_e32 v198, 1.0, v198
	v_exp_f32_e32 v215, v105
	v_add_f32_e32 v199, 1.0, v199
	v_exp_f32_e32 v216, v106
	v_add_f32_e32 v200, 1.0, v200
	v_exp_f32_e32 v217, v107
	v_add_f32_e32 v201, 1.0, v201
	v_exp_f32_e32 v218, v138
	v_add_f32_e32 v202, 1.0, v202
	v_exp_f32_e32 v219, v139
	v_add_f32_e32 v203, 1.0, v203
	v_exp_f32_e32 v220, v140
	v_add_f32_e32 v204, 1.0, v204
	v_exp_f32_e32 v221, v141
	v_add_f32_e32 v205, 1.0, v205
	v_rcp_f32_e32 v198, v198
	v_add_f32_e32 v214, 1.0, v214
	v_rcp_f32_e32 v199, v199
	v_add_f32_e32 v215, 1.0, v215
	v_rcp_f32_e32 v200, v200
	v_add_f32_e32 v216, 1.0, v216
	v_rcp_f32_e32 v201, v201
	v_add_f32_e32 v217, 1.0, v217
	v_rcp_f32_e32 v202, v202
	v_add_f32_e32 v218, 1.0, v218
	v_rcp_f32_e32 v203, v203
	v_add_f32_e32 v219, 1.0, v219
	v_rcp_f32_e32 v204, v204
	v_add_f32_e32 v220, 1.0, v220
	v_rcp_f32_e32 v205, v205
	v_add_f32_e32 v221, 1.0, v221
	v_mul_f32_e32 v198, v179, v198
	v_mul_f32_e32 v199, v179, v199
	v_mul_f32_e32 v200, v179, v200
	v_mul_f32_e32 v201, v179, v201
	v_mul_f32_e32 v202, v179, v202
	v_mul_f32_e32 v203, v179, v203
	v_mul_f32_e32 v204, v179, v204
	v_mul_f32_e32 v205, v179, v205
	v_exp_f32_e32 v120, v198
	v_exp_f32_e32 v121, v199
	v_exp_f32_e32 v122, v200
	v_exp_f32_e32 v123, v201
	v_exp_f32_e32 v124, v202
	v_exp_f32_e32 v125, v203
	v_exp_f32_e32 v126, v204
	v_exp_f32_e32 v127, v205
	v_fma_f32 v206, -v120, v120, 1.0
	v_fma_f32 v207, -v121, v121, 1.0
	v_fma_f32 v208, -v122, v122, 1.0
	v_fma_f32 v209, -v123, v123, 1.0
	v_fma_f32 v210, -v124, v124, 1.0
	v_fma_f32 v211, -v125, v125, 1.0
	v_fma_f32 v212, -v126, v126, 1.0
	v_fma_f32 v213, -v127, v127, 1.0
	v_max_f32_e32 v206, 0xda24260, v206
	v_max_f32_e32 v207, 0xda24260, v207
	v_max_f32_e32 v208, 0xda24260, v208
	v_max_f32_e32 v209, 0xda24260, v209
	v_max_f32_e32 v210, 0xda24260, v210
	v_max_f32_e32 v211, 0xda24260, v211
	v_max_f32_e32 v212, 0xda24260, v212
	v_max_f32_e32 v213, 0xda24260, v213
	v_mul_f32_e32 v198, v214, v206
	v_mul_f32_e32 v199, v215, v207
	v_mul_f32_e32 v200, v216, v208
	v_mul_f32_e32 v201, v217, v209
	v_mul_f32_e32 v202, v218, v210
	v_mul_f32_e32 v203, v219, v211
	v_mul_f32_e32 v204, v220, v212
	v_mul_f32_e32 v205, v221, v213
	v_mul_f32_e32 v214, v214, v198
	v_mul_f32_e32 v215, v215, v199
	v_mul_f32_e32 v216, v216, v200
	v_mul_f32_e32 v217, v217, v201
	v_mul_f32_e32 v218, v218, v202
	v_mul_f32_e32 v219, v219, v203
	v_mul_f32_e32 v220, v220, v204
	v_mul_f32_e32 v221, v221, v205
	v_rsq_f32_e32 v214, v214
	v_mul_f32_e32 v222, v108, v206
	v_rsq_f32_e32 v215, v215
	v_mul_f32_e32 v223, v109, v207
	v_rsq_f32_e32 v216, v216
	v_mul_f32_e32 v224, v110, v208
	v_rsq_f32_e32 v217, v217
	v_mul_f32_e32 v225, v111, v209
	v_rsq_f32_e32 v218, v218
	v_mul_f32_e32 v226, v142, v210
	v_rsq_f32_e32 v219, v219
	v_mul_f32_e32 v227, v143, v211
	v_rsq_f32_e32 v220, v220
	v_mul_f32_e32 v228, v144, v212
	v_rsq_f32_e32 v221, v221
	v_mul_f32_e32 v229, v145, v213
	v_mul_f32_e32 v170, v222, v214
	v_mul_f32_e32 v171, v223, v215
	v_mul_f32_e32 v172, v224, v216
	v_mul_f32_e32 v173, v225, v217
	v_mul_f32_e32 v174, v226, v218
	v_mul_f32_e32 v175, v227, v219
	v_mul_f32_e32 v176, v228, v220
	v_mul_f32_e32 v177, v229, v221
	v_mov_b32_e32 v198, v177
	v_mov_b32_e32 v199, v127
	v_fma_f32 v198, v126, v198, v176
	v_mul_f32_e32 v199, v199, v126
	v_fma_f32 v198, v125, v198, v175
	v_mul_f32_e32 v199, v199, v125
	v_fma_f32 v198, v124, v198, v174
	v_mul_f32_e32 v199, v199, v124
	v_fma_f32 v198, v123, v198, v173
	v_mul_f32_e32 v199, v199, v123
	v_fma_f32 v198, v122, v198, v172
	v_mul_f32_e32 v199, v199, v122
	v_fma_f32 v198, v121, v198, v171
	v_mul_f32_e32 v199, v199, v121
	v_fma_f32 v198, v120, v198, v170
	v_mul_f32_e32 v199, v199, v120
	v_mov_b32_e32 v164, v199
	v_mov_b32_e32 v166, v199
	v_mov_b32_e32 v246, v198
	v_mov_b32_e32 v248, v198
	s_nop 1
	v_permlane32_swap_b32 v164, v166
	v_permlane32_swap_b32 v246, v248
	s_nop 1
	v_mov_b32_e32 v165, v164
	v_mov_b32_e32 v167, v166
	v_mov_b32_e32 v247, v246
	v_mov_b32_e32 v249, v248
	s_nop 1
	v_permlane16_swap_b32 v164, v165
	v_permlane16_swap_b32 v166, v167
	v_permlane16_swap_b32 v246, v247
	v_permlane16_swap_b32 v248, v249
	s_nop 1
	v_mov_b32_e32 v251, v249
	v_mov_b32_e32 v250, v167
	v_fma_f32 v251, v251, v166, v248
	v_mul_f32_e32 v250, v250, v166
	v_fma_f32 v251, v251, v165, v247
	v_mul_f32_e32 v250, v250, v165
	v_fma_f32 v251, v251, v164, v246
	v_mul_f32_e32 v250, v250, v164
	s_mov_b64 exec, s[10:11]
	ds_write_b64 v182, v[250:251] offset:1024
	s_mov_b64 exec, -1
	s_waitcnt lgkmcnt(0)
	s_barrier
	ds_read2_b64 v[4:7], v183 offset0:128 offset1:144
	s_add_i32 s52, s4, 1
	s_sub_i32 s52, 31, s52
	s_lshl_b32 s52, s52, 12
	v_add_u32_e32 v197, s52, v184
	s_waitcnt lgkmcnt(0)
	v_fma_f32 v198, v180, v6, v7
	v_cndmask_b32_e64 v199, v180, v198, s[24:25]
	v_fma_f32 v180, v198, v4, v5
	v_fma_f32 v200, v199, v167, v249
	v_cndmask_b32_e64 v199, v199, v200, s[16:17]
	v_fma_f32 v200, v199, v166, v248
	v_cndmask_b32_e64 v199, v199, v200, s[20:21]
	v_fma_f32 v200, v199, v165, v247
	v_cndmask_b32_e64 v199, v199, v200, s[22:23]
	v_fma_f32 v221, v127, v199, v177
	v_fma_f32 v220, v126, v221, v176
	v_fma_f32 v219, v125, v220, v175
	v_fma_f32 v218, v124, v219, v174
	v_fma_f32 v217, v123, v218, v173
	v_fma_f32 v216, v122, v217, v172
	v_fma_f32 v215, v121, v216, v171
	v_fma_f32 v214, v120, v215, v170
	ds_read_u16 v206, v197 offset:0
	ds_read_u16 v207, v197 offset:64
	ds_read_u16 v208, v197 offset:128
	ds_read_u16 v209, v197 offset:192
	ds_read_u16 v210, v197 offset:256
	ds_read_u16 v211, v197 offset:320
	ds_read_u16 v212, v197 offset:384
	ds_read_u16 v213, v197 offset:448
	s_waitcnt lgkmcnt(0)
	v_lshlrev_b32_e32 v206, 16, v206
	v_lshlrev_b32_e32 v207, 16, v207
	v_lshlrev_b32_e32 v208, 16, v208
	v_lshlrev_b32_e32 v209, 16, v209
	v_lshlrev_b32_e32 v210, 16, v210
	v_lshlrev_b32_e32 v211, 16, v211
	v_lshlrev_b32_e32 v212, 16, v212
	v_lshlrev_b32_e32 v213, 16, v213
	v_add_f32_e32 v214, v214, v206
	v_add_f32_e32 v215, v215, v207
	v_add_f32_e32 v216, v216, v208
	v_add_f32_e32 v217, v217, v209
	v_add_f32_e32 v218, v218, v210
	v_add_f32_e32 v219, v219, v211
	v_add_f32_e32 v220, v220, v212
	v_add_f32_e32 v221, v221, v213
	v_cvt_pk_bf16_f32 v206, v214, v215
	v_cvt_pk_bf16_f32 v208, v216, v217
	v_cvt_pk_bf16_f32 v210, v218, v219
	v_cvt_pk_bf16_f32 v212, v220, v221
	ds_write_b16 v197, v206 offset:0
	ds_write_b16_d16_hi v197, v206 offset:64
	ds_write_b16 v197, v208 offset:128
	ds_write_b16_d16_hi v197, v208 offset:192
	ds_write_b16 v197, v210 offset:256
	ds_write_b16_d16_hi v197, v210 offset:320
	ds_write_b16 v197, v212 offset:384
	ds_write_b16_d16_hi v197, v212 offset:448
	s_add_i32 s4, s4, 2
	s_cmp_lt_u32 s4, 32
	s_cbranch_scc1 .Lrec2_loopB_d1
	s_waitcnt lgkmcnt(0)
	s_barrier
	s_add_i32 s64, s4, -1
	s_sub_i32 s64, 31, s64
	s_mul_i32 s71, s64, 0x30000
	s_add_u32 s38, s60, s71
	s_addc_u32 s39, s61, 0
	s_lshl_b32 s64, s64, 12
	v_add_u32_e32 v136, s64, v195
	ds_read_b128 v[116:119], v136
	s_waitcnt vmcnt(3)
	s_waitcnt lgkmcnt(0)
	v_lshlrev_b32_e32 v136, 16, v116
	v_lshlrev_b32_e32 v137, 16, v8
	v_and_b32_e32 v168, 0xffff0000, v116
	v_and_b32_e32 v169, 0xffff0000, v8
	v_mul_f32_e32 v136, v136, v137
	v_mul_f32_e32 v168, v168, v169
	v_cvt_pk_bf16_f32 v116, v136, v168
	v_lshlrev_b32_e32 v136, 16, v117
	v_lshlrev_b32_e32 v137, 16, v9
	v_and_b32_e32 v168, 0xffff0000, v117
	v_and_b32_e32 v169, 0xffff0000, v9
	v_mul_f32_e32 v136, v136, v137
	v_mul_f32_e32 v168, v168, v169
	v_cvt_pk_bf16_f32 v117, v136, v168
	v_lshlrev_b32_e32 v136, 16, v118
	v_lshlrev_b32_e32 v137, 16, v10
	v_and_b32_e32 v168, 0xffff0000, v118
	v_and_b32_e32 v169, 0xffff0000, v10
	v_mul_f32_e32 v136, v136, v137
	v_mul_f32_e32 v168, v168, v169
	v_cvt_pk_bf16_f32 v118, v136, v168
	v_lshlrev_b32_e32 v136, 16, v119
	v_lshlrev_b32_e32 v137, 16, v11
	v_and_b32_e32 v168, 0xffff0000, v119
	v_and_b32_e32 v169, 0xffff0000, v11
	v_mul_f32_e32 v136, v136, v137
	v_mul_f32_e32 v168, v168, v169
	v_cvt_pk_bf16_f32 v119, v136, v168
	global_store_dwordx4 v255, v[116:119], s[38:39]
